# SB: non-diagonal lean clone of each stream body (diag masking selects folded, v_max canonicalisation dropped) + dead phi copies around score MFMAs removed; MLA epilogue stores widened via permlane32_s
# speedup vs baseline: 1.0260x; 1.0058x over previous
; DI void mla_block(const Params& p, LAS unsigned char* lds, int b, int hd, int qb, int tid) {
;     ...
;     for (int kt = 0; kt < ntiles; ++kt) {
;         asm volatile("s_waitcnt vmcnt(0)" ::: "memory");
;         __builtin_amdgcn_s_barrier();
;         asm volatile("" ::: "memory");
;         const int bprev = bcur == 0 ? 2 : bcur - 1, bnext = bcur == 2 ? 0 : bcur + 1;
;         if (kt + 1 < ntiles) MLA_STAGE(kt + 1, bnext);
;         if (late && kt >= 1 && kt - 1 <= wlast) mla_pv(lds + bprev * MLA_BUF, r, h, pf0, pf1, o);
.LBB0_622:
	s_add_i32 s76, s73, 1
	s_waitcnt vmcnt(0)
	s_barrier
	s_cmp_lg_u32 s73, 2
	s_cselect_b32 s76, s76, 0
	s_add_i32 s88, s77, 1
	s_cmp_ge_u32 s88, s74
	s_cbranch_scc1 .LBB0_635
	s_andn2_b64 vcc, exec, s[2:3]
	s_cbranch_vccnz .Lmla_toplate_0
	s_cmp_gt_i32 s77, s33
	s_cbranch_scc0 .LBB0_635
	s_branch .Lmla_stnow_0
.Lmla_toplate_0:
	s_cmp_eq_u32 s77, 0
	s_cbranch_scc1 .Lmla_stnow_0
	s_cmp_le_i32 s77, s84
	s_cbranch_scc1 .LBB0_635

; #define LAS __attribute__((address_space(3)))
; #define MFMA32(a, b, c) __builtin_amdgcn_mfma_f32_32x32x16_bf16((a), (b), (c), 0, 0, 0)
; DI void mla_pv(const LAS unsigned char* base, int r, int h, const bf16x8 (&pf0)[2], const bf16x8 (&pf1)[2], f32x16 (&o)[4]) {
;     const LAS unsigned char* vp = base + MLA_KBYTES + r * MLA_VROW + h * 32;
; #pragma unroll
;     for (int s = 0; s < 2; ++s) {
;         bf16x8 va[4], vb[4];
; #pragma unroll
;         for (int dt = 0; dt < 4; ++dt) { va[dt] = *(const LAS bf16x8*)(vp + dt * 32 * MLA_VROW + s * 16); vb[dt] = *(const LAS bf16x8*)(vp + dt * 32 * MLA_VROW + 64 + s * 16); }
;         __builtin_amdgcn_sched_barrier(0);
; #pragma unroll
;         for (int dt = 0; dt < 4; ++dt) o[dt] = MFMA32(va[dt], pf0[s], o[dt]);
; #pragma unroll
;         for (int dt = 0; dt < 4; ++dt) o[dt] = MFMA32(vb[dt], pf1[s], o[dt]);
;         __builtin_amdgcn_sched_barrier(0);
;     }
; }
; DI void mla_block(const Params& p, LAS unsigned char* lds, int b, int hd, int qb, int tid) {
;     ...
;         if (kt + 1 < ntiles) MLA_STAGE(kt + 1, bnext);
.LBB0_635:
	s_cmp_lg_u32 s77, 0
	s_cselect_b64 s[90:91], -1, 0
	s_and_b64 s[90:91], s[78:79], s[90:91]
	s_cmp_le_i32 s77, s84
	s_cselect_b64 vcc, -1, 0
	s_and_b64 s[90:91], s[90:91], vcc
	s_andn2_b64 vcc, exec, s[90:91]
	s_mul_i32 s89, s73, 0xac00
	s_cbranch_vccnz .LBB0_638
	s_add_i32 s90, s89, 0xffff5400
	s_cmp_lg_u32 s73, 0
	s_cselect_b32 s73, s90, 0x15800
	v_add_u32_e32 v0, s73, v182
	ds_read_b128 v[84:87], v0 offset:25600
	ds_read_b128 v[88:91], v0 offset:25664
	ds_read_b128 v[92:95], v0 offset:30208
	ds_read_b128 v[96:99], v0 offset:30272
	ds_read_b128 v[100:103], v0 offset:34816
	ds_read_b128 v[104:107], v0 offset:34880
	ds_read_b128 v[108:111], v0 offset:39424
	ds_read_b128 v[186:189], v0 offset:39488
	ds_read_b128 v[200:203], v0 offset:25616
	ds_read_b128 v[204:207], v0 offset:25680
	ds_read_b128 v[208:211], v0 offset:30224
	ds_read_b128 v[212:215], v0 offset:30288
	ds_read_b128 v[216:219], v0 offset:34832
	ds_read_b128 v[220:223], v0 offset:34896
	ds_read_b128 v[224:227], v0 offset:39440
	ds_read_b128 v[228:231], v0 offset:39504
	s_cmp_ge_u32 s88, s74
	s_cbranch_scc1 .Lmla_pvplain_0
	s_mul_i32 s91, s76, 0xac00
	s_waitcnt lgkmcnt(8)
	v_mfma_f32_32x32x16_bf16 v[64:79], v[84:87], v[80:83], v[64:79]
	v_readlane_b32 s90, v255, 11
	v_lshl_add_u32 v253, s88, v176, v166
	s_add_i32 m0, s91, s90
	s_nop 0
	global_load_lds_dwordx4 v253, s[12:13]
	v_mfma_f32_32x32x16_bf16 v[48:63], v[92:95], v[80:83], v[48:63]
	v_mfma_f32_32x32x16_bf16 v[32:47], v[100:103], v[80:83], v[32:47]
	v_lshl_add_u32 v253, s88, v177, v167
	s_add_i32 m0, s91, s85
	s_nop 0
	global_load_lds_dwordx4 v253, s[12:13]
	v_mfma_f32_32x32x16_bf16 v[16:31], v[108:111], v[80:83], v[16:31]
	v_mfma_f32_32x32x16_bf16 v[64:79], v[88:91], v[6:9], v[64:79]
	v_lshl_add_u32 v253, s88, v178, v168
	s_add_i32 m0, s91, s72
	s_nop 0
	global_load_lds_dwordx4 v253, s[12:13]
	v_mfma_f32_32x32x16_bf16 v[48:63], v[96:99], v[6:9], v[48:63]
	v_mfma_f32_32x32x16_bf16 v[32:47], v[104:107], v[6:9], v[32:47]
	v_lshl_add_u32 v253, s88, v179, v169
	s_add_i32 m0, s91, s75
	s_nop 0
	global_load_lds_dwordx4 v253, s[12:13]
	v_mfma_f32_32x32x16_bf16 v[16:31], v[186:189], v[6:9], v[16:31]
	s_waitcnt lgkmcnt(0)
	v_mfma_f32_32x32x16_bf16 v[64:79], v[200:203], v[10:13], v[64:79]
	v_lshl_add_u32 v253, s88, v180, v170
	s_add_i32 m0, s91, s1
	s_nop 0
	global_load_lds_dwordx4 v253, s[12:13]
	v_mfma_f32_32x32x16_bf16 v[48:63], v[208:211], v[10:13], v[48:63]
	v_mfma_f32_32x32x16_bf16 v[32:47], v[216:219], v[10:13], v[32:47]
	s_andn2_b64 vcc, exec, s[94:95]
	s_cbranch_vccnz .Lmla_a5_pv_0
	v_readlane_b32 s90, v255, 9
	v_lshl_add_u32 v253, s88, v181, v171
	s_add_i32 m0, s91, s90
	s_nop 0
	global_load_lds_dwordx4 v253, s[12:13]
.Lmla_a5_pv_0:
	v_mfma_f32_32x32x16_bf16 v[16:31], v[224:227], v[10:13], v[16:31]
	v_mfma_f32_32x32x16_bf16 v[64:79], v[204:207], v[2:5], v[64:79]
	v_mfma_f32_32x32x16_bf16 v[48:63], v[212:215], v[2:5], v[48:63]
	v_mfma_f32_32x32x16_bf16 v[32:47], v[220:223], v[2:5], v[32:47]
	v_mfma_f32_32x32x16_bf16 v[16:31], v[228:231], v[2:5], v[16:31]
	s_branch .Lmla_pvdone_0
.Lmla_pvplain_0:
	s_waitcnt lgkmcnt(8)
	v_mfma_f32_32x32x16_bf16 v[64:79], v[84:87], v[80:83], v[64:79]
	v_mfma_f32_32x32x16_bf16 v[48:63], v[92:95], v[80:83], v[48:63]
	v_mfma_f32_32x32x16_bf16 v[32:47], v[100:103], v[80:83], v[32:47]
	v_mfma_f32_32x32x16_bf16 v[16:31], v[108:111], v[80:83], v[16:31]
	v_mfma_f32_32x32x16_bf16 v[64:79], v[88:91], v[6:9], v[64:79]
	v_mfma_f32_32x32x16_bf16 v[48:63], v[96:99], v[6:9], v[48:63]
	v_mfma_f32_32x32x16_bf16 v[32:47], v[104:107], v[6:9], v[32:47]
	v_mfma_f32_32x32x16_bf16 v[16:31], v[186:189], v[6:9], v[16:31]
	s_waitcnt lgkmcnt(0)
	v_mfma_f32_32x32x16_bf16 v[64:79], v[200:203], v[10:13], v[64:79]
	v_mfma_f32_32x32x16_bf16 v[48:63], v[208:211], v[10:13], v[48:63]
	v_mfma_f32_32x32x16_bf16 v[32:47], v[216:219], v[10:13], v[32:47]
	v_mfma_f32_32x32x16_bf16 v[16:31], v[224:227], v[10:13], v[16:31]
	v_mfma_f32_32x32x16_bf16 v[64:79], v[204:207], v[2:5], v[64:79]
	v_mfma_f32_32x32x16_bf16 v[48:63], v[212:215], v[2:5], v[48:63]
	v_mfma_f32_32x32x16_bf16 v[32:47], v[220:223], v[2:5], v[32:47]
	v_mfma_f32_32x32x16_bf16 v[16:31], v[228:231], v[2:5], v[16:31]
.Lmla_pvdone_0:
	s_cmp_gt_i32 s77, s33
	s_cbranch_scc0 .LBB0_639

; #define LAS __attribute__((address_space(3)))
; DI f32x16 zero16() { f32x16 z; for (int i = 0; i < 16; ++i) z[i] = 0.f; return z; }
; #define MFMA32(a, b, c) __builtin_amdgcn_mfma_f32_32x32x16_bf16((a), (b), (c), 0, 0, 0)
; DI void mla_s_softmax(const LAS unsigned char* base, int r, int h, bool is_diag, int lim, const bf16x8 (&qf)[12], f32x16 (&o)[4], float& m_run, float& l_run,
;                       bf16x8 (&pf0)[2], bf16x8 (&pf1)[2]) {
;     f32x16 s0 = zero16(), s1 = zero16();
;     const LAS unsigned char* kp = base + r * MLA_KROW + h * 16;
; #pragma unroll
;     for (int g = 0; g < 3; ++g) {
;         bf16x8 fa[4], fb[4];
; #pragma unroll
;         for (int j = 0; j < 4; ++j) { fa[j] = *(const LAS bf16x8*)(kp + (4 * g + j) * 32); fb[j] = *(const LAS bf16x8*)(kp + 32 * MLA_KROW + (4 * g + j) * 32); }
;         __builtin_amdgcn_sched_barrier(0);
; #pragma unroll
;         for (int j = 0; j < 4; ++j) { s0 = MFMA32(fa[j], qf[4 * g + j], s0); s1 = MFMA32(fb[j], qf[4 * g + j], s1); }
;         __builtin_amdgcn_sched_barrier(0);
;     }
; DI void mla_block(const Params& p, LAS unsigned char* lds, int b, int hd, int qb, int tid) {
;     ...
;         if (kt + 1 < ntiles) MLA_STAGE(kt + 1, bnext);
.LBB0_639:
	s_add_i32 s73, s89, 0
	v_add3_u32 v0, s73, v174, v162
	s_andn2_b64 vcc, exec, s[2:3]
	s_cbranch_vccnz .Lmla_splain_0
	s_cmp_ge_u32 s88, s74
	s_cbranch_scc1 .Lmla_splain_0
	s_mul_i32 s91, s76, 0xac00
	ds_read_b128 v[2:5], v0
	ds_read_b128 v[6:9], v0 offset:32
	ds_read_b128 v[10:13], v0 offset:12800
	ds_read_b128 v[186:189], v0 offset:12832
	ds_read_b128 v[190:193], v0 offset:64
	ds_read_b128 v[194:197], v0 offset:96
	ds_read_b128 v[198:201], v0 offset:12864
	ds_read_b128 v[202:205], v0 offset:12896
	ds_read_b128 v[206:209], v0 offset:128
	ds_read_b128 v[210:213], v0 offset:160
	ds_read_b128 v[214:217], v0 offset:12928
	ds_read_b128 v[218:221], v0 offset:12960
	ds_read_b128 v[222:225], v0 offset:192
	ds_read_b128 v[226:229], v0 offset:224
	ds_read_b128 v[230:233], v0 offset:12992
	ds_read_b128 v[234:237], v0 offset:13024
	s_waitcnt lgkmcnt(8)
	v_mfma_f32_32x32x16_bf16 v[96:111], v[2:5], v[112:115], 0
	v_readlane_b32 s90, v255, 11
	v_lshl_add_u32 v253, s88, v176, v166
	s_add_i32 m0, s91, s90
	s_nop 0
	global_load_lds_dwordx4 v253, s[12:13]
	v_mfma_f32_32x32x16_bf16 v[80:95], v[10:13], v[112:115], 0
	v_mfma_f32_32x32x16_bf16 v[96:111], v[6:9], v[116:119], v[96:111]
	v_lshl_add_u32 v253, s88, v177, v167
	s_add_i32 m0, s91, s85
	s_nop 0
	global_load_lds_dwordx4 v253, s[12:13]
	v_mfma_f32_32x32x16_bf16 v[80:95], v[186:189], v[116:119], v[80:95]
	v_mfma_f32_32x32x16_bf16 v[96:111], v[190:193], v[120:123], v[96:111]
	v_lshl_add_u32 v253, s88, v178, v168
	s_add_i32 m0, s91, s72
	s_nop 0
	global_load_lds_dwordx4 v253, s[12:13]
	v_mfma_f32_32x32x16_bf16 v[80:95], v[198:201], v[120:123], v[80:95]
	v_mfma_f32_32x32x16_bf16 v[96:111], v[194:197], v[124:127], v[96:111]
	v_lshl_add_u32 v253, s88, v179, v169
	s_add_i32 m0, s91, s75
	s_nop 0
	global_load_lds_dwordx4 v253, s[12:13]
	v_mfma_f32_32x32x16_bf16 v[80:95], v[202:205], v[124:127], v[80:95]
	ds_read_b128 v[2:5], v0 offset:256
	ds_read_b128 v[6:9], v0 offset:288
	ds_read_b128 v[10:13], v0 offset:13056
	ds_read_b128 v[186:189], v0 offset:13088
	ds_read_b128 v[190:193], v0 offset:320
	ds_read_b128 v[194:197], v0 offset:352
	ds_read_b128 v[198:201], v0 offset:13120
	ds_read_b128 v[202:205], v0 offset:13152
	s_waitcnt lgkmcnt(8)
	v_mfma_f32_32x32x16_bf16 v[96:111], v[206:209], v[128:131], v[96:111]
	v_lshl_add_u32 v253, s88, v180, v170
	s_add_i32 m0, s91, s1
	s_nop 0
	global_load_lds_dwordx4 v253, s[12:13]
	v_mfma_f32_32x32x16_bf16 v[80:95], v[214:217], v[128:131], v[80:95]
	v_mfma_f32_32x32x16_bf16 v[96:111], v[210:213], v[132:135], v[96:111]
	s_andn2_b64 vcc, exec, s[94:95]
	s_cbranch_vccnz .Lmla_a5_s_0
	v_readlane_b32 s90, v255, 9
	v_lshl_add_u32 v253, s88, v181, v171
	s_add_i32 m0, s91, s90
	s_nop 0
	global_load_lds_dwordx4 v253, s[12:13]
.Lmla_a5_s_0:
	v_mfma_f32_32x32x16_bf16 v[80:95], v[218:221], v[132:135], v[80:95]
	v_mfma_f32_32x32x16_bf16 v[96:111], v[222:225], v[136:139], v[96:111]
	v_mfma_f32_32x32x16_bf16 v[80:95], v[230:233], v[136:139], v[80:95]
	v_mfma_f32_32x32x16_bf16 v[96:111], v[226:229], v[140:143], v[96:111]
	v_mfma_f32_32x32x16_bf16 v[80:95], v[234:237], v[140:143], v[80:95]
	s_waitcnt lgkmcnt(0)
	v_mfma_f32_32x32x16_bf16 v[96:111], v[2:5], v[144:147], v[96:111]
	v_mfma_f32_32x32x16_bf16 v[80:95], v[10:13], v[144:147], v[80:95]
	v_mfma_f32_32x32x16_bf16 v[96:111], v[6:9], v[148:151], v[96:111]
	v_mfma_f32_32x32x16_bf16 v[80:95], v[186:189], v[148:151], v[80:95]
	v_mfma_f32_32x32x16_bf16 v[96:111], v[190:193], v[152:155], v[96:111]
	v_mfma_f32_32x32x16_bf16 v[80:95], v[198:201], v[152:155], v[80:95]
	v_mfma_f32_32x32x16_bf16 v[96:111], v[194:197], v[156:159], v[96:111]
	v_mfma_f32_32x32x16_bf16 v[80:95], v[202:205], v[156:159], v[80:95]
	s_cmp_lg_u32 s33, s77
	s_cbranch_scc1 .LBB0_641
	s_branch .Lmla_bb640_0
; #define LAS __attribute__((address_space(3)))
; DI f32x16 zero16() { f32x16 z; for (int i = 0; i < 16; ++i) z[i] = 0.f; return z; }
; #define MFMA32(a, b, c) __builtin_amdgcn_mfma_f32_32x32x16_bf16((a), (b), (c), 0, 0, 0)
; DI void mla_s_softmax(const LAS unsigned char* base, int r, int h, bool is_diag, int lim, const bf16x8 (&qf)[12], f32x16 (&o)[4], float& m_run, float& l_run,
;                       bf16x8 (&pf0)[2], bf16x8 (&pf1)[2]) {
;     f32x16 s0 = zero16(), s1 = zero16();
;     const LAS unsigned char* kp = base + r * MLA_KROW + h * 16;
; #pragma unroll
;     for (int g = 0; g < 3; ++g) {
;         bf16x8 fa[4], fb[4];
; #pragma unroll
;         for (int j = 0; j < 4; ++j) { fa[j] = *(const LAS bf16x8*)(kp + (4 * g + j) * 32); fb[j] = *(const LAS bf16x8*)(kp + 32 * MLA_KROW + (4 * g + j) * 32); }
;         __builtin_amdgcn_sched_barrier(0);
; #pragma unroll
;         for (int j = 0; j < 4; ++j) { s0 = MFMA32(fa[j], qf[4 * g + j], s0); s1 = MFMA32(fb[j], qf[4 * g + j], s1); }
;         __builtin_amdgcn_sched_barrier(0);
;     }
;     if (is_diag) {
; #pragma unroll
;         for (int i = 0; i < 16; ++i) { if (16 * h + i > lim) s0[i] = -1e30f; if (32 + 16 * h + i > lim) s1[i] = -1e30f; }
.Lmla_splain_0:
	ds_read_b128 v[2:5], v0
	ds_read_b128 v[6:9], v0 offset:32
	ds_read_b128 v[10:13], v0 offset:12800
	ds_read_b128 v[186:189], v0 offset:12832
	ds_read_b128 v[190:193], v0 offset:64
	ds_read_b128 v[194:197], v0 offset:96
	ds_read_b128 v[198:201], v0 offset:12864
	ds_read_b128 v[202:205], v0 offset:12896
	ds_read_b128 v[206:209], v0 offset:128
	ds_read_b128 v[210:213], v0 offset:160
	ds_read_b128 v[214:217], v0 offset:12928
	ds_read_b128 v[218:221], v0 offset:12960
	ds_read_b128 v[222:225], v0 offset:192
	ds_read_b128 v[226:229], v0 offset:224
	ds_read_b128 v[230:233], v0 offset:12992
	ds_read_b128 v[234:237], v0 offset:13024
	s_cmp_lg_u32 s33, s77
	s_waitcnt lgkmcnt(8)
	v_mfma_f32_32x32x16_bf16 v[96:111], v[2:5], v[112:115], 0
	v_mfma_f32_32x32x16_bf16 v[80:95], v[10:13], v[112:115], 0
	v_mfma_f32_32x32x16_bf16 v[96:111], v[6:9], v[116:119], v[96:111]
	v_mfma_f32_32x32x16_bf16 v[80:95], v[186:189], v[116:119], v[80:95]
	v_mfma_f32_32x32x16_bf16 v[96:111], v[190:193], v[120:123], v[96:111]
	v_mfma_f32_32x32x16_bf16 v[80:95], v[198:201], v[120:123], v[80:95]
	v_mfma_f32_32x32x16_bf16 v[96:111], v[194:197], v[124:127], v[96:111]
	v_mfma_f32_32x32x16_bf16 v[80:95], v[202:205], v[124:127], v[80:95]
	ds_read_b128 v[2:5], v0 offset:256
	ds_read_b128 v[6:9], v0 offset:288
	ds_read_b128 v[10:13], v0 offset:13056
	ds_read_b128 v[186:189], v0 offset:13088
	ds_read_b128 v[190:193], v0 offset:320
	ds_read_b128 v[194:197], v0 offset:352
	ds_read_b128 v[198:201], v0 offset:13120
	ds_read_b128 v[202:205], v0 offset:13152
	s_waitcnt lgkmcnt(8)
	v_mfma_f32_32x32x16_bf16 v[96:111], v[206:209], v[128:131], v[96:111]
	v_mfma_f32_32x32x16_bf16 v[80:95], v[214:217], v[128:131], v[80:95]
	v_mfma_f32_32x32x16_bf16 v[96:111], v[210:213], v[132:135], v[96:111]
	v_mfma_f32_32x32x16_bf16 v[80:95], v[218:221], v[132:135], v[80:95]
	v_mfma_f32_32x32x16_bf16 v[96:111], v[222:225], v[136:139], v[96:111]
	v_mfma_f32_32x32x16_bf16 v[80:95], v[230:233], v[136:139], v[80:95]
	v_mfma_f32_32x32x16_bf16 v[96:111], v[226:229], v[140:143], v[96:111]
	v_mfma_f32_32x32x16_bf16 v[80:95], v[234:237], v[140:143], v[80:95]
	s_waitcnt lgkmcnt(0)
	v_mfma_f32_32x32x16_bf16 v[96:111], v[2:5], v[144:147], v[96:111]
	v_mfma_f32_32x32x16_bf16 v[80:95], v[10:13], v[144:147], v[80:95]
	v_mfma_f32_32x32x16_bf16 v[96:111], v[6:9], v[148:151], v[96:111]
	v_mfma_f32_32x32x16_bf16 v[80:95], v[186:189], v[148:151], v[80:95]
	v_mfma_f32_32x32x16_bf16 v[96:111], v[190:193], v[152:155], v[96:111]
	v_mfma_f32_32x32x16_bf16 v[80:95], v[198:201], v[152:155], v[80:95]
	v_mfma_f32_32x32x16_bf16 v[96:111], v[194:197], v[156:159], v[96:111]
	v_mfma_f32_32x32x16_bf16 v[80:95], v[202:205], v[156:159], v[80:95]
	s_cbranch_scc1 .LBB0_641
.Lmla_bb640_0:
	v_readlane_b32 s90, v255, 49
	v_readlane_b32 s91, v255, 50
	s_nop 8
	v_cndmask_b32_e64 v80, v80, v164, s[6:7]
	v_cndmask_b32_e64 v97, v164, v97, s[8:9]
	v_cndmask_b32_e64 v0, v96, v164, s[90:91]
	v_cndmask_b32_e64 v96, v0, v96, s[8:9]
	v_cndmask_b32_e64 v81, v81, v164, s[10:11]
	v_cndmask_b32_e64 v98, v98, v164, s[86:87]
	v_cndmask_b32_e64 v82, v82, v164, s[4:5]
	v_cndmask_b32_e64 v99, v99, v164, s[16:17]
	v_cndmask_b32_e64 v83, v83, v164, s[18:19]
	v_cndmask_b32_e64 v100, v100, v164, s[20:21]
	v_cndmask_b32_e64 v84, v84, v164, s[22:23]
	v_cndmask_b32_e64 v101, v101, v164, s[24:25]
	v_cndmask_b32_e64 v85, v85, v164, s[26:27]
	v_cndmask_b32_e64 v102, v102, v164, s[28:29]
	v_cndmask_b32_e64 v86, v86, v164, s[30:31]
	v_cndmask_b32_e64 v103, v103, v164, s[34:35]
	v_cndmask_b32_e64 v87, v87, v164, s[36:37]
	v_cndmask_b32_e64 v104, v104, v164, s[38:39]
	v_cndmask_b32_e64 v88, v88, v164, s[40:41]
	v_cndmask_b32_e64 v105, v105, v164, s[42:43]
	v_cndmask_b32_e64 v89, v89, v164, s[44:45]
	v_cndmask_b32_e64 v106, v106, v164, s[46:47]
	v_cndmask_b32_e64 v90, v90, v164, s[48:49]
	v_cndmask_b32_e64 v107, v107, v164, s[50:51]
	v_cndmask_b32_e64 v91, v91, v164, s[52:53]
	v_cndmask_b32_e64 v108, v108, v164, s[54:55]
	v_cndmask_b32_e64 v92, v92, v164, s[56:57]
	v_cndmask_b32_e64 v109, v109, v164, s[58:59]
	v_cndmask_b32_e64 v93, v93, v164, s[60:61]
	v_cndmask_b32_e64 v110, v110, v164, s[62:63]
	v_cndmask_b32_e64 v94, v94, v164, s[64:65]
	v_cndmask_b32_e64 v111, v111, v164, s[66:67]
	v_cndmask_b32_e64 v95, v95, v164, s[68:69]

; DI unsigned pk2(float lo, float hi) { f32x2 v = {lo, hi}; bf2_t r = __builtin_convertvector(v, bf2_t); return __builtin_bit_cast(unsigned, r); }
; DI float xhalf_sum(float x) { float lo, hi; xhalf(x, lo, hi); return lo + hi; }
; DI void mla_block(const Params& p, LAS unsigned char* lds, int b, int hd, int qb, int tid) {
;     ...
;     const float lt = xhalf_sum(l_run), inv = 1.f / lt;
;     bf16_t* mix = (bf16_t*)(p.ws + OFF_MIX) + (tok0 + q0 + r) * 1024 + 512 + hd * 128 + 4 * h;
;     float ss = 0.f;
; #pragma unroll
;     for (int dt = 0; dt < 4; ++dt)
; #pragma unroll
;         for (int g = 0; g < 4; ++g) {
;             const float a0 = o[dt][4 * g] * inv, a1 = o[dt][4 * g + 1] * inv, a2 = o[dt][4 * g + 2] * inv, a3 = o[dt][4 * g + 3] * inv;
;             ss += (a0 * a0 + a1 * a1) + (a2 * a2 + a3 * a3);
;             u32x2 w; w.x = pk2(a0, a1); w.y = pk2(a2, a3);
;             *(u32x2*)(mix + dt * 32 + 8 * g) = w;
;         }
.LBB0_653:
	v_mov_b32_e32 v0, v175
	s_nop 1
	v_permlane32_swap_b32_e32 v175, v0
	v_add_f32_e32 v0, v175, v0
	v_div_scale_f32 v2, s[0:1], v0, v0, 1.0
	v_rcp_f32_e32 v3, v2
	s_mov_b64 s[18:19], s[14:15]
	s_mov_b64 s[16:17], s[12:13]
	v_readlane_b32 s18, v255, 43
	v_fma_f32 v4, -v2, v3, 1.0
	v_fmac_f32_e32 v3, v4, v3
	v_div_scale_f32 v4, vcc, 1.0, v0, 1.0
	v_mul_f32_e32 v5, v4, v3
	v_fma_f32 v6, -v2, v5, v4
	v_fmac_f32_e32 v5, v6, v3
	v_fma_f32 v2, -v2, v5, v4
	v_div_fmas_f32 v2, v2, v3, v5
	v_lshlrev_b64 v[4:5], 11, v[160:161]
	v_lshl_add_u64 v[4:5], s[16:17], 0, v[4:5]
	v_readlane_b32 s19, v255, 44
	s_lshl_b32 s18, s18, 1
	v_div_fixup_f32 v2, v2, v0, 1.0
	v_lshl_add_u64 v[4:5], v[4:5], 0, s[18:19]
	v_lshlrev_b32_e32 v0, 3, v165
	v_lshl_add_u64 v[6:7], v[4:5], 0, v[0:1]
	s_mov_b64 s[0:1], 0x2a000400
	v_lshl_add_u64 v[4:5], v[6:7], 0, s[0:1]
	v_pk_mul_f32 v[8:9], v[64:65], v[2:3] op_sel_hi:[1,0]
	s_mov_b32 s0, 0x2a000000
	v_pk_mul_f32 v[10:11], v[66:67], v[2:3] op_sel_hi:[1,0]
	v_mul_f32_e32 v0, v9, v9
	v_add_co_u32_e32 v6, vcc, s0, v6
	v_pk_fma_f32 v[12:13], v[8:9], v[8:9], v[0:1] op_sel_hi:[1,1,0]
	v_cvt_pk_bf16_f32 v200, v8, v9
	v_cvt_pk_bf16_f32 v201, v10, v11
	v_addc_co_u32_e32 v7, vcc, 0, v7, vcc
	v_mul_f32_e32 v0, v11, v11
	v_pk_mul_f32 v[6:7], v[68:69], v[2:3] op_sel_hi:[1,0]
	v_pk_fma_f32 v[14:15], v[10:11], v[10:11], v[0:1] op_sel_hi:[1,1,0]
	v_pk_mul_f32 v[8:9], v[70:71], v[2:3] op_sel_hi:[1,0]
	v_mul_f32_e32 v0, v7, v7
	v_pk_fma_f32 v[10:11], v[6:7], v[6:7], v[0:1] op_sel_hi:[1,1,0]
	v_mul_f32_e32 v0, v9, v9
	v_cvt_pk_bf16_f32 v202, v6, v7
	v_cvt_pk_bf16_f32 v203, v8, v9
	v_pk_add_f32 v[12:13], v[12:13], v[14:15]
	v_pk_fma_f32 v[14:15], v[8:9], v[8:9], v[0:1] op_sel_hi:[1,1,0]
	v_pk_mul_f32 v[6:7], v[72:73], v[2:3] op_sel_hi:[1,0]
	v_pk_add_f32 v[10:11], v[10:11], v[14:15]
	v_pk_mul_f32 v[8:9], v[74:75], v[2:3] op_sel_hi:[1,0]
	v_mul_f32_e32 v0, v7, v7
	v_pk_add_f32 v[10:11], v[12:13], v[10:11]
	v_pk_fma_f32 v[12:13], v[6:7], v[6:7], v[0:1] op_sel_hi:[1,1,0]
	v_mul_f32_e32 v0, v9, v9
	v_cvt_pk_bf16_f32 v204, v6, v7
	v_cvt_pk_bf16_f32 v205, v8, v9
	v_pk_fma_f32 v[14:15], v[8:9], v[8:9], v[0:1] op_sel_hi:[1,1,0]
	v_pk_mul_f32 v[6:7], v[76:77], v[2:3] op_sel_hi:[1,0]
	v_pk_add_f32 v[12:13], v[12:13], v[14:15]
	v_pk_mul_f32 v[8:9], v[78:79], v[2:3] op_sel_hi:[1,0]
	v_mul_f32_e32 v0, v7, v7
	v_pk_add_f32 v[10:11], v[12:13], v[10:11]
	v_pk_fma_f32 v[12:13], v[6:7], v[6:7], v[0:1] op_sel_hi:[1,1,0]
	v_mul_f32_e32 v0, v9, v9
	v_cvt_pk_bf16_f32 v206, v6, v7
	v_cvt_pk_bf16_f32 v207, v8, v9
	v_pk_fma_f32 v[14:15], v[8:9], v[8:9], v[0:1] op_sel_hi:[1,1,0]
	v_pk_mul_f32 v[6:7], v[48:49], v[2:3] op_sel_hi:[1,0]
	v_pk_add_f32 v[12:13], v[12:13], v[14:15]
	v_pk_mul_f32 v[8:9], v[50:51], v[2:3] op_sel_hi:[1,0]
	v_mul_f32_e32 v0, v7, v7
	v_pk_add_f32 v[10:11], v[12:13], v[10:11]
	v_pk_fma_f32 v[12:13], v[6:7], v[6:7], v[0:1] op_sel_hi:[1,1,0]
	v_mul_f32_e32 v0, v9, v9
	v_cvt_pk_bf16_f32 v208, v6, v7
	v_cvt_pk_bf16_f32 v209, v8, v9
	v_pk_fma_f32 v[14:15], v[8:9], v[8:9], v[0:1] op_sel_hi:[1,1,0]
	v_pk_mul_f32 v[6:7], v[52:53], v[2:3] op_sel_hi:[1,0]
	v_pk_add_f32 v[12:13], v[12:13], v[14:15]
	v_pk_mul_f32 v[8:9], v[54:55], v[2:3] op_sel_hi:[1,0]
	v_mul_f32_e32 v0, v7, v7
	v_pk_add_f32 v[10:11], v[12:13], v[10:11]
	v_pk_fma_f32 v[12:13], v[6:7], v[6:7], v[0:1] op_sel_hi:[1,1,0]
	v_mul_f32_e32 v0, v9, v9
	v_cvt_pk_bf16_f32 v210, v6, v7
	v_cvt_pk_bf16_f32 v211, v8, v9
	v_pk_fma_f32 v[14:15], v[8:9], v[8:9], v[0:1] op_sel_hi:[1,1,0]
	v_pk_mul_f32 v[6:7], v[56:57], v[2:3] op_sel_hi:[1,0]
	v_pk_add_f32 v[12:13], v[12:13], v[14:15]
	v_pk_mul_f32 v[8:9], v[58:59], v[2:3] op_sel_hi:[1,0]
	v_mul_f32_e32 v0, v7, v7
	v_pk_add_f32 v[10:11], v[12:13], v[10:11]
	v_pk_fma_f32 v[12:13], v[6:7], v[6:7], v[0:1] op_sel_hi:[1,1,0]
	v_mul_f32_e32 v0, v9, v9
	v_cvt_pk_bf16_f32 v212, v6, v7
	v_cvt_pk_bf16_f32 v213, v8, v9
	v_pk_fma_f32 v[14:15], v[8:9], v[8:9], v[0:1] op_sel_hi:[1,1,0]
	v_pk_mul_f32 v[6:7], v[60:61], v[2:3] op_sel_hi:[1,0]
	v_pk_add_f32 v[12:13], v[12:13], v[14:15]
	v_pk_mul_f32 v[8:9], v[62:63], v[2:3] op_sel_hi:[1,0]
	v_mul_f32_e32 v0, v7, v7
	v_pk_add_f32 v[10:11], v[12:13], v[10:11]
	v_pk_fma_f32 v[12:13], v[6:7], v[6:7], v[0:1] op_sel_hi:[1,1,0]
	v_mul_f32_e32 v0, v9, v9
	v_cvt_pk_bf16_f32 v214, v6, v7
	v_cvt_pk_bf16_f32 v215, v8, v9
	v_pk_fma_f32 v[14:15], v[8:9], v[8:9], v[0:1] op_sel_hi:[1,1,0]
	v_pk_mul_f32 v[6:7], v[32:33], v[2:3] op_sel_hi:[1,0]
	v_pk_add_f32 v[12:13], v[12:13], v[14:15]
	v_pk_mul_f32 v[8:9], v[34:35], v[2:3] op_sel_hi:[1,0]
	v_mul_f32_e32 v0, v7, v7
	v_pk_add_f32 v[10:11], v[12:13], v[10:11]
	v_pk_fma_f32 v[12:13], v[6:7], v[6:7], v[0:1] op_sel_hi:[1,1,0]
	v_mul_f32_e32 v0, v9, v9
	v_cvt_pk_bf16_f32 v216, v6, v7
	v_cvt_pk_bf16_f32 v217, v8, v9
	v_pk_fma_f32 v[14:15], v[8:9], v[8:9], v[0:1] op_sel_hi:[1,1,0]
	v_pk_mul_f32 v[6:7], v[36:37], v[2:3] op_sel_hi:[1,0]
	v_pk_add_f32 v[12:13], v[12:13], v[14:15]
	v_pk_mul_f32 v[8:9], v[38:39], v[2:3] op_sel_hi:[1,0]
	v_mul_f32_e32 v0, v7, v7
; DI unsigned pk2(float lo, float hi) { f32x2 v = {lo, hi}; bf2_t r = __builtin_convertvector(v, bf2_t); return __builtin_bit_cast(unsigned, r); }
; DI float xhalf_sum(float x) { float lo, hi; xhalf(x, lo, hi); return lo + hi; }
; DI void mla_block(const Params& p, LAS unsigned char* lds, int b, int hd, int qb, int tid) {
;     ...
; #pragma unroll
;     for (int dt = 0; dt < 4; ++dt)
; #pragma unroll
;         for (int g = 0; g < 4; ++g) {
;             const float a0 = o[dt][4 * g] * inv, a1 = o[dt][4 * g + 1] * inv, a2 = o[dt][4 * g + 2] * inv, a3 = o[dt][4 * g + 3] * inv;
;             ss += (a0 * a0 + a1 * a1) + (a2 * a2 + a3 * a3);
;             u32x2 w; w.x = pk2(a0, a1); w.y = pk2(a2, a3);
;             *(u32x2*)(mix + dt * 32 + 8 * g) = w;
;         }
;     ss = xhalf_sum(ss);
;     if (h == 0) ((float*)(p.ws + OFF_HSS))[(tok0 + q0 + r) * 16 + 8 + hd] = ss;
	v_pk_add_f32 v[10:11], v[12:13], v[10:11]
	v_pk_fma_f32 v[12:13], v[6:7], v[6:7], v[0:1] op_sel_hi:[1,1,0]
	v_mul_f32_e32 v0, v9, v9
	v_cvt_pk_bf16_f32 v218, v6, v7
	v_cvt_pk_bf16_f32 v219, v8, v9
	v_pk_fma_f32 v[14:15], v[8:9], v[8:9], v[0:1] op_sel_hi:[1,1,0]
	v_pk_mul_f32 v[6:7], v[40:41], v[2:3] op_sel_hi:[1,0]
	v_pk_add_f32 v[12:13], v[12:13], v[14:15]
	v_pk_mul_f32 v[8:9], v[42:43], v[2:3] op_sel_hi:[1,0]
	v_mul_f32_e32 v0, v7, v7
	v_pk_add_f32 v[10:11], v[12:13], v[10:11]
	v_pk_fma_f32 v[12:13], v[6:7], v[6:7], v[0:1] op_sel_hi:[1,1,0]
	v_mul_f32_e32 v0, v9, v9
	v_cvt_pk_bf16_f32 v220, v6, v7
	v_cvt_pk_bf16_f32 v221, v8, v9
	v_pk_fma_f32 v[14:15], v[8:9], v[8:9], v[0:1] op_sel_hi:[1,1,0]
	v_pk_mul_f32 v[6:7], v[44:45], v[2:3] op_sel_hi:[1,0]
	v_pk_add_f32 v[12:13], v[12:13], v[14:15]
	v_pk_mul_f32 v[8:9], v[46:47], v[2:3] op_sel_hi:[1,0]
	v_mul_f32_e32 v0, v7, v7
	v_pk_add_f32 v[10:11], v[12:13], v[10:11]
	v_pk_fma_f32 v[12:13], v[6:7], v[6:7], v[0:1] op_sel_hi:[1,1,0]
	v_mul_f32_e32 v0, v9, v9
	v_cvt_pk_bf16_f32 v222, v6, v7
	v_cvt_pk_bf16_f32 v223, v8, v9
	v_pk_fma_f32 v[14:15], v[8:9], v[8:9], v[0:1] op_sel_hi:[1,1,0]
	v_pk_mul_f32 v[6:7], v[16:17], v[2:3] op_sel_hi:[1,0]
	v_pk_add_f32 v[12:13], v[12:13], v[14:15]
	v_pk_mul_f32 v[8:9], v[18:19], v[2:3] op_sel_hi:[1,0]
	v_mul_f32_e32 v0, v7, v7
	v_pk_add_f32 v[10:11], v[12:13], v[10:11]
	v_pk_fma_f32 v[12:13], v[6:7], v[6:7], v[0:1] op_sel_hi:[1,1,0]
	v_mul_f32_e32 v0, v9, v9
	v_cvt_pk_bf16_f32 v224, v6, v7
	v_cvt_pk_bf16_f32 v225, v8, v9
	v_pk_fma_f32 v[14:15], v[8:9], v[8:9], v[0:1] op_sel_hi:[1,1,0]
	v_pk_mul_f32 v[6:7], v[20:21], v[2:3] op_sel_hi:[1,0]
	v_pk_add_f32 v[12:13], v[12:13], v[14:15]
	v_pk_mul_f32 v[8:9], v[22:23], v[2:3] op_sel_hi:[1,0]
	v_mul_f32_e32 v0, v7, v7
	v_pk_add_f32 v[10:11], v[12:13], v[10:11]
	v_pk_fma_f32 v[12:13], v[6:7], v[6:7], v[0:1] op_sel_hi:[1,1,0]
	v_mul_f32_e32 v0, v9, v9
	v_cvt_pk_bf16_f32 v226, v6, v7
	v_cvt_pk_bf16_f32 v227, v8, v9
	v_pk_fma_f32 v[14:15], v[8:9], v[8:9], v[0:1] op_sel_hi:[1,1,0]
	v_pk_mul_f32 v[6:7], v[24:25], v[2:3] op_sel_hi:[1,0]
	v_pk_add_f32 v[12:13], v[12:13], v[14:15]
	v_pk_mul_f32 v[8:9], v[26:27], v[2:3] op_sel_hi:[1,0]
	v_mul_f32_e32 v0, v7, v7
	v_pk_add_f32 v[10:11], v[12:13], v[10:11]
	v_pk_fma_f32 v[12:13], v[6:7], v[6:7], v[0:1] op_sel_hi:[1,1,0]
	v_cvt_pk_bf16_f32 v228, v6, v7
	v_cvt_pk_bf16_f32 v229, v8, v9
	v_mul_f32_e32 v0, v9, v9
	v_pk_mul_f32 v[6:7], v[28:29], v[2:3] op_sel_hi:[1,0]
	v_pk_fma_f32 v[14:15], v[8:9], v[8:9], v[0:1] op_sel_hi:[1,1,0]
	v_pk_mul_f32 v[8:9], v[30:31], v[2:3] op_sel_hi:[1,0]
	v_mul_f32_e32 v0, v7, v7
	v_pk_add_f32 v[12:13], v[12:13], v[14:15]
	v_pk_fma_f32 v[2:3], v[6:7], v[6:7], v[0:1] op_sel_hi:[1,1,0]
	v_mul_f32_e32 v0, v9, v9
	v_pk_add_f32 v[10:11], v[12:13], v[10:11]
	v_pk_fma_f32 v[12:13], v[8:9], v[8:9], v[0:1] op_sel_hi:[1,1,0]
	v_readlane_b32 s6, v255, 35
	v_pk_add_f32 v[2:3], v[2:3], v[12:13]
	v_readlane_b32 s8, v255, 37
	v_pk_add_f32 v[2:3], v[2:3], v[10:11]
	v_readlane_b32 s7, v255, 36
	v_mov_b32_e32 v0, v2
	v_readlane_b32 s9, v255, 38
	s_mov_b32 s20, 0x1e000000
	s_mov_b32 s21, 0x51eb851f
	s_movk_i32 s22, 0xffe7
	v_readlane_b32 s23, v255, 42
	v_readlane_b32 s24, v255, 41
	v_readlane_b32 s25, v255, 40
	v_cvt_pk_bf16_f32 v230, v6, v7
	v_cvt_pk_bf16_f32 v231, v8, v9
	v_permlane32_swap_b32_e32 v2, v0
	v_cmp_gt_u32_e32 vcc, 32, v163
	v_mbcnt_lo_u32_b32 v252, -1, 0
	v_mbcnt_hi_u32_b32 v252, -1, v252
	v_lshrrev_b32_e32 v252, 5, v252
	v_lshlrev_b32_e32 v252, 3, v252
	v_mov_b32_e32 v253, 0
	v_lshl_add_u64 v[252:253], v[4:5], 0, v[252:253]
	v_permlane32_swap_b32_e32 v200, v202
	v_permlane32_swap_b32_e32 v201, v203
	v_permlane32_swap_b32_e32 v204, v206
	v_permlane32_swap_b32_e32 v205, v207
	v_permlane32_swap_b32_e32 v208, v210
	v_permlane32_swap_b32_e32 v209, v211
	v_permlane32_swap_b32_e32 v212, v214
	v_permlane32_swap_b32_e32 v213, v215
	v_permlane32_swap_b32_e32 v216, v218
	v_permlane32_swap_b32_e32 v217, v219
	v_permlane32_swap_b32_e32 v220, v222
	v_permlane32_swap_b32_e32 v221, v223
	v_permlane32_swap_b32_e32 v224, v226
	v_permlane32_swap_b32_e32 v225, v227
	v_permlane32_swap_b32_e32 v228, v230
	v_permlane32_swap_b32_e32 v229, v231
	global_store_dwordx4 v[252:253], v[200:203], off
	global_store_dwordx4 v[252:253], v[204:207], off offset:32
	global_store_dwordx4 v[252:253], v[208:211], off offset:64
	global_store_dwordx4 v[252:253], v[212:215], off offset:96
	global_store_dwordx4 v[252:253], v[216:219], off offset:128
	global_store_dwordx4 v[252:253], v[220:223], off offset:160
	global_store_dwordx4 v[252:253], v[224:227], off offset:192
	global_store_dwordx4 v[252:253], v[228:231], off offset:224
	s_and_saveexec_b64 s[2:3], vcc
	s_cbranch_execz .LBB0_655
	v_readlane_b32 s0, v255, 31
	v_lshlrev_b64 v[4:5], 6, v[160:161]
	v_readlane_b32 s1, v255, 32
	v_add_f32_e32 v0, v2, v0
	s_nop 0
	v_lshl_add_u64 v[4:5], s[0:1], 0, v[4:5]
	v_readlane_b32 s0, v255, 39
	s_lshl_b32 s0, s0, 2
	s_mov_b32 s1, s19
	v_lshl_add_u64 v[4:5], v[4:5], 0, s[0:1]
	global_store_dword v[4:5], v0, off

; DI void mla_block(const Params& p, LAS unsigned char* lds, int b, int hd, int qb, int tid) {
;     ...
;     for (int kt = 0; kt < ntiles; ++kt) {
;         asm volatile("s_waitcnt vmcnt(0)" ::: "memory");
;         __builtin_amdgcn_s_barrier();
;         asm volatile("" ::: "memory");
;         const int bprev = bcur == 0 ? 2 : bcur - 1, bnext = bcur == 2 ? 0 : bcur + 1;
;         if (kt + 1 < ntiles) MLA_STAGE(kt + 1, bnext);
;         if (late && kt >= 1 && kt - 1 <= wlast) mla_pv(lds + bprev * MLA_BUF, r, h, pf0, pf1, o);
.LBB0_724:
	s_add_i32 s76, s87, 1
	s_waitcnt vmcnt(0)
	s_barrier
	s_cmp_lg_u32 s87, 2
	s_cselect_b32 s76, s76, 0
	s_add_i32 s77, s88, 1
	s_cmp_ge_u32 s77, s73
	s_cbranch_scc1 .LBB0_737
	s_andn2_b64 vcc, exec, s[2:3]
	s_cbranch_vccnz .Lmla_toplate_1
	s_cmp_gt_i32 s88, s33
	s_cbranch_scc0 .LBB0_737
	s_branch .Lmla_stnow_1
.Lmla_toplate_1:
	s_cmp_eq_u32 s88, 0
	s_cbranch_scc1 .Lmla_stnow_1
	s_cmp_le_i32 s88, s74
	s_cbranch_scc1 .LBB0_737

; #define LAS __attribute__((address_space(3)))
; #define MFMA32(a, b, c) __builtin_amdgcn_mfma_f32_32x32x16_bf16((a), (b), (c), 0, 0, 0)
; DI void mla_pv(const LAS unsigned char* base, int r, int h, const bf16x8 (&pf0)[2], const bf16x8 (&pf1)[2], f32x16 (&o)[4]) {
;     const LAS unsigned char* vp = base + MLA_KBYTES + r * MLA_VROW + h * 32;
; #pragma unroll
;     for (int s = 0; s < 2; ++s) {
;         bf16x8 va[4], vb[4];
; #pragma unroll
;         for (int dt = 0; dt < 4; ++dt) { va[dt] = *(const LAS bf16x8*)(vp + dt * 32 * MLA_VROW + s * 16); vb[dt] = *(const LAS bf16x8*)(vp + dt * 32 * MLA_VROW + 64 + s * 16); }
;         __builtin_amdgcn_sched_barrier(0);
; #pragma unroll
;         for (int dt = 0; dt < 4; ++dt) o[dt] = MFMA32(va[dt], pf0[s], o[dt]);
; #pragma unroll
;         for (int dt = 0; dt < 4; ++dt) o[dt] = MFMA32(vb[dt], pf1[s], o[dt]);
;         __builtin_amdgcn_sched_barrier(0);
;     }
; }
; DI void mla_block(const Params& p, LAS unsigned char* lds, int b, int hd, int qb, int tid) {
;     ...
;         if (kt + 1 < ntiles) MLA_STAGE(kt + 1, bnext);
.LBB0_737:
	s_cmp_lg_u32 s88, 0
	s_cselect_b64 s[90:91], -1, 0
	s_and_b64 s[90:91], s[78:79], s[90:91]
	s_cmp_le_i32 s88, s74
	s_cselect_b64 vcc, -1, 0
	s_and_b64 s[90:91], s[90:91], vcc
	s_andn2_b64 vcc, exec, s[90:91]
	s_mul_i32 s89, s87, 0xac00
	s_cbranch_vccnz .LBB0_740
	s_add_i32 s90, s89, 0xffff5400
	s_cmp_lg_u32 s87, 0
	s_cselect_b32 s87, s90, 0x15800
	v_add_u32_e32 v0, s87, v182
	ds_read_b128 v[84:87], v0 offset:25600
	ds_read_b128 v[88:91], v0 offset:25664
	ds_read_b128 v[92:95], v0 offset:30208
	ds_read_b128 v[96:99], v0 offset:30272
	ds_read_b128 v[100:103], v0 offset:34816
	ds_read_b128 v[104:107], v0 offset:34880
	ds_read_b128 v[108:111], v0 offset:39424
	ds_read_b128 v[186:189], v0 offset:39488
	ds_read_b128 v[200:203], v0 offset:25616
	ds_read_b128 v[204:207], v0 offset:25680
	ds_read_b128 v[208:211], v0 offset:30224
	ds_read_b128 v[212:215], v0 offset:30288
	ds_read_b128 v[216:219], v0 offset:34832
	ds_read_b128 v[220:223], v0 offset:34896
	ds_read_b128 v[224:227], v0 offset:39440
	ds_read_b128 v[228:231], v0 offset:39504
	s_cmp_ge_u32 s77, s73
	s_cbranch_scc1 .Lmla_pvplain_1
	s_mul_i32 s91, s76, 0xac00
	s_waitcnt lgkmcnt(8)
	v_mfma_f32_32x32x16_bf16 v[64:79], v[84:87], v[80:83], v[64:79]
	v_readlane_b32 s90, v255, 9
	v_lshl_add_u32 v253, s77, v176, v166
	s_add_i32 m0, s91, s90
	s_nop 0
	global_load_lds_dwordx4 v253, s[12:13]
	v_mfma_f32_32x32x16_bf16 v[48:63], v[92:95], v[80:83], v[48:63]
	v_mfma_f32_32x32x16_bf16 v[32:47], v[100:103], v[80:83], v[32:47]
	v_lshl_add_u32 v253, s77, v177, v167
	s_add_i32 m0, s91, s75
	s_nop 0
	global_load_lds_dwordx4 v253, s[12:13]
	v_mfma_f32_32x32x16_bf16 v[16:31], v[108:111], v[80:83], v[16:31]
	v_mfma_f32_32x32x16_bf16 v[64:79], v[88:91], v[6:9], v[64:79]
	v_readlane_b32 s90, v255, 11
	v_lshl_add_u32 v253, s77, v178, v168
	s_add_i32 m0, s91, s90
	s_nop 0
	global_load_lds_dwordx4 v253, s[12:13]
	v_mfma_f32_32x32x16_bf16 v[48:63], v[96:99], v[6:9], v[48:63]
	v_mfma_f32_32x32x16_bf16 v[32:47], v[104:107], v[6:9], v[32:47]
	v_readlane_b32 s90, v255, 49
	v_lshl_add_u32 v253, s77, v179, v169
	s_add_i32 m0, s91, s90
	s_nop 0
	global_load_lds_dwordx4 v253, s[12:13]
	v_mfma_f32_32x32x16_bf16 v[16:31], v[186:189], v[6:9], v[16:31]
	s_waitcnt lgkmcnt(0)
	v_mfma_f32_32x32x16_bf16 v[64:79], v[200:203], v[10:13], v[64:79]
	v_lshl_add_u32 v253, s77, v180, v170
	s_add_i32 m0, s91, s86
	s_nop 0
	global_load_lds_dwordx4 v253, s[12:13]
	v_mfma_f32_32x32x16_bf16 v[48:63], v[208:211], v[10:13], v[48:63]
	v_mfma_f32_32x32x16_bf16 v[32:47], v[216:219], v[10:13], v[32:47]
	s_andn2_b64 vcc, exec, s[94:95]
	s_cbranch_vccnz .Lmla_a5_pv_1
	v_lshl_add_u32 v253, s77, v181, v171
	s_add_i32 m0, s91, s72
	s_nop 0
	global_load_lds_dwordx4 v253, s[12:13]

; DI void mla_block(const Params& p, LAS unsigned char* lds, int b, int hd, int qb, int tid) {
;     ...
;         if (kt <= wlast) {
;             mla_s_softmax(lds + bcur * MLA_BUF, r, h, kt == wlast, q0 + r - kt * 64, qf, o, m_run, l_run, pf0, pf1);
.Lmla_pvdone_1:
	s_cmp_gt_i32 s88, s33
	s_cbranch_scc0 .LBB0_741

; #define LAS __attribute__((address_space(3)))
; DI f32x16 zero16() { f32x16 z; for (int i = 0; i < 16; ++i) z[i] = 0.f; return z; }
; #define MFMA32(a, b, c) __builtin_amdgcn_mfma_f32_32x32x16_bf16((a), (b), (c), 0, 0, 0)
; DI void mla_s_softmax(const LAS unsigned char* base, int r, int h, bool is_diag, int lim, const bf16x8 (&qf)[12], f32x16 (&o)[4], float& m_run, float& l_run,
;                       bf16x8 (&pf0)[2], bf16x8 (&pf1)[2]) {
;     f32x16 s0 = zero16(), s1 = zero16();
;     const LAS unsigned char* kp = base + r * MLA_KROW + h * 16;
; #pragma unroll
;     for (int g = 0; g < 3; ++g) {
;         bf16x8 fa[4], fb[4];
; #pragma unroll
;         for (int j = 0; j < 4; ++j) { fa[j] = *(const LAS bf16x8*)(kp + (4 * g + j) * 32); fb[j] = *(const LAS bf16x8*)(kp + 32 * MLA_KROW + (4 * g + j) * 32); }
;         __builtin_amdgcn_sched_barrier(0);
; #pragma unroll
;         for (int j = 0; j < 4; ++j) { s0 = MFMA32(fa[j], qf[4 * g + j], s0); s1 = MFMA32(fb[j], qf[4 * g + j], s1); }
;         __builtin_amdgcn_sched_barrier(0);
;     }
; DI void mla_block(const Params& p, LAS unsigned char* lds, int b, int hd, int qb, int tid) {
;     ...
;         if (kt + 1 < ntiles) MLA_STAGE(kt + 1, bnext);
.LBB0_741:
	s_add_i32 s87, s89, 0
	v_add3_u32 v0, s87, v175, v162
	s_andn2_b64 vcc, exec, s[2:3]
	s_cbranch_vccnz .Lmla_splain_1
	s_cmp_ge_u32 s77, s73
	s_cbranch_scc1 .Lmla_splain_1
	s_mul_i32 s91, s76, 0xac00
	ds_read_b128 v[2:5], v0
	ds_read_b128 v[6:9], v0 offset:32
	ds_read_b128 v[10:13], v0 offset:12800
	ds_read_b128 v[186:189], v0 offset:12832
	ds_read_b128 v[190:193], v0 offset:64
	ds_read_b128 v[194:197], v0 offset:96
	ds_read_b128 v[198:201], v0 offset:12864
	ds_read_b128 v[202:205], v0 offset:12896
	ds_read_b128 v[206:209], v0 offset:128
	ds_read_b128 v[210:213], v0 offset:160
	ds_read_b128 v[214:217], v0 offset:12928
	ds_read_b128 v[218:221], v0 offset:12960
	ds_read_b128 v[222:225], v0 offset:192
	ds_read_b128 v[226:229], v0 offset:224
	ds_read_b128 v[230:233], v0 offset:12992
	ds_read_b128 v[234:237], v0 offset:13024
	s_waitcnt lgkmcnt(8)
	v_mfma_f32_32x32x16_bf16 v[96:111], v[2:5], v[112:115], 0
	v_readlane_b32 s90, v255, 9
	v_lshl_add_u32 v253, s77, v176, v166
	s_add_i32 m0, s91, s90
	s_nop 0
	global_load_lds_dwordx4 v253, s[12:13]
	v_mfma_f32_32x32x16_bf16 v[80:95], v[10:13], v[112:115], 0
	v_mfma_f32_32x32x16_bf16 v[96:111], v[6:9], v[116:119], v[96:111]
	v_lshl_add_u32 v253, s77, v177, v167
	s_add_i32 m0, s91, s75
	s_nop 0
	global_load_lds_dwordx4 v253, s[12:13]
	v_mfma_f32_32x32x16_bf16 v[80:95], v[186:189], v[116:119], v[80:95]
	v_mfma_f32_32x32x16_bf16 v[96:111], v[190:193], v[120:123], v[96:111]
	v_readlane_b32 s90, v255, 11
	v_lshl_add_u32 v253, s77, v178, v168
	s_add_i32 m0, s91, s90
	s_nop 0
	global_load_lds_dwordx4 v253, s[12:13]
	v_mfma_f32_32x32x16_bf16 v[80:95], v[198:201], v[120:123], v[80:95]
	v_mfma_f32_32x32x16_bf16 v[96:111], v[194:197], v[124:127], v[96:111]
	v_readlane_b32 s90, v255, 49
	v_lshl_add_u32 v253, s77, v179, v169
	s_add_i32 m0, s91, s90
	s_nop 0
	global_load_lds_dwordx4 v253, s[12:13]
	v_mfma_f32_32x32x16_bf16 v[80:95], v[202:205], v[124:127], v[80:95]
	ds_read_b128 v[2:5], v0 offset:256
	ds_read_b128 v[6:9], v0 offset:288
	ds_read_b128 v[10:13], v0 offset:13056
	ds_read_b128 v[186:189], v0 offset:13088
	ds_read_b128 v[190:193], v0 offset:320
	ds_read_b128 v[194:197], v0 offset:352
	ds_read_b128 v[198:201], v0 offset:13120
	ds_read_b128 v[202:205], v0 offset:13152
	s_waitcnt lgkmcnt(8)
	v_mfma_f32_32x32x16_bf16 v[96:111], v[206:209], v[128:131], v[96:111]
	v_lshl_add_u32 v253, s77, v180, v170
	s_add_i32 m0, s91, s86
	s_nop 0
	global_load_lds_dwordx4 v253, s[12:13]
	v_mfma_f32_32x32x16_bf16 v[80:95], v[214:217], v[128:131], v[80:95]
	v_mfma_f32_32x32x16_bf16 v[96:111], v[210:213], v[132:135], v[96:111]
	s_andn2_b64 vcc, exec, s[94:95]
	s_cbranch_vccnz .Lmla_a5_s_1
	v_lshl_add_u32 v253, s77, v181, v171
	s_add_i32 m0, s91, s72
	s_nop 0
	global_load_lds_dwordx4 v253, s[12:13]
.Lmla_a5_s_1:
	v_mfma_f32_32x32x16_bf16 v[80:95], v[218:221], v[132:135], v[80:95]
	v_mfma_f32_32x32x16_bf16 v[96:111], v[222:225], v[136:139], v[96:111]
	v_mfma_f32_32x32x16_bf16 v[80:95], v[230:233], v[136:139], v[80:95]
	v_mfma_f32_32x32x16_bf16 v[96:111], v[226:229], v[140:143], v[96:111]
	v_mfma_f32_32x32x16_bf16 v[80:95], v[234:237], v[140:143], v[80:95]
	s_waitcnt lgkmcnt(0)
	v_mfma_f32_32x32x16_bf16 v[96:111], v[2:5], v[144:147], v[96:111]
	v_mfma_f32_32x32x16_bf16 v[80:95], v[10:13], v[144:147], v[80:95]
	v_mfma_f32_32x32x16_bf16 v[96:111], v[6:9], v[148:151], v[96:111]
	v_mfma_f32_32x32x16_bf16 v[80:95], v[186:189], v[148:151], v[80:95]
	v_mfma_f32_32x32x16_bf16 v[96:111], v[190:193], v[152:155], v[96:111]
	v_mfma_f32_32x32x16_bf16 v[80:95], v[198:201], v[152:155], v[80:95]
	v_mfma_f32_32x32x16_bf16 v[96:111], v[194:197], v[156:159], v[96:111]
	v_mfma_f32_32x32x16_bf16 v[80:95], v[202:205], v[156:159], v[80:95]
	s_cmp_lg_u32 s33, s88
	s_cbranch_scc1 .LBB0_743
	s_branch .Lmla_bb640_1
; #define LAS __attribute__((address_space(3)))
; DI f32x16 zero16() { f32x16 z; for (int i = 0; i < 16; ++i) z[i] = 0.f; return z; }
; #define MFMA32(a, b, c) __builtin_amdgcn_mfma_f32_32x32x16_bf16((a), (b), (c), 0, 0, 0)
; DI void mla_s_softmax(const LAS unsigned char* base, int r, int h, bool is_diag, int lim, const bf16x8 (&qf)[12], f32x16 (&o)[4], float& m_run, float& l_run,
;                       bf16x8 (&pf0)[2], bf16x8 (&pf1)[2]) {
;     f32x16 s0 = zero16(), s1 = zero16();
;     const LAS unsigned char* kp = base + r * MLA_KROW + h * 16;
; #pragma unroll
;     for (int g = 0; g < 3; ++g) {
;         bf16x8 fa[4], fb[4];
; #pragma unroll
;         for (int j = 0; j < 4; ++j) { fa[j] = *(const LAS bf16x8*)(kp + (4 * g + j) * 32); fb[j] = *(const LAS bf16x8*)(kp + 32 * MLA_KROW + (4 * g + j) * 32); }
;         __builtin_amdgcn_sched_barrier(0);
; #pragma unroll
;         for (int j = 0; j < 4; ++j) { s0 = MFMA32(fa[j], qf[4 * g + j], s0); s1 = MFMA32(fb[j], qf[4 * g + j], s1); }
;         __builtin_amdgcn_sched_barrier(0);
;     }
;     if (is_diag) {
; #pragma unroll
;         for (int i = 0; i < 16; ++i) { if (16 * h + i > lim) s0[i] = -1e30f; if (32 + 16 * h + i > lim) s1[i] = -1e30f; }
.Lmla_splain_1:
	ds_read_b128 v[2:5], v0
	ds_read_b128 v[6:9], v0 offset:32
	ds_read_b128 v[10:13], v0 offset:12800
	ds_read_b128 v[186:189], v0 offset:12832
	ds_read_b128 v[190:193], v0 offset:64
	ds_read_b128 v[194:197], v0 offset:96
	ds_read_b128 v[198:201], v0 offset:12864
	ds_read_b128 v[202:205], v0 offset:12896
	ds_read_b128 v[206:209], v0 offset:128
	ds_read_b128 v[210:213], v0 offset:160
	ds_read_b128 v[214:217], v0 offset:12928
	ds_read_b128 v[218:221], v0 offset:12960
	ds_read_b128 v[222:225], v0 offset:192
	ds_read_b128 v[226:229], v0 offset:224
	ds_read_b128 v[230:233], v0 offset:12992
	ds_read_b128 v[234:237], v0 offset:13024
	s_cmp_lg_u32 s33, s88
	s_waitcnt lgkmcnt(8)
	v_mfma_f32_32x32x16_bf16 v[96:111], v[2:5], v[112:115], 0
	v_mfma_f32_32x32x16_bf16 v[80:95], v[10:13], v[112:115], 0
	v_mfma_f32_32x32x16_bf16 v[96:111], v[6:9], v[116:119], v[96:111]
	v_mfma_f32_32x32x16_bf16 v[80:95], v[186:189], v[116:119], v[80:95]
	v_mfma_f32_32x32x16_bf16 v[96:111], v[190:193], v[120:123], v[96:111]
	v_mfma_f32_32x32x16_bf16 v[80:95], v[198:201], v[120:123], v[80:95]
	v_mfma_f32_32x32x16_bf16 v[96:111], v[194:197], v[124:127], v[96:111]
	v_mfma_f32_32x32x16_bf16 v[80:95], v[202:205], v[124:127], v[80:95]
	ds_read_b128 v[2:5], v0 offset:256
	ds_read_b128 v[6:9], v0 offset:288
	ds_read_b128 v[10:13], v0 offset:13056
	ds_read_b128 v[186:189], v0 offset:13088
	ds_read_b128 v[190:193], v0 offset:320
	ds_read_b128 v[194:197], v0 offset:352
	ds_read_b128 v[198:201], v0 offset:13120
	ds_read_b128 v[202:205], v0 offset:13152
	s_waitcnt lgkmcnt(8)
	v_mfma_f32_32x32x16_bf16 v[96:111], v[206:209], v[128:131], v[96:111]
	v_mfma_f32_32x32x16_bf16 v[80:95], v[214:217], v[128:131], v[80:95]
	v_mfma_f32_32x32x16_bf16 v[96:111], v[210:213], v[132:135], v[96:111]
	v_mfma_f32_32x32x16_bf16 v[80:95], v[218:221], v[132:135], v[80:95]
	v_mfma_f32_32x32x16_bf16 v[96:111], v[222:225], v[136:139], v[96:111]
	v_mfma_f32_32x32x16_bf16 v[80:95], v[230:233], v[136:139], v[80:95]
	v_mfma_f32_32x32x16_bf16 v[96:111], v[226:229], v[140:143], v[96:111]
	v_mfma_f32_32x32x16_bf16 v[80:95], v[234:237], v[140:143], v[80:95]
	s_waitcnt lgkmcnt(0)
	v_mfma_f32_32x32x16_bf16 v[96:111], v[2:5], v[144:147], v[96:111]
	v_mfma_f32_32x32x16_bf16 v[80:95], v[10:13], v[144:147], v[80:95]
	v_mfma_f32_32x32x16_bf16 v[96:111], v[6:9], v[148:151], v[96:111]
	v_mfma_f32_32x32x16_bf16 v[80:95], v[186:189], v[148:151], v[80:95]
	v_mfma_f32_32x32x16_bf16 v[96:111], v[190:193], v[152:155], v[96:111]
	v_mfma_f32_32x32x16_bf16 v[80:95], v[198:201], v[152:155], v[80:95]
	v_mfma_f32_32x32x16_bf16 v[96:111], v[194:197], v[156:159], v[96:111]
	v_mfma_f32_32x32x16_bf16 v[80:95], v[202:205], v[156:159], v[80:95]
	s_cbranch_scc1 .LBB0_743
.Lmla_bb640_1:
	s_nop 9
	v_cndmask_b32_e64 v0, v96, v164, s[4:5]
	v_cndmask_b32_e64 v80, v80, v164, s[6:7]
	v_cndmask_b32_e64 v97, v164, v97, s[8:9]
	v_cndmask_b32_e64 v96, v0, v96, s[8:9]
	v_cndmask_b32_e64 v81, v81, v164, s[10:11]
	v_cndmask_b32_e64 v98, v98, v164, s[84:85]
	v_cndmask_b32_e64 v82, v82, v164, s[0:1]
	v_cndmask_b32_e64 v99, v99, v164, s[16:17]
	v_cndmask_b32_e64 v83, v83, v164, s[18:19]
	v_cndmask_b32_e64 v100, v100, v164, s[20:21]
	v_cndmask_b32_e64 v84, v84, v164, s[22:23]
	v_cndmask_b32_e64 v101, v101, v164, s[24:25]
	v_cndmask_b32_e64 v85, v85, v164, s[26:27]
	v_cndmask_b32_e64 v102, v102, v164, s[28:29]
	v_cndmask_b32_e64 v86, v86, v164, s[30:31]
	v_cndmask_b32_e64 v103, v103, v164, s[34:35]
	v_cndmask_b32_e64 v87, v87, v164, s[36:37]
	v_cndmask_b32_e64 v104, v104, v164, s[38:39]
	v_cndmask_b32_e64 v88, v88, v164, s[40:41]
	v_cndmask_b32_e64 v105, v105, v164, s[42:43]
	v_cndmask_b32_e64 v89, v89, v164, s[44:45]
	v_cndmask_b32_e64 v106, v106, v164, s[46:47]
	v_cndmask_b32_e64 v90, v90, v164, s[48:49]
	v_cndmask_b32_e64 v107, v107, v164, s[50:51]
	v_cndmask_b32_e64 v91, v91, v164, s[52:53]
	v_cndmask_b32_e64 v108, v108, v164, s[54:55]
	v_cndmask_b32_e64 v92, v92, v164, s[56:57]
	v_cndmask_b32_e64 v109, v109, v164, s[58:59]
	v_cndmask_b32_e64 v93, v93, v164, s[60:61]
	v_cndmask_b32_e64 v110, v110, v164, s[62:63]
	v_cndmask_b32_e64 v94, v94, v164, s[64:65]
	v_cndmask_b32_e64 v111, v111, v164, s[66:67]
	v_cndmask_b32_e64 v95, v95, v164, s[68:69]

; DI unsigned pk2(float lo, float hi) { f32x2 v = {lo, hi}; bf2_t r = __builtin_convertvector(v, bf2_t); return __builtin_bit_cast(unsigned, r); }
; DI float xhalf_sum(float x) { float lo, hi; xhalf(x, lo, hi); return lo + hi; }
; DI void mla_block(const Params& p, LAS unsigned char* lds, int b, int hd, int qb, int tid) {
;     ...
;     const float lt = xhalf_sum(l_run), inv = 1.f / lt;
;     bf16_t* mix = (bf16_t*)(p.ws + OFF_MIX) + (tok0 + q0 + r) * 1024 + 512 + hd * 128 + 4 * h;
;     float ss = 0.f;
; #pragma unroll
;     for (int dt = 0; dt < 4; ++dt)
; #pragma unroll
;         for (int g = 0; g < 4; ++g) {
;             const float a0 = o[dt][4 * g] * inv, a1 = o[dt][4 * g + 1] * inv, a2 = o[dt][4 * g + 2] * inv, a3 = o[dt][4 * g + 3] * inv;
;             ss += (a0 * a0 + a1 * a1) + (a2 * a2 + a3 * a3);
;             u32x2 w; w.x = pk2(a0, a1); w.y = pk2(a2, a3);
;             *(u32x2*)(mix + dt * 32 + 8 * g) = w;
;         }
.LBB0_755:
	v_mov_b32_e32 v0, v172
	s_nop 1
	v_permlane32_swap_b32_e32 v172, v0
	v_add_f32_e32 v0, v172, v0
	v_div_scale_f32 v2, s[0:1], v0, v0, 1.0
	v_rcp_f32_e32 v3, v2
	s_mov_b64 s[86:87], s[14:15]
	s_mov_b64 s[84:85], s[12:13]
	v_readlane_b32 s12, v255, 43
	v_fma_f32 v4, -v2, v3, 1.0
	v_fmac_f32_e32 v3, v4, v3
	v_div_scale_f32 v4, vcc, 1.0, v0, 1.0
	v_mul_f32_e32 v5, v4, v3
	v_fma_f32 v6, -v2, v5, v4
	v_fmac_f32_e32 v5, v6, v3
	v_fma_f32 v2, -v2, v5, v4
	v_div_fmas_f32 v2, v2, v3, v5
	v_div_fixup_f32 v4, v2, v0, 1.0
	v_lshlrev_b64 v[2:3], 11, v[160:161]
	v_readlane_b32 s13, v255, 44
	v_lshl_add_u64 v[2:3], s[84:85], 0, v[2:3]
	v_lshlrev_b32_e32 v0, 3, v165
	v_lshl_add_u64 v[2:3], v[2:3], 0, s[12:13]
	v_lshl_add_u64 v[6:7], v[2:3], 0, v[0:1]
	s_mov_b64 s[0:1], 0x2a000400
	v_lshl_add_u64 v[2:3], v[6:7], 0, s[0:1]
	v_pk_mul_f32 v[8:9], v[64:65], v[4:5] op_sel_hi:[1,0]
	s_mov_b32 s0, 0x2a000000
	v_pk_mul_f32 v[10:11], v[66:67], v[4:5] op_sel_hi:[1,0]
	v_mul_f32_e32 v0, v9, v9
	v_add_co_u32_e32 v6, vcc, s0, v6
	v_pk_fma_f32 v[12:13], v[8:9], v[8:9], v[0:1] op_sel_hi:[1,1,0]
	v_cvt_pk_bf16_f32 v200, v8, v9
	v_cvt_pk_bf16_f32 v201, v10, v11
	v_addc_co_u32_e32 v7, vcc, 0, v7, vcc
	v_mul_f32_e32 v0, v11, v11
	v_pk_mul_f32 v[6:7], v[68:69], v[4:5] op_sel_hi:[1,0]
	v_pk_fma_f32 v[14:15], v[10:11], v[10:11], v[0:1] op_sel_hi:[1,1,0]
	v_pk_mul_f32 v[8:9], v[70:71], v[4:5] op_sel_hi:[1,0]
	v_mul_f32_e32 v0, v7, v7
	v_pk_fma_f32 v[10:11], v[6:7], v[6:7], v[0:1] op_sel_hi:[1,1,0]
	v_mul_f32_e32 v0, v9, v9
	v_cvt_pk_bf16_f32 v202, v6, v7
	v_cvt_pk_bf16_f32 v203, v8, v9
	v_pk_add_f32 v[12:13], v[12:13], v[14:15]
	v_pk_fma_f32 v[14:15], v[8:9], v[8:9], v[0:1] op_sel_hi:[1,1,0]
	v_pk_mul_f32 v[6:7], v[72:73], v[4:5] op_sel_hi:[1,0]
	v_pk_add_f32 v[10:11], v[10:11], v[14:15]
	v_pk_mul_f32 v[8:9], v[74:75], v[4:5] op_sel_hi:[1,0]
	v_mul_f32_e32 v0, v7, v7
	v_pk_add_f32 v[10:11], v[12:13], v[10:11]
	v_pk_fma_f32 v[12:13], v[6:7], v[6:7], v[0:1] op_sel_hi:[1,1,0]
	v_mul_f32_e32 v0, v9, v9
	v_cvt_pk_bf16_f32 v204, v6, v7
	v_cvt_pk_bf16_f32 v205, v8, v9
	v_pk_fma_f32 v[14:15], v[8:9], v[8:9], v[0:1] op_sel_hi:[1,1,0]
	v_pk_mul_f32 v[6:7], v[76:77], v[4:5] op_sel_hi:[1,0]
	v_pk_add_f32 v[12:13], v[12:13], v[14:15]
	v_pk_mul_f32 v[8:9], v[78:79], v[4:5] op_sel_hi:[1,0]
	v_mul_f32_e32 v0, v7, v7
	v_pk_add_f32 v[10:11], v[12:13], v[10:11]
	v_pk_fma_f32 v[12:13], v[6:7], v[6:7], v[0:1] op_sel_hi:[1,1,0]
	v_mul_f32_e32 v0, v9, v9
	v_cvt_pk_bf16_f32 v206, v6, v7
	v_cvt_pk_bf16_f32 v207, v8, v9
	v_pk_fma_f32 v[14:15], v[8:9], v[8:9], v[0:1] op_sel_hi:[1,1,0]
	v_pk_mul_f32 v[6:7], v[48:49], v[4:5] op_sel_hi:[1,0]
	v_pk_add_f32 v[12:13], v[12:13], v[14:15]
	v_pk_mul_f32 v[8:9], v[50:51], v[4:5] op_sel_hi:[1,0]
	v_mul_f32_e32 v0, v7, v7
	v_pk_add_f32 v[10:11], v[12:13], v[10:11]
	v_pk_fma_f32 v[12:13], v[6:7], v[6:7], v[0:1] op_sel_hi:[1,1,0]
	v_mul_f32_e32 v0, v9, v9
	v_cvt_pk_bf16_f32 v208, v6, v7
	v_cvt_pk_bf16_f32 v209, v8, v9
	v_pk_fma_f32 v[14:15], v[8:9], v[8:9], v[0:1] op_sel_hi:[1,1,0]
	v_pk_mul_f32 v[6:7], v[52:53], v[4:5] op_sel_hi:[1,0]
	v_pk_add_f32 v[12:13], v[12:13], v[14:15]
	v_pk_mul_f32 v[8:9], v[54:55], v[4:5] op_sel_hi:[1,0]
	v_mul_f32_e32 v0, v7, v7
	v_pk_add_f32 v[10:11], v[12:13], v[10:11]
	v_pk_fma_f32 v[12:13], v[6:7], v[6:7], v[0:1] op_sel_hi:[1,1,0]
	v_mul_f32_e32 v0, v9, v9
	v_cvt_pk_bf16_f32 v210, v6, v7
	v_cvt_pk_bf16_f32 v211, v8, v9
	v_pk_fma_f32 v[14:15], v[8:9], v[8:9], v[0:1] op_sel_hi:[1,1,0]
	v_pk_mul_f32 v[6:7], v[56:57], v[4:5] op_sel_hi:[1,0]
	v_pk_add_f32 v[12:13], v[12:13], v[14:15]
	v_pk_mul_f32 v[8:9], v[58:59], v[4:5] op_sel_hi:[1,0]
	v_mul_f32_e32 v0, v7, v7
	v_pk_add_f32 v[10:11], v[12:13], v[10:11]
	v_pk_fma_f32 v[12:13], v[6:7], v[6:7], v[0:1] op_sel_hi:[1,1,0]
	v_mul_f32_e32 v0, v9, v9
	v_cvt_pk_bf16_f32 v212, v6, v7
	v_cvt_pk_bf16_f32 v213, v8, v9
	v_pk_fma_f32 v[14:15], v[8:9], v[8:9], v[0:1] op_sel_hi:[1,1,0]
	v_pk_mul_f32 v[6:7], v[60:61], v[4:5] op_sel_hi:[1,0]
	v_pk_add_f32 v[12:13], v[12:13], v[14:15]
	v_pk_mul_f32 v[8:9], v[62:63], v[4:5] op_sel_hi:[1,0]
	v_mul_f32_e32 v0, v7, v7
	v_pk_add_f32 v[10:11], v[12:13], v[10:11]
	v_pk_fma_f32 v[12:13], v[6:7], v[6:7], v[0:1] op_sel_hi:[1,1,0]
	v_mul_f32_e32 v0, v9, v9
	v_cvt_pk_bf16_f32 v214, v6, v7
	v_cvt_pk_bf16_f32 v215, v8, v9
	v_pk_fma_f32 v[14:15], v[8:9], v[8:9], v[0:1] op_sel_hi:[1,1,0]
	v_pk_mul_f32 v[6:7], v[32:33], v[4:5] op_sel_hi:[1,0]
	v_pk_add_f32 v[12:13], v[12:13], v[14:15]
	v_pk_mul_f32 v[8:9], v[34:35], v[4:5] op_sel_hi:[1,0]
	v_mul_f32_e32 v0, v7, v7
	v_pk_add_f32 v[10:11], v[12:13], v[10:11]
	v_pk_fma_f32 v[12:13], v[6:7], v[6:7], v[0:1] op_sel_hi:[1,1,0]
	v_mul_f32_e32 v0, v9, v9
	v_cvt_pk_bf16_f32 v216, v6, v7
	v_cvt_pk_bf16_f32 v217, v8, v9
	v_pk_fma_f32 v[14:15], v[8:9], v[8:9], v[0:1] op_sel_hi:[1,1,0]
	v_pk_mul_f32 v[6:7], v[36:37], v[4:5] op_sel_hi:[1,0]
	v_pk_add_f32 v[12:13], v[12:13], v[14:15]
	v_pk_mul_f32 v[8:9], v[38:39], v[4:5] op_sel_hi:[1,0]
	v_mul_f32_e32 v0, v7, v7
	v_pk_add_f32 v[10:11], v[12:13], v[10:11]
	v_pk_fma_f32 v[12:13], v[6:7], v[6:7], v[0:1] op_sel_hi:[1,1,0]
	v_mul_f32_e32 v0, v9, v9
	v_cvt_pk_bf16_f32 v218, v6, v7
	v_cvt_pk_bf16_f32 v219, v8, v9
	v_pk_fma_f32 v[14:15], v[8:9], v[8:9], v[0:1] op_sel_hi:[1,1,0]
; DI unsigned pk2(float lo, float hi) { f32x2 v = {lo, hi}; bf2_t r = __builtin_convertvector(v, bf2_t); return __builtin_bit_cast(unsigned, r); }
; DI float xhalf_sum(float x) { float lo, hi; xhalf(x, lo, hi); return lo + hi; }
; DI void mla_block(const Params& p, LAS unsigned char* lds, int b, int hd, int qb, int tid) {
;     ...
; #pragma unroll
;     for (int dt = 0; dt < 4; ++dt)
; #pragma unroll
;         for (int g = 0; g < 4; ++g) {
;             const float a0 = o[dt][4 * g] * inv, a1 = o[dt][4 * g + 1] * inv, a2 = o[dt][4 * g + 2] * inv, a3 = o[dt][4 * g + 3] * inv;
;             ss += (a0 * a0 + a1 * a1) + (a2 * a2 + a3 * a3);
;             u32x2 w; w.x = pk2(a0, a1); w.y = pk2(a2, a3);
;             *(u32x2*)(mix + dt * 32 + 8 * g) = w;
;         }
;     ss = xhalf_sum(ss);
;     if (h == 0) ((float*)(p.ws + OFF_HSS))[(tok0 + q0 + r) * 16 + 8 + hd] = ss;
	v_pk_mul_f32 v[6:7], v[40:41], v[4:5] op_sel_hi:[1,0]
	v_pk_add_f32 v[12:13], v[12:13], v[14:15]
	v_pk_mul_f32 v[8:9], v[42:43], v[4:5] op_sel_hi:[1,0]
	v_mul_f32_e32 v0, v7, v7
	v_pk_add_f32 v[10:11], v[12:13], v[10:11]
	v_pk_fma_f32 v[12:13], v[6:7], v[6:7], v[0:1] op_sel_hi:[1,1,0]
	v_mul_f32_e32 v0, v9, v9
	v_cvt_pk_bf16_f32 v220, v6, v7
	v_cvt_pk_bf16_f32 v221, v8, v9
	v_pk_fma_f32 v[14:15], v[8:9], v[8:9], v[0:1] op_sel_hi:[1,1,0]
	v_pk_mul_f32 v[6:7], v[44:45], v[4:5] op_sel_hi:[1,0]
	v_pk_add_f32 v[12:13], v[12:13], v[14:15]
	v_pk_mul_f32 v[8:9], v[46:47], v[4:5] op_sel_hi:[1,0]
	v_mul_f32_e32 v0, v7, v7
	v_pk_add_f32 v[10:11], v[12:13], v[10:11]
	v_pk_fma_f32 v[12:13], v[6:7], v[6:7], v[0:1] op_sel_hi:[1,1,0]
	v_mul_f32_e32 v0, v9, v9
	v_cvt_pk_bf16_f32 v222, v6, v7
	v_cvt_pk_bf16_f32 v223, v8, v9
	v_pk_fma_f32 v[14:15], v[8:9], v[8:9], v[0:1] op_sel_hi:[1,1,0]
	v_pk_mul_f32 v[6:7], v[16:17], v[4:5] op_sel_hi:[1,0]
	v_pk_add_f32 v[12:13], v[12:13], v[14:15]
	v_pk_mul_f32 v[8:9], v[18:19], v[4:5] op_sel_hi:[1,0]
	v_mul_f32_e32 v0, v7, v7
	v_pk_add_f32 v[10:11], v[12:13], v[10:11]
	v_pk_fma_f32 v[12:13], v[6:7], v[6:7], v[0:1] op_sel_hi:[1,1,0]
	v_mul_f32_e32 v0, v9, v9
	v_cvt_pk_bf16_f32 v224, v6, v7
	v_cvt_pk_bf16_f32 v225, v8, v9
	v_pk_fma_f32 v[14:15], v[8:9], v[8:9], v[0:1] op_sel_hi:[1,1,0]
	v_pk_mul_f32 v[6:7], v[20:21], v[4:5] op_sel_hi:[1,0]
	v_pk_add_f32 v[12:13], v[12:13], v[14:15]
	v_pk_mul_f32 v[8:9], v[22:23], v[4:5] op_sel_hi:[1,0]
	v_mul_f32_e32 v0, v7, v7
	v_pk_add_f32 v[10:11], v[12:13], v[10:11]
	v_pk_fma_f32 v[12:13], v[6:7], v[6:7], v[0:1] op_sel_hi:[1,1,0]
	v_mul_f32_e32 v0, v9, v9
	v_cvt_pk_bf16_f32 v226, v6, v7
	v_cvt_pk_bf16_f32 v227, v8, v9
	v_pk_fma_f32 v[14:15], v[8:9], v[8:9], v[0:1] op_sel_hi:[1,1,0]
	v_pk_mul_f32 v[6:7], v[24:25], v[4:5] op_sel_hi:[1,0]
	v_pk_add_f32 v[12:13], v[12:13], v[14:15]
	v_pk_mul_f32 v[8:9], v[26:27], v[4:5] op_sel_hi:[1,0]
	v_mul_f32_e32 v0, v7, v7
	v_pk_add_f32 v[10:11], v[12:13], v[10:11]
	v_pk_fma_f32 v[12:13], v[6:7], v[6:7], v[0:1] op_sel_hi:[1,1,0]
	v_cvt_pk_bf16_f32 v228, v6, v7
	v_cvt_pk_bf16_f32 v229, v8, v9
	v_mul_f32_e32 v0, v9, v9
	v_pk_mul_f32 v[6:7], v[28:29], v[4:5] op_sel_hi:[1,0]
	v_pk_fma_f32 v[14:15], v[8:9], v[8:9], v[0:1] op_sel_hi:[1,1,0]
	v_pk_mul_f32 v[8:9], v[30:31], v[4:5] op_sel_hi:[1,0]
	v_mul_f32_e32 v0, v7, v7
	v_pk_add_f32 v[12:13], v[12:13], v[14:15]
	v_pk_fma_f32 v[4:5], v[6:7], v[6:7], v[0:1] op_sel_hi:[1,1,0]
	v_mul_f32_e32 v0, v9, v9
	v_pk_add_f32 v[10:11], v[12:13], v[10:11]
	v_pk_fma_f32 v[12:13], v[8:9], v[8:9], v[0:1] op_sel_hi:[1,1,0]
	v_readlane_b32 s68, v255, 15
	v_pk_add_f32 v[4:5], v[4:5], v[12:13]
	v_readlane_b32 s58, v255, 35
	v_pk_add_f32 v[4:5], v[4:5], v[10:11]
	v_readlane_b32 s60, v255, 37
	v_mov_b32_e32 v0, v4
	v_readlane_b32 s80, v255, 27
	v_readlane_b32 s81, v255, 28
	v_readlane_b32 s82, v255, 29
	v_readlane_b32 s83, v255, 30
	v_readlane_b32 s88, v255, 33
	v_readlane_b32 s59, v255, 36
	v_readlane_b32 s61, v255, 38
	s_mov_b32 s16, 0x1e000000
	s_mov_b32 s14, 0x51eb851f
	s_movk_i32 s15, 0xffe7
	v_readlane_b32 s17, v255, 46
	v_cvt_pk_bf16_f32 v230, v6, v7
	v_cvt_pk_bf16_f32 v231, v8, v9
	v_permlane32_swap_b32_e32 v4, v0
	v_cmp_gt_u32_e32 vcc, 32, v163
	v_readlane_b32 s69, v255, 16
	v_readlane_b32 s70, v255, 17
	v_readlane_b32 s71, v255, 18
	v_readlane_b32 s72, v255, 19
	v_readlane_b32 s73, v255, 20
	v_readlane_b32 s74, v255, 21
	v_readlane_b32 s75, v255, 22
	v_readlane_b32 s76, v255, 23
	v_readlane_b32 s77, v255, 24
	v_readlane_b32 s78, v255, 25
	v_readlane_b32 s79, v255, 26
	v_readlane_b32 s89, v255, 34
	v_mbcnt_lo_u32_b32 v252, -1, 0
	v_mbcnt_hi_u32_b32 v252, -1, v252
	v_lshrrev_b32_e32 v252, 5, v252
	v_lshlrev_b32_e32 v252, 3, v252
	v_mov_b32_e32 v253, 0
	v_lshl_add_u64 v[252:253], v[2:3], 0, v[252:253]
	v_permlane32_swap_b32_e32 v200, v202
	v_permlane32_swap_b32_e32 v201, v203
	v_permlane32_swap_b32_e32 v204, v206
	v_permlane32_swap_b32_e32 v205, v207
	v_permlane32_swap_b32_e32 v208, v210
	v_permlane32_swap_b32_e32 v209, v211
	v_permlane32_swap_b32_e32 v212, v214
	v_permlane32_swap_b32_e32 v213, v215
	v_permlane32_swap_b32_e32 v216, v218
	v_permlane32_swap_b32_e32 v217, v219
	v_permlane32_swap_b32_e32 v220, v222
	v_permlane32_swap_b32_e32 v221, v223
	v_permlane32_swap_b32_e32 v224, v226
	v_permlane32_swap_b32_e32 v225, v227
	v_permlane32_swap_b32_e32 v228, v230
	v_permlane32_swap_b32_e32 v229, v231
	global_store_dwordx4 v[252:253], v[200:203], off
	global_store_dwordx4 v[252:253], v[204:207], off offset:32
	global_store_dwordx4 v[252:253], v[208:211], off offset:64
	global_store_dwordx4 v[252:253], v[212:215], off offset:96
	global_store_dwordx4 v[252:253], v[216:219], off offset:128
	global_store_dwordx4 v[252:253], v[220:223], off offset:160
	global_store_dwordx4 v[252:253], v[224:227], off offset:192
	global_store_dwordx4 v[252:253], v[228:231], off offset:224
	s_and_saveexec_b64 s[2:3], vcc
	s_cbranch_execz .LBB0_552
	v_readlane_b32 s0, v255, 31
	v_lshlrev_b64 v[2:3], 6, v[160:161]
	v_readlane_b32 s1, v255, 32
	v_add_f32_e32 v0, v4, v0
	s_nop 0
	v_lshl_add_u64 v[2:3], s[0:1], 0, v[2:3]
	v_readlane_b32 s0, v255, 39
	s_lshl_b32 s12, s0, 2
	v_lshl_add_u64 v[2:3], v[2:3], 0, s[12:13]
	global_store_dword v[2:3], v0, off
	s_branch .LBB0_552

; DI unsigned pk2(float lo, float hi) { f32x2 v = {lo, hi}; bf2_t r = __builtin_convertvector(v, bf2_t); return __builtin_bit_cast(unsigned, r); }
; DI void xhalf(float x, float& lo, float& hi) { const u32x2p r = __builtin_amdgcn_permlane32_swap(__float_as_uint(x), __float_as_uint(x), false, false); lo = __uint_as_float(r.x); hi = __uint_as_float(r.y); }
; #define MFMA32(a, b, c) __builtin_amdgcn_mfma_f32_32x32x16_bf16((a), (b), (c), 0, 0, 0)
; DI void sb_block2(const Params& p, LAS unsigned char* lds, int bh, int qb2, int tid) {
;     ...
;                         if (g == 0 ? act0 : act1) {
;                             const f32x16 z = zz[g];
;                             const bool diag = (kb == q0[g]);
;                             f32x16 a;
;                             float tot = 1.f;
; #pragma unroll
;                             for (int i = 15; i >= 0; --i) {
;                                 const float w = __builtin_amdgcn_exp2f(fminf(z[i], 86.f));
;                                 float be = __builtin_amdgcn_rcpf(1.f + w);
;                                 float om = w * be;
;                                 if (diag) { const bool valid = (16 * h + i < r); be = valid ? be : 0.f; om = valid ? om : 1.f; }
;                                 a[i] = be * tot;
;                                 tot *= om;
;                             }
;                             float tlo, thi; xhalf(tot, tlo, thi);
;                             const float bs = carry[g] * (h == 0 ? thi : 1.f);
;                             carry[g] *= tlo * thi;
; #pragma unroll
;                             for (int i = 0; i < 16; ++i) a[i] *= bs;
;                             bf16x8 pf[2];
; #pragma unroll
;                             for (int s2 = 0; s2 < 2; ++s2) {
;                                 u32x4 w; w.x = pk2(a[8 * s2 + 0], a[8 * s2 + 1]); w.y = pk2(a[8 * s2 + 2], a[8 * s2 + 3]); w.z = pk2(a[8 * s2 + 4], a[8 * s2 + 5]); w.w = pk2(a[8 * s2 + 6], a[8 * s2 + 7]);
;                                 pf[s2] = __builtin_bit_cast(bf16x8, w);
;                             }
; #pragma unroll
;                             for (int s2 = 0; s2 < 2; ++s2) { o0[g] = MFMA32(vf[s2], pf[s2], o0[g]); o1[g] = MFMA32(vf[2 + s2], pf[s2], o1[g]); }
.LBB0_836:
	s_andn2_b64 vcc, exec, s[2:3]
	s_or_b32 s0, s59, 32
	s_cbranch_vccnz .LBB0_839
	s_nop 0
	s_cmp_eq_u32 s0, s56
	s_cbranch_scc0 .Lsb_lean_0
	v_min_f32_e32 v17, 0x42ac0000, v33
	v_exp_f32_e32 v17, v17
	v_min_f32_e32 v32, 0x42ac0000, v32
	v_exp_f32_e32 v32, v32
	v_add_f32_e32 v33, 1.0, v17
	v_rcp_f32_e32 v33, v33
	v_add_f32_e32 v50, 1.0, v32
	v_rcp_f32_e32 v50, v50
	v_min_f32_e32 v31, 0x42ac0000, v31
	v_exp_f32_e32 v31, v31
	s_cmp_eq_u32 s0, s56
	v_cndmask_b32_e64 v51, 0, v33, s[14:15]
	s_cselect_b64 vcc, -1, 0
	v_mul_f32_e32 v17, v17, v33
	v_cndmask_b32_e32 v33, v33, v51, vcc
	v_cndmask_b32_e64 v51, 0, v50, s[16:17]
	v_mul_f32_e32 v32, v32, v50
	v_cndmask_b32_e32 v50, v50, v51, vcc
	v_add_f32_e32 v51, 1.0, v31
	v_rcp_f32_e32 v51, v51
	v_min_f32_e32 v30, 0x42ac0000, v30
	v_exp_f32_e32 v30, v30
	v_cndmask_b32_e64 v52, 1.0, v17, s[14:15]
	v_cndmask_b32_e32 v17, v17, v52, vcc
	v_cndmask_b32_e64 v52, 1.0, v32, s[16:17]
	v_cndmask_b32_e32 v52, v32, v52, vcc
	v_mul_f32_e32 v32, v50, v17
	v_cndmask_b32_e64 v50, 0, v51, s[18:19]
	v_mul_f32_e32 v31, v31, v51
	v_cndmask_b32_e32 v50, v51, v50, vcc
	v_add_f32_e32 v51, 1.0, v30
	v_rcp_f32_e32 v51, v51
	v_min_f32_e32 v29, 0x42ac0000, v29
	v_exp_f32_e32 v29, v29
	v_mul_f32_e32 v17, v17, v52
	v_cndmask_b32_e64 v52, 1.0, v31, s[18:19]
	v_cndmask_b32_e32 v31, v31, v52, vcc
	v_mul_f32_e32 v82, v50, v17
	v_mul_f32_e32 v17, v31, v17
	v_cndmask_b32_e64 v31, 0, v51, s[20:21]
	v_mul_f32_e32 v30, v30, v51
	v_cndmask_b32_e32 v31, v51, v31, vcc
	v_add_f32_e32 v51, 1.0, v29
	v_rcp_f32_e32 v51, v51
	v_min_f32_e32 v28, 0x42ac0000, v28
	v_exp_f32_e32 v28, v28
	v_cndmask_b32_e64 v50, 1.0, v30, s[20:21]
	v_cndmask_b32_e32 v30, v30, v50, vcc
	v_mul_f32_e32 v31, v31, v17
	v_mul_f32_e32 v17, v30, v17
	v_cndmask_b32_e64 v30, 0, v51, s[22:23]
	v_mul_f32_e32 v29, v29, v51
	v_cndmask_b32_e32 v30, v51, v30, vcc
	v_add_f32_e32 v51, 1.0, v28
	v_rcp_f32_e32 v51, v51
	v_min_f32_e32 v27, 0x42ac0000, v27
	v_exp_f32_e32 v27, v27
	v_cndmask_b32_e64 v50, 1.0, v29, s[22:23]
	v_cndmask_b32_e32 v29, v29, v50, vcc
	v_mul_f32_e32 v30, v30, v17
	v_mul_f32_e32 v17, v29, v17
	v_cndmask_b32_e64 v29, 0, v51, s[24:25]
	v_mul_f32_e32 v28, v28, v51
	v_cndmask_b32_e32 v29, v51, v29, vcc
	v_add_f32_e32 v51, 1.0, v27
	v_rcp_f32_e32 v51, v51
	v_min_f32_e32 v26, 0x42ac0000, v26
	v_exp_f32_e32 v26, v26
	v_min_f32_e32 v25, 0x42ac0000, v25
	v_cndmask_b32_e64 v50, 1.0, v28, s[24:25]
	v_mul_f32_e32 v27, v27, v51
	v_exp_f32_e32 v25, v25
	v_cndmask_b32_e32 v28, v28, v50, vcc
	v_cndmask_b32_e64 v50, 1.0, v27, s[26:27]
	v_mul_f32_e32 v29, v29, v17
	v_mul_f32_e32 v17, v28, v17
	v_cndmask_b32_e64 v28, 0, v51, s[26:27]
	v_cndmask_b32_e32 v27, v27, v50, vcc
	v_add_f32_e32 v50, 1.0, v26
	v_cndmask_b32_e32 v28, v51, v28, vcc
	v_rcp_f32_e32 v50, v50
	v_mul_f32_e32 v28, v28, v17
	v_mul_f32_e32 v17, v27, v17
	v_add_f32_e32 v27, 1.0, v25
	v_rcp_f32_e32 v27, v27
	v_min_f32_e32 v24, 0x42ac0000, v24
	v_exp_f32_e32 v24, v24
	v_mul_f32_e32 v26, v26, v50
	v_cndmask_b32_e64 v51, 1.0, v26, s[28:29]
	v_cndmask_b32_e32 v26, v26, v51, vcc
	v_cndmask_b32_e64 v51, 0, v27, s[30:31]
	v_mul_f32_e32 v25, v25, v27
	v_cndmask_b32_e32 v27, v27, v51, vcc
	v_add_f32_e32 v51, 1.0, v24
	v_rcp_f32_e32 v51, v51
	v_min_f32_e32 v23, 0x42ac0000, v23
	v_exp_f32_e32 v23, v23
	v_cndmask_b32_e64 v52, 1.0, v25, s[30:31]
	v_mul_f32_e32 v26, v26, v17
	v_cndmask_b32_e32 v25, v25, v52, vcc
	v_mul_f32_e32 v27, v27, v26
	v_mul_f32_e32 v25, v25, v26
	v_cndmask_b32_e64 v26, 0, v51, s[34:35]
	v_mul_f32_e32 v24, v24, v51
	v_cndmask_b32_e32 v26, v51, v26, vcc
	v_add_f32_e32 v51, 1.0, v23
	v_rcp_f32_e32 v51, v51
	v_min_f32_e32 v22, 0x42ac0000, v22
	v_exp_f32_e32 v22, v22
	v_cndmask_b32_e64 v52, 1.0, v24, s[34:35]
	v_cndmask_b32_e32 v24, v24, v52, vcc
	v_mul_f32_e32 v26, v26, v25
	v_mul_f32_e32 v24, v24, v25
	v_cndmask_b32_e64 v25, 0, v51, s[36:37]
	v_mul_f32_e32 v23, v23, v51
	v_cndmask_b32_e32 v25, v51, v25, vcc
	v_add_f32_e32 v51, 1.0, v22
	v_rcp_f32_e32 v51, v51
	v_min_f32_e32 v21, 0x42ac0000, v21
	v_exp_f32_e32 v21, v21
	v_cndmask_b32_e64 v52, 1.0, v23, s[36:37]
	v_cndmask_b32_e32 v23, v23, v52, vcc
	v_mul_f32_e32 v25, v25, v24
	v_mul_f32_e32 v23, v23, v24
	v_cndmask_b32_e64 v24, 0, v51, s[38:39]
	v_mul_f32_e32 v22, v22, v51
	v_cndmask_b32_e32 v24, v51, v24, vcc
	v_add_f32_e32 v51, 1.0, v21
	v_rcp_f32_e32 v51, v51
	v_min_f32_e32 v20, 0x42ac0000, v20
	v_exp_f32_e32 v20, v20
	v_cndmask_b32_e64 v52, 1.0, v22, s[38:39]
	v_cndmask_b32_e32 v22, v22, v52, vcc
	v_mul_f32_e32 v24, v24, v23
	v_mul_f32_e32 v22, v22, v23
	v_cndmask_b32_e64 v23, 0, v51, s[40:41]
	v_mul_f32_e32 v21, v21, v51
	v_cndmask_b32_e32 v23, v51, v23, vcc
	v_add_f32_e32 v51, 1.0, v20
	v_rcp_f32_e32 v51, v51
	v_min_f32_e32 v19, 0x42ac0000, v19
	v_exp_f32_e32 v19, v19
	v_cndmask_b32_e64 v52, 1.0, v21, s[40:41]
	v_cndmask_b32_e32 v21, v21, v52, vcc
	v_mul_f32_e32 v23, v23, v22
	v_mul_f32_e32 v21, v21, v22
	v_cndmask_b32_e64 v22, 0, v51, s[42:43]
	v_mul_f32_e32 v20, v20, v51
	v_cndmask_b32_e32 v22, v51, v22, vcc
	v_add_f32_e32 v51, 1.0, v19
	v_rcp_f32_e32 v51, v51
	v_min_f32_e32 v18, 0x42ac0000, v18
	v_exp_f32_e32 v18, v18
	v_cndmask_b32_e64 v52, 1.0, v20, s[42:43]
	v_cndmask_b32_e32 v20, v20, v52, vcc
	v_mul_f32_e32 v52, v22, v21
	v_mul_f32_e32 v20, v20, v21
	v_cndmask_b32_e64 v21, 0, v51, s[44:45]
	v_mul_f32_e32 v19, v19, v51
	v_cndmask_b32_e32 v21, v51, v21, vcc
	v_add_f32_e32 v51, 1.0, v18
	v_rcp_f32_e32 v51, v51
	v_cndmask_b32_e64 v22, 1.0, v19, s[44:45]
	v_cndmask_b32_e32 v19, v19, v22, vcc
	v_mul_f32_e32 v19, v19, v20
	v_mul_f32_e32 v18, v18, v51
	v_cndmask_b32_e64 v22, 1.0, v18, s[46:47]
	v_cndmask_b32_e32 v18, v18, v22, vcc
	v_mul_f32_e32 v83, v18, v19
	v_mul_f32_e32 v21, v21, v20
	v_cndmask_b32_e64 v20, 0, v51, s[46:47]
	v_mov_b32_e32 v84, v83
	v_cndmask_b32_e32 v20, v51, v20, vcc
	s_nop 0
	v_permlane32_swap_b32_e32 v83, v84
	v_mul_f32_e32 v20, v20, v19
	v_cndmask_b32_e64 v22, 1.0, v84, s[10:11]
	v_mul_f32_e32 v18, v20, v22
	v_mul_f32_e32 v19, v21, v22
	v_mul_f32_e32 v20, v52, v22
	v_mul_f32_e32 v21, v23, v22
	v_mul_f32_e32 v23, v24, v22
	v_mul_f32_e32 v24, v25, v22
	v_mul_f32_e32 v25, v26, v22
	v_mul_f32_e32 v26, v27, v22
	v_cvt_pk_bf16_f32 v18, v18, v19
	v_cvt_pk_bf16_f32 v19, v20, v21
	v_cvt_pk_bf16_f32 v20, v23, v24
	v_cvt_pk_bf16_f32 v21, v25, v26
	v_cndmask_b32_e64 v23, 0, v50, s[28:29]
	v_cndmask_b32_e32 v23, v50, v23, vcc
	v_mfma_f32_32x32x16_bf16 v[66:81], v[46:49], v[18:21], 0
	v_mul_f32_e32 v17, v23, v17
	v_mul_f32_e32 v17, v17, v22
	v_mul_f32_e32 v24, v28, v22
	v_mul_f32_e32 v25, v29, v22
	v_mul_f32_e32 v26, v30, v22
	v_mul_f32_e32 v190, v83, v84
	s_branch .Lsb_join_0
; DI unsigned pk2(float lo, float hi) { f32x2 v = {lo, hi}; bf2_t r = __builtin_convertvector(v, bf2_t); return __builtin_bit_cast(unsigned, r); }
; DI void xhalf(float x, float& lo, float& hi) { const u32x2p r = __builtin_amdgcn_permlane32_swap(__float_as_uint(x), __float_as_uint(x), false, false); lo = __uint_as_float(r.x); hi = __uint_as_float(r.y); }
; #define MFMA32(a, b, c) __builtin_amdgcn_mfma_f32_32x32x16_bf16((a), (b), (c), 0, 0, 0)
; DI void sb_block2(const Params& p, LAS unsigned char* lds, int bh, int qb2, int tid) {
;     ...
;                         if (g == 0 ? act0 : act1) {
;                             const f32x16 z = zz[g];
;                             const bool diag = (kb == q0[g]);
;                             f32x16 a;
;                             float tot = 1.f;
; #pragma unroll
;                             for (int i = 15; i >= 0; --i) {
;                                 const float w = __builtin_amdgcn_exp2f(fminf(z[i], 86.f));
;                                 float be = __builtin_amdgcn_rcpf(1.f + w);
;                                 float om = w * be;
;                                 if (diag) { const bool valid = (16 * h + i < r); be = valid ? be : 0.f; om = valid ? om : 1.f; }
;                                 a[i] = be * tot;
;                                 tot *= om;
;                             }
;                             float tlo, thi; xhalf(tot, tlo, thi);
;                             const float bs = carry[g] * (h == 0 ? thi : 1.f);
;                             carry[g] *= tlo * thi;
; #pragma unroll
;                             for (int i = 0; i < 16; ++i) a[i] *= bs;
;                             bf16x8 pf[2];
; #pragma unroll
;                             for (int s2 = 0; s2 < 2; ++s2) {
;                                 u32x4 w; w.x = pk2(a[8 * s2 + 0], a[8 * s2 + 1]); w.y = pk2(a[8 * s2 + 2], a[8 * s2 + 3]); w.z = pk2(a[8 * s2 + 4], a[8 * s2 + 5]); w.w = pk2(a[8 * s2 + 6], a[8 * s2 + 7]);
;                                 pf[s2] = __builtin_bit_cast(bf16x8, w);
;                             }
; #pragma unroll
;                             for (int s2 = 0; s2 < 2; ++s2) { o0[g] = MFMA32(vf[s2], pf[s2], o0[g]); o1[g] = MFMA32(vf[2 + s2], pf[s2], o1[g]); }
;                             if (__all(carry[g] < SB_PTHR)) done[g] = true;
;                         }
.Lsb_lean_0:
	v_min_f32_e32 v17, 0x42ac0000, v33
	v_exp_f32_e32 v17, v17
	v_min_f32_e32 v32, 0x42ac0000, v32
	v_exp_f32_e32 v32, v32
	v_add_f32_e32 v33, 1.0, v17
	v_rcp_f32_e32 v33, v33
	v_add_f32_e32 v50, 1.0, v32
	v_rcp_f32_e32 v50, v50
	v_min_f32_e32 v31, 0x42ac0000, v31
	v_exp_f32_e32 v31, v31
	v_mul_f32_e32 v17, v17, v33
	v_mul_f32_e32 v32, v32, v50
	v_add_f32_e32 v51, 1.0, v31
	v_rcp_f32_e32 v51, v51
	v_min_f32_e32 v30, 0x42ac0000, v30
	v_exp_f32_e32 v30, v30
	v_mov_b32_e32 v52, v32
	v_mul_f32_e32 v32, v50, v17
	v_mul_f32_e32 v31, v31, v51
	v_mov_b32_e32 v50, v51
	v_add_f32_e32 v51, 1.0, v30
	v_rcp_f32_e32 v51, v51
	v_min_f32_e32 v29, 0x42ac0000, v29
	v_exp_f32_e32 v29, v29
	v_mul_f32_e32 v17, v17, v52
	v_mul_f32_e32 v82, v50, v17
	v_mul_f32_e32 v17, v31, v17
	v_mul_f32_e32 v30, v30, v51
	v_mov_b32_e32 v31, v51
	v_add_f32_e32 v51, 1.0, v29
	v_rcp_f32_e32 v51, v51
	v_min_f32_e32 v28, 0x42ac0000, v28
	v_exp_f32_e32 v28, v28
	v_mul_f32_e32 v31, v31, v17
	v_mul_f32_e32 v17, v30, v17
	v_mul_f32_e32 v29, v29, v51
	v_mov_b32_e32 v30, v51
	v_add_f32_e32 v51, 1.0, v28
	v_rcp_f32_e32 v51, v51
	v_min_f32_e32 v27, 0x42ac0000, v27
	v_exp_f32_e32 v27, v27
	v_mul_f32_e32 v30, v30, v17
	v_mul_f32_e32 v17, v29, v17
	v_mul_f32_e32 v28, v28, v51
	v_mov_b32_e32 v29, v51
	v_add_f32_e32 v51, 1.0, v27
	v_rcp_f32_e32 v51, v51
	v_min_f32_e32 v26, 0x42ac0000, v26
	v_exp_f32_e32 v26, v26
	v_min_f32_e32 v25, 0x42ac0000, v25
	v_mul_f32_e32 v27, v27, v51
	v_exp_f32_e32 v25, v25
	v_mul_f32_e32 v29, v29, v17
	v_mul_f32_e32 v17, v28, v17
	v_add_f32_e32 v50, 1.0, v26
	v_mov_b32_e32 v28, v51
	v_rcp_f32_e32 v50, v50
	v_mul_f32_e32 v28, v28, v17
	v_mul_f32_e32 v17, v27, v17
	v_add_f32_e32 v27, 1.0, v25
	v_rcp_f32_e32 v27, v27
	v_min_f32_e32 v24, 0x42ac0000, v24
	v_exp_f32_e32 v24, v24
	v_mul_f32_e32 v26, v26, v50
	v_mul_f32_e32 v25, v25, v27
	v_add_f32_e32 v51, 1.0, v24
	v_rcp_f32_e32 v51, v51
	v_min_f32_e32 v23, 0x42ac0000, v23
	v_exp_f32_e32 v23, v23
	v_mul_f32_e32 v26, v26, v17
	v_mul_f32_e32 v27, v27, v26
	v_mul_f32_e32 v25, v25, v26
	v_mul_f32_e32 v24, v24, v51
	v_mov_b32_e32 v26, v51
	v_add_f32_e32 v51, 1.0, v23
	v_rcp_f32_e32 v51, v51
	v_min_f32_e32 v22, 0x42ac0000, v22
	v_exp_f32_e32 v22, v22
	v_mul_f32_e32 v26, v26, v25
	v_mul_f32_e32 v24, v24, v25
	v_mul_f32_e32 v23, v23, v51
	v_mov_b32_e32 v25, v51
	v_add_f32_e32 v51, 1.0, v22
	v_rcp_f32_e32 v51, v51
	v_min_f32_e32 v21, 0x42ac0000, v21
	v_exp_f32_e32 v21, v21
	v_mul_f32_e32 v25, v25, v24
	v_mul_f32_e32 v23, v23, v24
	v_mul_f32_e32 v22, v22, v51
	v_mov_b32_e32 v24, v51
	v_add_f32_e32 v51, 1.0, v21
	v_rcp_f32_e32 v51, v51
	v_min_f32_e32 v20, 0x42ac0000, v20
	v_exp_f32_e32 v20, v20
	v_mul_f32_e32 v24, v24, v23
	v_mul_f32_e32 v22, v22, v23
	v_mul_f32_e32 v21, v21, v51
	v_mov_b32_e32 v23, v51
	v_add_f32_e32 v51, 1.0, v20
	v_rcp_f32_e32 v51, v51
	v_min_f32_e32 v19, 0x42ac0000, v19
	v_exp_f32_e32 v19, v19
	v_mul_f32_e32 v23, v23, v22
	v_mul_f32_e32 v21, v21, v22
	v_mul_f32_e32 v20, v20, v51
	v_mov_b32_e32 v22, v51
	v_add_f32_e32 v51, 1.0, v19
	v_rcp_f32_e32 v51, v51
	v_min_f32_e32 v18, 0x42ac0000, v18
	v_exp_f32_e32 v18, v18
	v_mul_f32_e32 v52, v22, v21
	v_mul_f32_e32 v20, v20, v21
	v_mul_f32_e32 v19, v19, v51
	v_mov_b32_e32 v21, v51
	v_add_f32_e32 v51, 1.0, v18
	v_rcp_f32_e32 v51, v51
	v_mul_f32_e32 v19, v19, v20
	v_mul_f32_e32 v18, v18, v51
	v_mul_f32_e32 v83, v18, v19
	v_mul_f32_e32 v21, v21, v20
	v_mov_b32_e32 v84, v83
	v_mov_b32_e32 v20, v51
	s_nop 0
	v_permlane32_swap_b32_e32 v83, v84
	v_mul_f32_e32 v20, v20, v19
	v_cndmask_b32_e64 v22, 1.0, v84, s[10:11]
	v_mul_f32_e32 v18, v20, v22
	v_mul_f32_e32 v19, v21, v22
	v_mul_f32_e32 v20, v52, v22
	v_mul_f32_e32 v21, v23, v22
	v_mul_f32_e32 v23, v24, v22
	v_mul_f32_e32 v24, v25, v22
	v_mul_f32_e32 v25, v26, v22
	v_mul_f32_e32 v26, v27, v22
	v_cvt_pk_bf16_f32 v18, v18, v19
	v_cvt_pk_bf16_f32 v19, v20, v21
	v_cvt_pk_bf16_f32 v20, v23, v24
	v_cvt_pk_bf16_f32 v21, v25, v26
	v_mov_b32_e32 v23, v50
	s_nop 0
	v_mfma_f32_32x32x16_bf16 v[66:81], v[46:49], v[18:21], 0
	v_mul_f32_e32 v17, v23, v17
	v_mul_f32_e32 v17, v17, v22
	v_mul_f32_e32 v24, v28, v22
	v_mul_f32_e32 v25, v29, v22
	v_mul_f32_e32 v26, v30, v22
	v_mul_f32_e32 v190, v83, v84
.Lsb_join_0:
	v_cmp_gt_f32_e32 vcc, s68, v190
	v_mfma_f32_32x32x16_bf16 v[50:65], v[42:45], v[18:21], 0
	v_mul_f32_e32 v20, v31, v22
	v_mul_f32_e32 v21, v82, v22
	v_pk_mul_f32 v[22:23], v[32:33], v[22:23] op_sel_hi:[1,0]
	v_cvt_pk_bf16_f32 v18, v17, v24
	v_cvt_pk_bf16_f32 v19, v25, v26
	v_cvt_pk_bf16_f32 v20, v20, v21
	v_cvt_pk_bf16_f32 v21, v22, v23
	s_cmp_eq_u64 vcc, exec
	s_cselect_b64 s[62:63], -1, 0
	v_mfma_f32_32x32x16_bf16 v[66:81], v[38:41], v[18:21], v[66:81]
	v_mfma_f32_32x32x16_bf16 v[50:65], v[34:37], v[18:21], v[50:65]
	s_branch .LBB0_840

; DI unsigned pk2(float lo, float hi) { f32x2 v = {lo, hi}; bf2_t r = __builtin_convertvector(v, bf2_t); return __builtin_bit_cast(unsigned, r); }
; DI void xhalf(float x, float& lo, float& hi) { const u32x2p r = __builtin_amdgcn_permlane32_swap(__float_as_uint(x), __float_as_uint(x), false, false); lo = __uint_as_float(r.x); hi = __uint_as_float(r.y); }
; #define MFMA32(a, b, c) __builtin_amdgcn_mfma_f32_32x32x16_bf16((a), (b), (c), 0, 0, 0)
; DI void sb_block2(const Params& p, LAS unsigned char* lds, int bh, int qb2, int tid) {
;     ...
;                         if (g == 0 ? act0 : act1) {
;                             const f32x16 z = zz[g];
;                             const bool diag = (kb == q0[g]);
;                             f32x16 a;
;                             float tot = 1.f;
; #pragma unroll
;                             for (int i = 15; i >= 0; --i) {
;                                 const float w = __builtin_amdgcn_exp2f(fminf(z[i], 86.f));
;                                 float be = __builtin_amdgcn_rcpf(1.f + w);
;                                 float om = w * be;
;                                 if (diag) { const bool valid = (16 * h + i < r); be = valid ? be : 0.f; om = valid ? om : 1.f; }
;                                 a[i] = be * tot;
;                                 tot *= om;
;                             }
;                             float tlo, thi; xhalf(tot, tlo, thi);
;                             const float bs = carry[g] * (h == 0 ? thi : 1.f);
;                             carry[g] *= tlo * thi;
; #pragma unroll
;                             for (int i = 0; i < 16; ++i) a[i] *= bs;
;                             bf16x8 pf[2];
; #pragma unroll
;                             for (int s2 = 0; s2 < 2; ++s2) {
;                                 u32x4 w; w.x = pk2(a[8 * s2 + 0], a[8 * s2 + 1]); w.y = pk2(a[8 * s2 + 2], a[8 * s2 + 3]); w.z = pk2(a[8 * s2 + 4], a[8 * s2 + 5]); w.w = pk2(a[8 * s2 + 6], a[8 * s2 + 7]);
;                                 pf[s2] = __builtin_bit_cast(bf16x8, w);
;                             }
; #pragma unroll
;                             for (int s2 = 0; s2 < 2; ++s2) { o0[g] = MFMA32(vf[s2], pf[s2], o0[g]); o1[g] = MFMA32(vf[2 + s2], pf[s2], o1[g]); }
.LBB0_840:
	s_cmp_eq_u32 s0, s58
	s_cbranch_scc0 .Lsb_lean_1
	v_min_f32_e32 v15, 0x42ac0000, v15
	v_exp_f32_e32 v15, v15
	v_min_f32_e32 v14, 0x42ac0000, v14
	v_exp_f32_e32 v14, v14
	v_add_f32_e32 v17, 1.0, v15
	v_rcp_f32_e32 v17, v17
	v_add_f32_e32 v18, 1.0, v14
	v_rcp_f32_e32 v18, v18
	v_min_f32_e32 v13, 0x42ac0000, v13
	v_exp_f32_e32 v13, v13
	s_cmp_eq_u32 s0, s58
	v_mul_f32_e32 v19, v15, v17
	v_cndmask_b32_e64 v15, 0, v17, s[14:15]
	v_cndmask_b32_e64 v20, 1.0, v19, s[14:15]
	s_cselect_b64 vcc, -1, 0
	v_cndmask_b32_e32 v15, v17, v15, vcc
	v_cndmask_b32_e32 v17, v19, v20, vcc
	v_cndmask_b32_e64 v19, 0, v18, s[16:17]
	v_mul_f32_e32 v14, v14, v18
	v_cndmask_b32_e32 v18, v18, v19, vcc
	v_add_f32_e32 v19, 1.0, v13
	v_rcp_f32_e32 v19, v19
	v_min_f32_e32 v12, 0x42ac0000, v12
	v_exp_f32_e32 v12, v12
	v_cndmask_b32_e64 v20, 1.0, v14, s[16:17]
	v_cndmask_b32_e32 v20, v14, v20, vcc
	v_mul_f32_e32 v14, v18, v17
	v_cndmask_b32_e64 v18, 0, v19, s[18:19]
	v_mul_f32_e32 v13, v13, v19
	v_cndmask_b32_e32 v18, v19, v18, vcc
	v_add_f32_e32 v19, 1.0, v12
	v_rcp_f32_e32 v19, v19
	v_min_f32_e32 v11, 0x42ac0000, v11
	v_exp_f32_e32 v11, v11
	v_mul_f32_e32 v17, v17, v20
	v_cndmask_b32_e64 v20, 1.0, v13, s[18:19]
	v_cndmask_b32_e32 v13, v13, v20, vcc
	v_mul_f32_e32 v18, v18, v17
	v_mul_f32_e32 v13, v13, v17
	v_cndmask_b32_e64 v17, 0, v19, s[20:21]
	v_mul_f32_e32 v12, v12, v19
	v_cndmask_b32_e32 v17, v19, v17, vcc
	v_add_f32_e32 v19, 1.0, v11
	v_rcp_f32_e32 v19, v19
	v_min_f32_e32 v10, 0x42ac0000, v10
	v_exp_f32_e32 v10, v10
	v_cndmask_b32_e64 v20, 1.0, v12, s[20:21]
	v_cndmask_b32_e32 v12, v12, v20, vcc
	v_mul_f32_e32 v17, v17, v13
	v_mul_f32_e32 v12, v12, v13
	v_cndmask_b32_e64 v13, 0, v19, s[22:23]
	v_mul_f32_e32 v11, v11, v19
	v_cndmask_b32_e32 v13, v19, v13, vcc
	v_add_f32_e32 v19, 1.0, v10
	v_rcp_f32_e32 v19, v19
	v_min_f32_e32 v9, 0x42ac0000, v9
	v_exp_f32_e32 v9, v9
	v_cndmask_b32_e64 v20, 1.0, v11, s[22:23]
	v_cndmask_b32_e32 v11, v11, v20, vcc
	v_mul_f32_e32 v13, v13, v12
	v_mul_f32_e32 v11, v11, v12
	v_cndmask_b32_e64 v12, 0, v19, s[24:25]
	v_mul_f32_e32 v10, v10, v19
	v_cndmask_b32_e32 v12, v19, v12, vcc
	v_add_f32_e32 v19, 1.0, v9
	v_rcp_f32_e32 v19, v19
	v_min_f32_e32 v8, 0x42ac0000, v8
	v_exp_f32_e32 v8, v8
	v_cndmask_b32_e64 v20, 1.0, v10, s[24:25]
	v_min_f32_e32 v7, 0x42ac0000, v7
	v_cndmask_b32_e32 v10, v10, v20, vcc
	v_exp_f32_e32 v7, v7
	v_mul_f32_e32 v12, v12, v11
	v_mul_f32_e32 v10, v10, v11
	v_mul_f32_e32 v9, v9, v19
	v_cndmask_b32_e64 v11, 0, v19, s[26:27]
	v_cndmask_b32_e64 v20, 1.0, v9, s[26:27]
	v_cndmask_b32_e32 v11, v19, v11, vcc
	v_add_f32_e32 v19, 1.0, v8
	v_cndmask_b32_e32 v9, v9, v20, vcc
	v_rcp_f32_e32 v19, v19
	v_mul_f32_e32 v11, v11, v10
	v_mul_f32_e32 v9, v9, v10
	v_add_f32_e32 v10, 1.0, v7
	v_rcp_f32_e32 v10, v10
	v_min_f32_e32 v6, 0x42ac0000, v6
	v_exp_f32_e32 v6, v6
	v_mul_f32_e32 v8, v8, v19
	v_cndmask_b32_e64 v20, 1.0, v8, s[28:29]
	v_cndmask_b32_e32 v8, v8, v20, vcc
	v_cndmask_b32_e64 v20, 0, v10, s[30:31]
	v_mul_f32_e32 v7, v7, v10
	v_cndmask_b32_e32 v10, v10, v20, vcc
	v_add_f32_e32 v20, 1.0, v6
	v_rcp_f32_e32 v20, v20
	v_min_f32_e32 v5, 0x42ac0000, v5
	v_exp_f32_e32 v5, v5
	v_cndmask_b32_e64 v21, 1.0, v7, s[30:31]
	v_mul_f32_e32 v8, v8, v9
	v_cndmask_b32_e32 v7, v7, v21, vcc
	v_mul_f32_e32 v10, v10, v8
	v_mul_f32_e32 v7, v7, v8
	v_cndmask_b32_e64 v8, 0, v20, s[34:35]
	v_mul_f32_e32 v6, v6, v20
	v_cndmask_b32_e32 v8, v20, v8, vcc
	v_add_f32_e32 v20, 1.0, v5
	v_rcp_f32_e32 v20, v20
	v_min_f32_e32 v4, 0x42ac0000, v4
	v_exp_f32_e32 v4, v4
	v_cndmask_b32_e64 v21, 1.0, v6, s[34:35]
	v_cndmask_b32_e32 v6, v6, v21, vcc
	v_mul_f32_e32 v8, v8, v7
	v_mul_f32_e32 v6, v6, v7
	v_cndmask_b32_e64 v7, 0, v20, s[36:37]
	v_mul_f32_e32 v5, v5, v20
	v_cndmask_b32_e32 v7, v20, v7, vcc
	v_add_f32_e32 v20, 1.0, v4
	v_rcp_f32_e32 v20, v20
	v_min_f32_e32 v3, 0x42ac0000, v3
	v_exp_f32_e32 v3, v3
	v_cndmask_b32_e64 v21, 1.0, v5, s[36:37]
	v_cndmask_b32_e32 v5, v5, v21, vcc
	v_mul_f32_e32 v7, v7, v6
	v_mul_f32_e32 v5, v5, v6
	v_cndmask_b32_e64 v6, 0, v20, s[38:39]
	v_mul_f32_e32 v4, v4, v20
	v_cndmask_b32_e32 v6, v20, v6, vcc
	v_add_f32_e32 v20, 1.0, v3
	v_rcp_f32_e32 v20, v20
	v_min_f32_e32 v2, 0x42ac0000, v2
	v_exp_f32_e32 v2, v2
	v_cndmask_b32_e64 v21, 1.0, v4, s[38:39]
	v_cndmask_b32_e32 v4, v4, v21, vcc
	v_mul_f32_e32 v6, v6, v5
	v_mul_f32_e32 v4, v4, v5
	v_cndmask_b32_e64 v5, 0, v20, s[40:41]
	v_mul_f32_e32 v3, v3, v20
	v_cndmask_b32_e32 v5, v20, v5, vcc
	v_add_f32_e32 v20, 1.0, v2
	v_rcp_f32_e32 v20, v20
	v_min_f32_e32 v1, 0x42ac0000, v1
	v_exp_f32_e32 v1, v1
	v_cndmask_b32_e64 v21, 1.0, v3, s[40:41]
	v_cndmask_b32_e32 v3, v3, v21, vcc
	v_mul_f32_e32 v5, v5, v4
	v_mul_f32_e32 v3, v3, v4
	v_cndmask_b32_e64 v4, 0, v20, s[42:43]
	v_mul_f32_e32 v2, v2, v20
	v_cndmask_b32_e32 v4, v20, v4, vcc
	v_add_f32_e32 v20, 1.0, v1
	v_rcp_f32_e32 v20, v20
	v_min_f32_e32 v0, 0x42ac0000, v0
	v_exp_f32_e32 v0, v0
	v_cndmask_b32_e64 v21, 1.0, v2, s[42:43]
	v_cndmask_b32_e32 v2, v2, v21, vcc
	v_mul_f32_e32 v21, v4, v3
	v_mul_f32_e32 v2, v2, v3
	v_cndmask_b32_e64 v3, 0, v20, s[44:45]
	v_mul_f32_e32 v1, v1, v20
	v_cndmask_b32_e32 v3, v20, v3, vcc
	v_add_f32_e32 v20, 1.0, v0
	v_rcp_f32_e32 v20, v20
	v_cndmask_b32_e64 v4, 1.0, v1, s[44:45]
	v_cndmask_b32_e32 v1, v1, v4, vcc
	v_mul_f32_e32 v3, v3, v2
	v_mul_f32_e32 v0, v0, v20
	v_cndmask_b32_e64 v4, 1.0, v0, s[46:47]
	v_mul_f32_e32 v1, v1, v2
	v_cndmask_b32_e64 v2, 0, v20, s[46:47]
	v_cndmask_b32_e32 v0, v0, v4, vcc
	v_cndmask_b32_e32 v2, v20, v2, vcc
	v_mul_f32_e32 v20, v0, v1
	v_mov_b32_e32 v22, v20
	s_nop 1
	s_nop 0
	v_permlane32_swap_b32_e32 v20, v22
	v_mul_f32_e32 v2, v2, v1
	v_cndmask_b32_e64 v4, 1.0, v22, s[10:11]
	v_mul_f32_e32 v0, v2, v4
	v_mul_f32_e32 v1, v3, v4
	v_mul_f32_e32 v2, v21, v4
	v_mul_f32_e32 v3, v5, v4
	v_mul_f32_e32 v5, v6, v4
	v_mul_f32_e32 v6, v7, v4
	v_mul_f32_e32 v7, v8, v4
	v_mul_f32_e32 v8, v10, v4
	v_cvt_pk_bf16_f32 v0, v0, v1
	v_cvt_pk_bf16_f32 v1, v2, v3
	v_cvt_pk_bf16_f32 v2, v5, v6
	v_cvt_pk_bf16_f32 v3, v7, v8
	v_cndmask_b32_e64 v5, 0, v19, s[28:29]
	v_cndmask_b32_e32 v5, v19, v5, vcc
	v_mfma_f32_32x32x16_bf16 v[98:113], v[46:49], v[0:3], 0
	v_mul_f32_e32 v5, v5, v9
	v_mul_f32_e32 v6, v5, v4
	v_mul_f32_e32 v7, v11, v4
	v_mul_f32_e32 v8, v12, v4
	v_mul_f32_e32 v9, v13, v4
	v_mul_f32_e32 v191, v20, v22
	s_branch .Lsb_join_1
; DI unsigned pk2(float lo, float hi) { f32x2 v = {lo, hi}; bf2_t r = __builtin_convertvector(v, bf2_t); return __builtin_bit_cast(unsigned, r); }
; DI void xhalf(float x, float& lo, float& hi) { const u32x2p r = __builtin_amdgcn_permlane32_swap(__float_as_uint(x), __float_as_uint(x), false, false); lo = __uint_as_float(r.x); hi = __uint_as_float(r.y); }
; #define MFMA32(a, b, c) __builtin_amdgcn_mfma_f32_32x32x16_bf16((a), (b), (c), 0, 0, 0)
; DI void sb_block2(const Params& p, LAS unsigned char* lds, int bh, int qb2, int tid) {
;     ...
;                         if (g == 0 ? act0 : act1) {
;                             const f32x16 z = zz[g];
;                             const bool diag = (kb == q0[g]);
;                             f32x16 a;
;                             float tot = 1.f;
; #pragma unroll
;                             for (int i = 15; i >= 0; --i) {
;                                 const float w = __builtin_amdgcn_exp2f(fminf(z[i], 86.f));
;                                 float be = __builtin_amdgcn_rcpf(1.f + w);
;                                 float om = w * be;
;                                 if (diag) { const bool valid = (16 * h + i < r); be = valid ? be : 0.f; om = valid ? om : 1.f; }
;                                 a[i] = be * tot;
;                                 tot *= om;
;                             }
;                             float tlo, thi; xhalf(tot, tlo, thi);
;                             const float bs = carry[g] * (h == 0 ? thi : 1.f);
;                             carry[g] *= tlo * thi;
; #pragma unroll
;                             for (int i = 0; i < 16; ++i) a[i] *= bs;
;                             bf16x8 pf[2];
; #pragma unroll
;                             for (int s2 = 0; s2 < 2; ++s2) {
;                                 u32x4 w; w.x = pk2(a[8 * s2 + 0], a[8 * s2 + 1]); w.y = pk2(a[8 * s2 + 2], a[8 * s2 + 3]); w.z = pk2(a[8 * s2 + 4], a[8 * s2 + 5]); w.w = pk2(a[8 * s2 + 6], a[8 * s2 + 7]);
;                                 pf[s2] = __builtin_bit_cast(bf16x8, w);
;                             }
; #pragma unroll
;                             for (int s2 = 0; s2 < 2; ++s2) { o0[g] = MFMA32(vf[s2], pf[s2], o0[g]); o1[g] = MFMA32(vf[2 + s2], pf[s2], o1[g]); }
;                             if (__all(carry[g] < SB_PTHR)) done[g] = true;
;                         }
.Lsb_lean_1:
	v_min_f32_e32 v15, 0x42ac0000, v15
	v_exp_f32_e32 v15, v15
	v_min_f32_e32 v14, 0x42ac0000, v14
	v_exp_f32_e32 v14, v14
	v_add_f32_e32 v17, 1.0, v15
	v_rcp_f32_e32 v17, v17
	v_add_f32_e32 v18, 1.0, v14
	v_rcp_f32_e32 v18, v18
	v_min_f32_e32 v13, 0x42ac0000, v13
	v_exp_f32_e32 v13, v13
	v_mul_f32_e32 v19, v15, v17
	v_mov_b32_e32 v15, v17
	v_mov_b32_e32 v17, v19
	v_mul_f32_e32 v14, v14, v18
	v_add_f32_e32 v19, 1.0, v13
	v_rcp_f32_e32 v19, v19
	v_min_f32_e32 v12, 0x42ac0000, v12
	v_exp_f32_e32 v12, v12
	v_mov_b32_e32 v20, v14
	v_mul_f32_e32 v14, v18, v17
	v_mul_f32_e32 v13, v13, v19
	v_mov_b32_e32 v18, v19
	v_add_f32_e32 v19, 1.0, v12
	v_rcp_f32_e32 v19, v19
	v_min_f32_e32 v11, 0x42ac0000, v11
	v_exp_f32_e32 v11, v11
	v_mul_f32_e32 v17, v17, v20
	v_mul_f32_e32 v18, v18, v17
	v_mul_f32_e32 v13, v13, v17
	v_mul_f32_e32 v12, v12, v19
	v_mov_b32_e32 v17, v19
	v_add_f32_e32 v19, 1.0, v11
	v_rcp_f32_e32 v19, v19
	v_min_f32_e32 v10, 0x42ac0000, v10
	v_exp_f32_e32 v10, v10
	v_mul_f32_e32 v17, v17, v13
	v_mul_f32_e32 v12, v12, v13
	v_mul_f32_e32 v11, v11, v19
	v_mov_b32_e32 v13, v19
	v_add_f32_e32 v19, 1.0, v10
	v_rcp_f32_e32 v19, v19
	v_min_f32_e32 v9, 0x42ac0000, v9
	v_exp_f32_e32 v9, v9
	v_mul_f32_e32 v13, v13, v12
	v_mul_f32_e32 v11, v11, v12
	v_mul_f32_e32 v10, v10, v19
	v_mov_b32_e32 v12, v19
	v_add_f32_e32 v19, 1.0, v9
	v_rcp_f32_e32 v19, v19
	v_min_f32_e32 v8, 0x42ac0000, v8
	v_exp_f32_e32 v8, v8
	v_min_f32_e32 v7, 0x42ac0000, v7
	v_exp_f32_e32 v7, v7
	v_mul_f32_e32 v12, v12, v11
	v_mul_f32_e32 v10, v10, v11
	v_mul_f32_e32 v9, v9, v19
	v_mov_b32_e32 v11, v19
	v_add_f32_e32 v19, 1.0, v8
	v_rcp_f32_e32 v19, v19
	v_mul_f32_e32 v11, v11, v10
	v_mul_f32_e32 v9, v9, v10
	v_add_f32_e32 v10, 1.0, v7
	v_rcp_f32_e32 v10, v10
	v_min_f32_e32 v6, 0x42ac0000, v6
	v_exp_f32_e32 v6, v6
	v_mul_f32_e32 v8, v8, v19
	v_mul_f32_e32 v7, v7, v10
	v_add_f32_e32 v20, 1.0, v6
	v_rcp_f32_e32 v20, v20
	v_min_f32_e32 v5, 0x42ac0000, v5
	v_exp_f32_e32 v5, v5
	v_mul_f32_e32 v8, v8, v9
	v_mul_f32_e32 v10, v10, v8
	v_mul_f32_e32 v7, v7, v8
	v_mul_f32_e32 v6, v6, v20
	v_mov_b32_e32 v8, v20
	v_add_f32_e32 v20, 1.0, v5
	v_rcp_f32_e32 v20, v20
	v_min_f32_e32 v4, 0x42ac0000, v4
	v_exp_f32_e32 v4, v4
	v_mul_f32_e32 v8, v8, v7
	v_mul_f32_e32 v6, v6, v7
	v_mul_f32_e32 v5, v5, v20
	v_mov_b32_e32 v7, v20
	v_add_f32_e32 v20, 1.0, v4
	v_rcp_f32_e32 v20, v20
	v_min_f32_e32 v3, 0x42ac0000, v3
	v_exp_f32_e32 v3, v3
	v_mul_f32_e32 v7, v7, v6
	v_mul_f32_e32 v5, v5, v6
	v_mul_f32_e32 v4, v4, v20
	v_mov_b32_e32 v6, v20
	v_add_f32_e32 v20, 1.0, v3
	v_rcp_f32_e32 v20, v20
	v_min_f32_e32 v2, 0x42ac0000, v2
	v_exp_f32_e32 v2, v2
	v_mul_f32_e32 v6, v6, v5
	v_mul_f32_e32 v4, v4, v5
	v_mul_f32_e32 v3, v3, v20
	v_mov_b32_e32 v5, v20
	v_add_f32_e32 v20, 1.0, v2
	v_rcp_f32_e32 v20, v20
	v_min_f32_e32 v1, 0x42ac0000, v1
	v_exp_f32_e32 v1, v1
	v_mul_f32_e32 v5, v5, v4
	v_mul_f32_e32 v3, v3, v4
	v_mul_f32_e32 v2, v2, v20
	v_mov_b32_e32 v4, v20
	v_add_f32_e32 v20, 1.0, v1
	v_rcp_f32_e32 v20, v20
	v_min_f32_e32 v0, 0x42ac0000, v0
	v_exp_f32_e32 v0, v0
	v_mul_f32_e32 v21, v4, v3
	v_mul_f32_e32 v2, v2, v3
	v_mul_f32_e32 v1, v1, v20
	v_mov_b32_e32 v3, v20
	v_add_f32_e32 v20, 1.0, v0
	v_rcp_f32_e32 v20, v20
	v_mul_f32_e32 v3, v3, v2
	v_mul_f32_e32 v0, v0, v20
	v_mul_f32_e32 v1, v1, v2
	v_mov_b32_e32 v2, v20
	v_mul_f32_e32 v20, v0, v1
	v_mov_b32_e32 v22, v20
	s_nop 1
	s_nop 0
	v_permlane32_swap_b32_e32 v20, v22
	v_mul_f32_e32 v2, v2, v1
	v_cndmask_b32_e64 v4, 1.0, v22, s[10:11]
	v_mul_f32_e32 v0, v2, v4
	v_mul_f32_e32 v1, v3, v4
	v_mul_f32_e32 v2, v21, v4
	v_mul_f32_e32 v3, v5, v4
	v_mul_f32_e32 v5, v6, v4
	v_mul_f32_e32 v6, v7, v4
	v_mul_f32_e32 v7, v8, v4
	v_mul_f32_e32 v8, v10, v4
	v_cvt_pk_bf16_f32 v0, v0, v1
	v_cvt_pk_bf16_f32 v1, v2, v3
	v_cvt_pk_bf16_f32 v2, v5, v6
	v_cvt_pk_bf16_f32 v3, v7, v8
	v_mov_b32_e32 v5, v19
	s_nop 0
	v_mfma_f32_32x32x16_bf16 v[98:113], v[46:49], v[0:3], 0
	v_mul_f32_e32 v5, v5, v9
	v_mul_f32_e32 v6, v5, v4
	v_mul_f32_e32 v7, v11, v4
	v_mul_f32_e32 v8, v12, v4
	v_mul_f32_e32 v9, v13, v4
	v_mul_f32_e32 v191, v20, v22
.Lsb_join_1:
	v_cmp_gt_f32_e32 vcc, s68, v191
	v_mfma_f32_32x32x16_bf16 v[82:97], v[42:45], v[0:3], 0
	v_mul_f32_e32 v2, v17, v4
	v_mul_f32_e32 v3, v18, v4
	v_pk_mul_f32 v[4:5], v[14:15], v[4:5] op_sel_hi:[1,0]
	v_cvt_pk_bf16_f32 v0, v6, v7
	v_cvt_pk_bf16_f32 v1, v8, v9
	v_cvt_pk_bf16_f32 v2, v2, v3
	v_cvt_pk_bf16_f32 v3, v4, v5
	s_cmp_eq_u64 vcc, exec
	s_cselect_b64 s[0:1], -1, 0
	v_mfma_f32_32x32x16_bf16 v[98:113], v[38:41], v[0:3], v[98:113]
	v_mfma_f32_32x32x16_bf16 v[82:97], v[34:37], v[0:3], v[82:97]
	v_cndmask_b32_e64 v0, 0, 1, s[0:1]
	s_nop 0
	v_readfirstlane_b32 s81, v0

; #define LAS __attribute__((address_space(3)))
; DI f32x16 zero16() { f32x16 z; for (int i = 0; i < 16; ++i) z[i] = 0.f; return z; }
; #define MFMA32(a, b, c) __builtin_amdgcn_mfma_f32_32x32x16_bf16((a), (b), (c), 0, 0, 0)
; DI void sb_block2(const Params& p, LAS unsigned char* lds, int bh, int qb2, int tid) {
;     ...
;                 const LAS unsigned char* kp = base + (sub * 32 + r) * SB_ROW + h * 16;
;                 const bool act0 = !done[0] && kb <= q0[0], act1 = !done[1] && kb <= q0[1];
;                 if (act0 || act1) {
;                     bf16x8 kf[4], vf[4];
; #pragma unroll
;                     for (int ks = 0; ks < 4; ++ks) kf[ks] = *(const LAS bf16x8*)(kp + ks * 32);
; #pragma unroll
;                     for (int dt = 0; dt < 2; ++dt)
; #pragma unroll
;                         for (int s2 = 0; s2 < 2; ++s2) vf[dt * 2 + s2] = *(const LAS bf16x8*)(base + SB_KBYTES + (dt * 32 + r) * SB_ROW + (sub * 32 + 16 * h + 8 * s2) * 2);
;                     f32x16 zz[2];
; #pragma unroll
;                     for (int g = 0; g < 2; ++g) {
;                         zz[g] = zero16();
;                         if (g == 0 ? act0 : act1) {
; #pragma unroll
;                             for (int ks = 0; ks < 4; ++ks) zz[g] = MFMA32(kf[ks], qf[g][ks], zz[g]);
;                         }
.LBB0_845:
	v_cndmask_b32_e64 v32, 0, 1, s[2:3]
	v_cmp_ne_u32_e64 s[48:49], 1, v32
	s_andn2_b64 vcc, exec, s[2:3]
	s_nop 7
	v_mov_b64_e32 v[32:33], v[14:15]
	v_mov_b64_e32 v[30:31], v[12:13]
	v_mov_b64_e32 v[28:29], v[10:11]
	v_mov_b64_e32 v[26:27], v[8:9]
	v_mov_b64_e32 v[24:25], v[6:7]
	v_mov_b64_e32 v[22:23], v[4:5]
	v_mov_b64_e32 v[20:21], v[2:3]
	v_mov_b64_e32 v[18:19], v[0:1]
	s_cbranch_vccnz .LBB0_934
	s_waitcnt lgkmcnt(0)
	v_mfma_f32_32x32x16_bf16 v[34:49], v[174:177], v[130:133], 0
	v_mfma_f32_32x32x16_bf16 v[34:49], v[170:173], v[134:137], v[34:49]
	v_mfma_f32_32x32x16_bf16 v[34:49], v[166:169], v[138:141], v[34:49]
	v_mfma_f32_32x32x16_bf16 v[34:49], v[162:165], v[142:145], v[34:49]
	s_and_b64 vcc, exec, s[0:1]
	s_cbranch_vccz .LBB0_935

; DI unsigned pk2(float lo, float hi) { f32x2 v = {lo, hi}; bf2_t r = __builtin_convertvector(v, bf2_t); return __builtin_bit_cast(unsigned, r); }
; DI void xhalf(float x, float& lo, float& hi) { const u32x2p r = __builtin_amdgcn_permlane32_swap(__float_as_uint(x), __float_as_uint(x), false, false); lo = __uint_as_float(r.x); hi = __uint_as_float(r.y); }
; #define MFMA32(a, b, c) __builtin_amdgcn_mfma_f32_32x32x16_bf16((a), (b), (c), 0, 0, 0)
; DI void sb_block2(const Params& p, LAS unsigned char* lds, int bh, int qb2, int tid) {
;     ...
;                         if (g == 0 ? act0 : act1) {
;                             const f32x16 z = zz[g];
;                             const bool diag = (kb == q0[g]);
;                             f32x16 a;
;                             float tot = 1.f;
; #pragma unroll
;                             for (int i = 15; i >= 0; --i) {
;                                 const float w = __builtin_amdgcn_exp2f(fminf(z[i], 86.f));
;                                 float be = __builtin_amdgcn_rcpf(1.f + w);
;                                 float om = w * be;
;                                 if (diag) { const bool valid = (16 * h + i < r); be = valid ? be : 0.f; om = valid ? om : 1.f; }
;                                 a[i] = be * tot;
;                                 tot *= om;
;                             }
;                             float tlo, thi; xhalf(tot, tlo, thi);
;                             const float bs = carry[g] * (h == 0 ? thi : 1.f);
;                             carry[g] *= tlo * thi;
; #pragma unroll
;                             for (int i = 0; i < 16; ++i) a[i] *= bs;
;                             bf16x8 pf[2];
; #pragma unroll
;                             for (int s2 = 0; s2 < 2; ++s2) {
;                                 u32x4 w; w.x = pk2(a[8 * s2 + 0], a[8 * s2 + 1]); w.y = pk2(a[8 * s2 + 2], a[8 * s2 + 3]); w.z = pk2(a[8 * s2 + 4], a[8 * s2 + 5]); w.w = pk2(a[8 * s2 + 6], a[8 * s2 + 7]);
;                                 pf[s2] = __builtin_bit_cast(bf16x8, w);
;                             }
; #pragma unroll
;                             for (int s2 = 0; s2 < 2; ++s2) { o0[g] = MFMA32(vf[s2], pf[s2], o0[g]); o1[g] = MFMA32(vf[2 + s2], pf[s2], o1[g]); }
.LBB0_848:
	s_nop 7
	s_cmp_eq_u32 s59, s58
	s_cbranch_scc0 .Lsb_lean_2
	v_min_f32_e32 v0, 0x42ac0000, v49
	v_exp_f32_e32 v0, v0
	v_min_f32_e32 v1, 0x42ac0000, v48
	v_exp_f32_e32 v2, v1
	v_add_f32_e32 v1, 1.0, v0
	v_rcp_f32_e32 v1, v1
	s_cmp_eq_u32 s59, s58
	v_add_f32_e32 v3, 1.0, v2
	v_rcp_f32_e32 v3, v3
	v_mul_f32_e32 v0, v0, v1
	v_cndmask_b32_e64 v4, 0, v1, s[14:15]
	v_cndmask_b32_e64 v5, 1.0, v0, s[14:15]
	s_cselect_b64 vcc, -1, 0
	v_cndmask_b32_e32 v1, v1, v4, vcc
	v_cndmask_b32_e32 v4, v0, v5, vcc
	v_mul_f32_e32 v0, v2, v3
	v_min_f32_e32 v2, 0x42ac0000, v47
	v_exp_f32_e32 v2, v2
	v_cndmask_b32_e64 v5, 0, v3, s[16:17]
	v_cndmask_b32_e64 v6, 1.0, v0, s[16:17]
	v_cndmask_b32_e32 v3, v3, v5, vcc
	v_cndmask_b32_e32 v6, v0, v6, vcc
	v_add_f32_e32 v5, 1.0, v2
	v_mul_f32_e32 v0, v3, v4
	v_mul_f32_e32 v3, v4, v6
	v_rcp_f32_e32 v5, v5
	v_min_f32_e32 v4, 0x42ac0000, v46
	v_exp_f32_e32 v4, v4
	v_cndmask_b32_e64 v6, 0, v5, s[18:19]
	v_mul_f32_e32 v2, v2, v5
	v_cndmask_b32_e32 v5, v5, v6, vcc
	v_add_f32_e32 v6, 1.0, v4
	v_rcp_f32_e32 v6, v6
	v_cndmask_b32_e64 v7, 1.0, v2, s[18:19]
	v_cndmask_b32_e32 v2, v2, v7, vcc
	v_mul_f32_e32 v7, v5, v3
	v_mul_f32_e32 v2, v2, v3
	v_mul_f32_e32 v3, v4, v6
	v_min_f32_e32 v4, 0x42ac0000, v45
	v_exp_f32_e32 v4, v4
	v_cndmask_b32_e64 v5, 0, v6, s[20:21]
	v_cndmask_b32_e32 v5, v6, v5, vcc
	v_cndmask_b32_e64 v8, 1.0, v3, s[20:21]
	v_add_f32_e32 v6, 1.0, v4
	v_rcp_f32_e32 v6, v6
	v_cndmask_b32_e32 v3, v3, v8, vcc
	v_mul_f32_e32 v8, v5, v2
	v_mul_f32_e32 v2, v3, v2
	v_mul_f32_e32 v3, v4, v6
	v_min_f32_e32 v4, 0x42ac0000, v44
	v_exp_f32_e32 v4, v4
	v_cndmask_b32_e64 v5, 0, v6, s[22:23]
	v_cndmask_b32_e32 v5, v6, v5, vcc
	v_cndmask_b32_e64 v9, 1.0, v3, s[22:23]
	v_add_f32_e32 v6, 1.0, v4
	v_rcp_f32_e32 v6, v6
	v_cndmask_b32_e32 v3, v3, v9, vcc
	v_mul_f32_e32 v9, v5, v2
	v_mul_f32_e32 v2, v3, v2
	v_mul_f32_e32 v3, v4, v6
	v_min_f32_e32 v4, 0x42ac0000, v43
	v_exp_f32_e32 v4, v4
	v_cndmask_b32_e64 v5, 0, v6, s[24:25]
	v_cndmask_b32_e64 v10, 1.0, v3, s[24:25]
	v_cndmask_b32_e32 v5, v6, v5, vcc
	v_add_f32_e32 v6, 1.0, v4
	v_cndmask_b32_e32 v3, v3, v10, vcc
	v_mul_f32_e32 v10, v5, v2
	v_rcp_f32_e32 v6, v6
	v_min_f32_e32 v5, 0x42ac0000, v42
	v_exp_f32_e32 v5, v5
	v_mul_f32_e32 v2, v3, v2
	v_mul_f32_e32 v3, v4, v6
	v_cndmask_b32_e64 v4, 0, v6, s[26:27]
	v_cndmask_b32_e64 v11, 1.0, v3, s[26:27]
	v_cndmask_b32_e32 v4, v6, v4, vcc
	v_add_f32_e32 v6, 1.0, v5
	v_cndmask_b32_e32 v3, v3, v11, vcc
	v_rcp_f32_e32 v11, v6
	v_min_f32_e32 v6, 0x42ac0000, v41
	v_exp_f32_e32 v6, v6
	v_mul_f32_e32 v12, v4, v2
	v_mul_f32_e32 v13, v3, v2
	v_mul_f32_e32 v2, v5, v11
	v_add_f32_e32 v3, 1.0, v6
	v_rcp_f32_e32 v3, v3
	v_min_f32_e32 v5, 0x42ac0000, v40
	v_exp_f32_e32 v5, v5
	v_cndmask_b32_e64 v4, 1.0, v2, s[28:29]
	v_cndmask_b32_e32 v2, v2, v4, vcc
	v_mul_f32_e32 v4, v6, v3
	v_cndmask_b32_e64 v6, 0, v3, s[30:31]
	v_cndmask_b32_e32 v3, v3, v6, vcc
	v_add_f32_e32 v6, 1.0, v5
	v_rcp_f32_e32 v6, v6
	v_cndmask_b32_e64 v14, 1.0, v4, s[30:31]
	v_mul_f32_e32 v2, v2, v13
	v_cndmask_b32_e32 v4, v4, v14, vcc
	v_mul_f32_e32 v3, v3, v2
	v_mul_f32_e32 v2, v4, v2
	v_mul_f32_e32 v4, v5, v6
	v_min_f32_e32 v5, 0x42ac0000, v39
	v_exp_f32_e32 v5, v5
	v_cndmask_b32_e64 v14, 0, v6, s[34:35]
	v_cndmask_b32_e32 v6, v6, v14, vcc
	v_cndmask_b32_e64 v15, 1.0, v4, s[34:35]
	v_add_f32_e32 v14, 1.0, v5
	v_rcp_f32_e32 v14, v14
	v_cndmask_b32_e32 v4, v4, v15, vcc
	v_mul_f32_e32 v15, v6, v2
	v_mul_f32_e32 v2, v4, v2
	v_mul_f32_e32 v4, v5, v14
	v_min_f32_e32 v5, 0x42ac0000, v38
	v_exp_f32_e32 v5, v5
	v_cndmask_b32_e64 v6, 0, v14, s[36:37]
	v_cndmask_b32_e32 v6, v14, v6, vcc
	v_cndmask_b32_e64 v17, 1.0, v4, s[36:37]
	v_add_f32_e32 v14, 1.0, v5
	v_rcp_f32_e32 v14, v14
	v_cndmask_b32_e32 v4, v4, v17, vcc
	v_mul_f32_e32 v17, v6, v2
	v_mul_f32_e32 v2, v4, v2
	v_mul_f32_e32 v4, v5, v14
	v_min_f32_e32 v5, 0x42ac0000, v37
	v_exp_f32_e32 v5, v5
	v_cndmask_b32_e64 v6, 0, v14, s[38:39]
	v_cndmask_b32_e32 v6, v14, v6, vcc
	v_cndmask_b32_e64 v18, 1.0, v4, s[38:39]
	v_add_f32_e32 v14, 1.0, v5
	v_rcp_f32_e32 v14, v14
	v_cndmask_b32_e32 v4, v4, v18, vcc
	v_mul_f32_e32 v18, v6, v2
	v_mul_f32_e32 v2, v4, v2
	v_mul_f32_e32 v4, v5, v14
	v_min_f32_e32 v5, 0x42ac0000, v36
	v_exp_f32_e32 v5, v5
	v_cndmask_b32_e64 v6, 0, v14, s[40:41]
	v_cndmask_b32_e32 v6, v14, v6, vcc
	v_cndmask_b32_e64 v19, 1.0, v4, s[40:41]
	v_add_f32_e32 v14, 1.0, v5
	v_rcp_f32_e32 v14, v14
	v_cndmask_b32_e32 v4, v4, v19, vcc
	v_mul_f32_e32 v19, v6, v2
	v_mul_f32_e32 v2, v4, v2
	v_mul_f32_e32 v4, v5, v14
	v_min_f32_e32 v5, 0x42ac0000, v35
	v_exp_f32_e32 v5, v5
	v_cndmask_b32_e64 v6, 0, v14, s[42:43]
	v_cndmask_b32_e32 v6, v14, v6, vcc
	v_cndmask_b32_e64 v20, 1.0, v4, s[42:43]
	v_add_f32_e32 v14, 1.0, v5
	v_rcp_f32_e32 v14, v14
	v_cndmask_b32_e32 v4, v4, v20, vcc
	v_mul_f32_e32 v20, v6, v2
	v_mul_f32_e32 v2, v4, v2
	v_mul_f32_e32 v4, v5, v14
	v_min_f32_e32 v5, 0x42ac0000, v34
	v_exp_f32_e32 v5, v5
	v_cndmask_b32_e64 v6, 0, v14, s[44:45]
	v_cndmask_b32_e32 v6, v14, v6, vcc
	v_cndmask_b32_e64 v21, 1.0, v4, s[44:45]
	v_add_f32_e32 v14, 1.0, v5
	v_rcp_f32_e32 v14, v14
	v_cndmask_b32_e32 v4, v4, v21, vcc
	v_mul_f32_e32 v21, v6, v2
	v_mul_f32_e32 v2, v4, v2
	v_mul_f32_e32 v4, v5, v14
	v_cndmask_b32_e64 v6, 1.0, v4, s[46:47]
	v_cndmask_b32_e64 v5, 0, v14, s[46:47]
	v_cndmask_b32_e32 v4, v4, v6, vcc
	v_cndmask_b32_e32 v5, v14, v5, vcc
	v_mul_f32_e32 v14, v4, v2
	v_mov_b32_e32 v22, v14
	s_nop 1
	s_nop 0
	v_permlane32_swap_b32_e32 v14, v22
	v_mul_f32_e32 v5, v5, v2
	v_cndmask_b32_e64 v2, 1.0, v22, s[10:11]
	v_mul_f32_e32 v6, v191, v2
	v_mul_f32_e32 v2, v5, v6
	v_mul_f32_e32 v4, v21, v6
	v_mul_f32_e32 v5, v20, v6
	v_mul_f32_e32 v19, v19, v6
	v_mul_f32_e32 v18, v18, v6
	v_mul_f32_e32 v17, v17, v6
	v_mul_f32_e32 v15, v15, v6
	v_mul_f32_e32 v20, v3, v6
	v_cvt_pk_bf16_f32 v2, v2, v4
	v_cvt_pk_bf16_f32 v3, v5, v19
	v_cvt_pk_bf16_f32 v4, v18, v17
	v_cvt_pk_bf16_f32 v5, v15, v20
	v_cndmask_b32_e64 v15, 0, v11, s[28:29]
	v_cndmask_b32_e32 v11, v11, v15, vcc
	s_waitcnt lgkmcnt(0)
	v_mfma_f32_32x32x16_bf16 v[98:113], v[158:161], v[2:5], v[98:113]
	v_mul_f32_e32 v11, v11, v13
	v_mul_f32_e32 v11, v11, v6
	v_mul_f32_e32 v12, v12, v6
	v_mul_f32_e32 v10, v10, v6
	v_mul_f32_e32 v9, v9, v6
	v_mfma_f32_32x32x16_bf16 v[82:97], v[154:157], v[2:5], v[82:97]
	v_mul_f32_e32 v2, v8, v6
	v_mul_f32_e32 v3, v7, v6
	v_mul_f32_e64 v4, v0, v6
	v_mul_f32_e64 v5, v1, v6
	v_cvt_pk_bf16_f32 v0, v11, v12
	v_cvt_pk_bf16_f32 v1, v10, v9
	v_cvt_pk_bf16_f32 v2, v2, v3
	v_cvt_pk_bf16_f32 v3, v4, v5
	v_mul_f32_e32 v4, v14, v22
	v_mul_f32_e32 v191, v191, v4
	v_mfma_f32_32x32x16_bf16 v[98:113], v[150:153], v[0:3], v[98:113]
	s_branch .Lsb_join_2
; DI unsigned pk2(float lo, float hi) { f32x2 v = {lo, hi}; bf2_t r = __builtin_convertvector(v, bf2_t); return __builtin_bit_cast(unsigned, r); }
; DI void xhalf(float x, float& lo, float& hi) { const u32x2p r = __builtin_amdgcn_permlane32_swap(__float_as_uint(x), __float_as_uint(x), false, false); lo = __uint_as_float(r.x); hi = __uint_as_float(r.y); }
; #define MFMA32(a, b, c) __builtin_amdgcn_mfma_f32_32x32x16_bf16((a), (b), (c), 0, 0, 0)
; DI void sb_block2(const Params& p, LAS unsigned char* lds, int bh, int qb2, int tid) {
;     ...
;                             for (int i = 15; i >= 0; --i) {
;                                 const float w = __builtin_amdgcn_exp2f(fminf(z[i], 86.f));
;                                 float be = __builtin_amdgcn_rcpf(1.f + w);
;                                 float om = w * be;
;                                 if (diag) { const bool valid = (16 * h + i < r); be = valid ? be : 0.f; om = valid ? om : 1.f; }
;                                 a[i] = be * tot;
;                                 tot *= om;
;                             }
;                             float tlo, thi; xhalf(tot, tlo, thi);
;                             const float bs = carry[g] * (h == 0 ? thi : 1.f);
;                             carry[g] *= tlo * thi;
; #pragma unroll
;                             for (int i = 0; i < 16; ++i) a[i] *= bs;
;                             bf16x8 pf[2];
; #pragma unroll
;                             for (int s2 = 0; s2 < 2; ++s2) {
;                                 u32x4 w; w.x = pk2(a[8 * s2 + 0], a[8 * s2 + 1]); w.y = pk2(a[8 * s2 + 2], a[8 * s2 + 3]); w.z = pk2(a[8 * s2 + 4], a[8 * s2 + 5]); w.w = pk2(a[8 * s2 + 6], a[8 * s2 + 7]);
;                                 pf[s2] = __builtin_bit_cast(bf16x8, w);
;                             }
; #pragma unroll
;                             for (int s2 = 0; s2 < 2; ++s2) { o0[g] = MFMA32(vf[s2], pf[s2], o0[g]); o1[g] = MFMA32(vf[2 + s2], pf[s2], o1[g]); }
;                             if (__all(carry[g] < SB_PTHR)) done[g] = true;
.Lsb_lean_2:
	v_min_f32_e32 v0, 0x42ac0000, v49
	v_exp_f32_e32 v0, v0
	v_min_f32_e32 v1, 0x42ac0000, v48
	v_exp_f32_e32 v2, v1
	v_add_f32_e32 v1, 1.0, v0
	v_rcp_f32_e32 v1, v1
	v_add_f32_e32 v3, 1.0, v2
	v_rcp_f32_e32 v3, v3
	v_mul_f32_e32 v0, v0, v1
	v_mov_b32_e32 v4, v0
	v_mul_f32_e32 v0, v2, v3
	v_min_f32_e32 v2, 0x42ac0000, v47
	v_exp_f32_e32 v2, v2
	v_mov_b32_e32 v6, v0
	v_add_f32_e32 v5, 1.0, v2
	v_mul_f32_e32 v0, v3, v4
	v_mul_f32_e32 v3, v4, v6
	v_rcp_f32_e32 v5, v5
	v_min_f32_e32 v4, 0x42ac0000, v46
	v_exp_f32_e32 v4, v4
	v_mul_f32_e32 v2, v2, v5
	v_add_f32_e32 v6, 1.0, v4
	v_rcp_f32_e32 v6, v6
	v_mul_f32_e32 v7, v5, v3
	v_mul_f32_e32 v2, v2, v3
	v_mul_f32_e32 v3, v4, v6
	v_min_f32_e32 v4, 0x42ac0000, v45
	v_exp_f32_e32 v4, v4
	v_mov_b32_e32 v5, v6
	v_add_f32_e32 v6, 1.0, v4
	v_rcp_f32_e32 v6, v6
	v_mul_f32_e32 v8, v5, v2
	v_mul_f32_e32 v2, v3, v2
	v_mul_f32_e32 v3, v4, v6
	v_min_f32_e32 v4, 0x42ac0000, v44
	v_exp_f32_e32 v4, v4
	v_mov_b32_e32 v5, v6
	v_add_f32_e32 v6, 1.0, v4
	v_rcp_f32_e32 v6, v6
	v_mul_f32_e32 v9, v5, v2
	v_mul_f32_e32 v2, v3, v2
	v_mul_f32_e32 v3, v4, v6
	v_min_f32_e32 v4, 0x42ac0000, v43
	v_exp_f32_e32 v4, v4
	v_mov_b32_e32 v5, v6
	v_add_f32_e32 v6, 1.0, v4
	v_mul_f32_e32 v10, v5, v2
	v_rcp_f32_e32 v6, v6
	v_min_f32_e32 v5, 0x42ac0000, v42
	v_exp_f32_e32 v5, v5
	v_mul_f32_e32 v2, v3, v2
	v_mul_f32_e32 v3, v4, v6
	v_mov_b32_e32 v4, v6
	v_add_f32_e32 v6, 1.0, v5
	v_rcp_f32_e32 v11, v6
	v_min_f32_e32 v6, 0x42ac0000, v41
	v_exp_f32_e32 v6, v6
	v_mul_f32_e32 v12, v4, v2
	v_mul_f32_e32 v13, v3, v2
	v_mul_f32_e32 v2, v5, v11
	v_add_f32_e32 v3, 1.0, v6
	v_rcp_f32_e32 v3, v3
	v_min_f32_e32 v5, 0x42ac0000, v40
	v_exp_f32_e32 v5, v5
	v_mul_f32_e32 v4, v6, v3
	v_add_f32_e32 v6, 1.0, v5
	v_rcp_f32_e32 v6, v6
	v_mul_f32_e32 v2, v2, v13
	v_mul_f32_e32 v3, v3, v2
	v_mul_f32_e32 v2, v4, v2
	v_mul_f32_e32 v4, v5, v6
	v_min_f32_e32 v5, 0x42ac0000, v39
	v_exp_f32_e32 v5, v5
	s_nop 0
	v_add_f32_e32 v14, 1.0, v5
	v_rcp_f32_e32 v14, v14
	v_mul_f32_e32 v15, v6, v2
	v_mul_f32_e32 v2, v4, v2
	v_mul_f32_e32 v4, v5, v14
	v_min_f32_e32 v5, 0x42ac0000, v38
	v_exp_f32_e32 v5, v5
	v_mov_b32_e32 v6, v14
	v_add_f32_e32 v14, 1.0, v5
	v_rcp_f32_e32 v14, v14
	v_mul_f32_e32 v17, v6, v2
	v_mul_f32_e32 v2, v4, v2
	v_mul_f32_e32 v4, v5, v14
	v_min_f32_e32 v5, 0x42ac0000, v37
	v_exp_f32_e32 v5, v5
	v_mov_b32_e32 v6, v14
	v_add_f32_e32 v14, 1.0, v5
	v_rcp_f32_e32 v14, v14
	v_mul_f32_e32 v18, v6, v2
	v_mul_f32_e32 v2, v4, v2
	v_mul_f32_e32 v4, v5, v14
	v_min_f32_e32 v5, 0x42ac0000, v36
	v_exp_f32_e32 v5, v5
	v_mov_b32_e32 v6, v14
	v_add_f32_e32 v14, 1.0, v5
	v_rcp_f32_e32 v14, v14
	v_mul_f32_e32 v19, v6, v2
	v_mul_f32_e32 v2, v4, v2
	v_mul_f32_e32 v4, v5, v14
	v_min_f32_e32 v5, 0x42ac0000, v35
	v_exp_f32_e32 v5, v5
	v_mov_b32_e32 v6, v14
	v_add_f32_e32 v14, 1.0, v5
	v_rcp_f32_e32 v14, v14
	v_mul_f32_e32 v20, v6, v2
	v_mul_f32_e32 v2, v4, v2
	v_mul_f32_e32 v4, v5, v14
	v_min_f32_e32 v5, 0x42ac0000, v34
	v_exp_f32_e32 v5, v5
	v_mov_b32_e32 v6, v14
	v_add_f32_e32 v14, 1.0, v5
	v_rcp_f32_e32 v14, v14
	v_mul_f32_e32 v21, v6, v2
	v_mul_f32_e32 v2, v4, v2
	v_mul_f32_e32 v4, v5, v14
	v_mov_b32_e32 v5, v14
	v_mul_f32_e32 v14, v4, v2
	v_mov_b32_e32 v22, v14
	s_nop 1
	s_nop 0
	v_permlane32_swap_b32_e32 v14, v22
	v_mul_f32_e32 v5, v5, v2
	v_cndmask_b32_e64 v2, 1.0, v22, s[10:11]
	v_mul_f32_e32 v6, v191, v2
	v_mul_f32_e32 v2, v5, v6
	v_mul_f32_e32 v4, v21, v6
	v_mul_f32_e32 v5, v20, v6
	v_mul_f32_e32 v19, v19, v6
	v_mul_f32_e32 v18, v18, v6
	v_mul_f32_e32 v17, v17, v6
	v_mul_f32_e32 v15, v15, v6
	v_mul_f32_e32 v20, v3, v6
	v_cvt_pk_bf16_f32 v2, v2, v4
	v_cvt_pk_bf16_f32 v3, v5, v19
	v_cvt_pk_bf16_f32 v4, v18, v17
	v_cvt_pk_bf16_f32 v5, v15, v20
	v_cndmask_b32_e64 v15, 0, v11, s[28:29]
	s_waitcnt lgkmcnt(0)
	v_mfma_f32_32x32x16_bf16 v[98:113], v[158:161], v[2:5], v[98:113]
	v_mul_f32_e32 v11, v11, v13
	v_mul_f32_e32 v11, v11, v6
	v_mul_f32_e32 v12, v12, v6
	v_mul_f32_e32 v10, v10, v6
	v_mul_f32_e32 v9, v9, v6
	v_mfma_f32_32x32x16_bf16 v[82:97], v[154:157], v[2:5], v[82:97]
	v_mul_f32_e32 v2, v8, v6
	v_mul_f32_e32 v3, v7, v6
	v_mul_f32_e64 v4, v0, v6
	v_mul_f32_e64 v5, v1, v6
	v_cvt_pk_bf16_f32 v0, v11, v12
	v_cvt_pk_bf16_f32 v1, v10, v9
	v_cvt_pk_bf16_f32 v2, v2, v3
	v_cvt_pk_bf16_f32 v3, v4, v5
	v_mul_f32_e32 v4, v14, v22
	v_mul_f32_e32 v191, v191, v4
	v_mfma_f32_32x32x16_bf16 v[98:113], v[150:153], v[0:3], v[98:113]
.Lsb_join_2:
	v_cmp_gt_f32_e32 vcc, s68, v191
	s_cmp_eq_u64 vcc, exec
	s_cselect_b64 s[0:1], -1, 0
	v_mfma_f32_32x32x16_bf16 v[82:97], v[146:149], v[0:3], v[82:97]
	v_cndmask_b32_e64 v0, 0, 1, s[0:1]
	s_nop 0
	v_readfirstlane_b32 s81, v0

; DI unsigned pk2(float lo, float hi) { f32x2 v = {lo, hi}; bf2_t r = __builtin_convertvector(v, bf2_t); return __builtin_bit_cast(unsigned, r); }
; DI void xhalf(float x, float& lo, float& hi) { const u32x2p r = __builtin_amdgcn_permlane32_swap(__float_as_uint(x), __float_as_uint(x), false, false); lo = __uint_as_float(r.x); hi = __uint_as_float(r.y); }
; #define MFMA32(a, b, c) __builtin_amdgcn_mfma_f32_32x32x16_bf16((a), (b), (c), 0, 0, 0)
; DI void sb_block2(const Params& p, LAS unsigned char* lds, int bh, int qb2, int tid) {
;     ...
;                             for (int i = 15; i >= 0; --i) {
;                                 const float w = __builtin_amdgcn_exp2f(fminf(z[i], 86.f));
;                                 float be = __builtin_amdgcn_rcpf(1.f + w);
;                                 float om = w * be;
;                                 if (diag) { const bool valid = (16 * h + i < r); be = valid ? be : 0.f; om = valid ? om : 1.f; }
;                                 a[i] = be * tot;
;                                 tot *= om;
;                             }
;                             float tlo, thi; xhalf(tot, tlo, thi);
;                             const float bs = carry[g] * (h == 0 ? thi : 1.f);
;                             carry[g] *= tlo * thi;
; #pragma unroll
;                             for (int i = 0; i < 16; ++i) a[i] *= bs;
;                             bf16x8 pf[2];
; #pragma unroll
;                             for (int s2 = 0; s2 < 2; ++s2) {
;                                 u32x4 w; w.x = pk2(a[8 * s2 + 0], a[8 * s2 + 1]); w.y = pk2(a[8 * s2 + 2], a[8 * s2 + 3]); w.z = pk2(a[8 * s2 + 4], a[8 * s2 + 5]); w.w = pk2(a[8 * s2 + 6], a[8 * s2 + 7]);
;                                 pf[s2] = __builtin_bit_cast(bf16x8, w);
;                             }
; #pragma unroll
;                             for (int s2 = 0; s2 < 2; ++s2) { o0[g] = MFMA32(vf[s2], pf[s2], o0[g]); o1[g] = MFMA32(vf[2 + s2], pf[s2], o1[g]); }
;                             if (__all(carry[g] < SB_PTHR)) done[g] = true;
.LBB0_921:
	s_nop 7
	s_cmp_eq_u32 s71, s79
	s_cbranch_scc0 .Lsb_lean_3
	v_min_f32_e32 v0, 0x42ac0000, v49
	v_exp_f32_e32 v0, v0
	v_min_f32_e32 v1, 0x42ac0000, v48
	v_exp_f32_e32 v2, v1
	v_add_f32_e32 v1, 1.0, v0
	v_rcp_f32_e32 v1, v1
	s_cmp_eq_u32 s71, s79
	v_add_f32_e32 v3, 1.0, v2
	v_rcp_f32_e32 v3, v3
	v_mul_f32_e32 v0, v0, v1
	v_cndmask_b32_e64 v4, 0, v1, s[14:15]
	v_cndmask_b32_e64 v5, 1.0, v0, s[14:15]
	s_cselect_b64 vcc, -1, 0
	v_cndmask_b32_e32 v1, v1, v4, vcc
	v_cndmask_b32_e32 v4, v0, v5, vcc
	v_mul_f32_e32 v0, v2, v3
	v_min_f32_e32 v2, 0x42ac0000, v47
	v_exp_f32_e32 v2, v2
	v_cndmask_b32_e64 v5, 0, v3, s[16:17]
	v_cndmask_b32_e64 v6, 1.0, v0, s[16:17]
	v_cndmask_b32_e32 v3, v3, v5, vcc
	v_cndmask_b32_e32 v6, v0, v6, vcc
	v_add_f32_e32 v5, 1.0, v2
	v_mul_f32_e32 v0, v3, v4
	v_mul_f32_e32 v3, v4, v6
	v_rcp_f32_e32 v5, v5
	v_min_f32_e32 v4, 0x42ac0000, v46
	v_exp_f32_e32 v4, v4
	v_cndmask_b32_e64 v6, 0, v5, s[18:19]
	v_mul_f32_e32 v2, v2, v5
	v_cndmask_b32_e32 v5, v5, v6, vcc
	v_add_f32_e32 v6, 1.0, v4
	v_rcp_f32_e32 v6, v6
	v_cndmask_b32_e64 v7, 1.0, v2, s[18:19]
	v_cndmask_b32_e32 v2, v2, v7, vcc
	v_mul_f32_e32 v7, v5, v3
	v_mul_f32_e32 v2, v2, v3
	v_mul_f32_e32 v3, v4, v6
	v_min_f32_e32 v4, 0x42ac0000, v45
	v_exp_f32_e32 v4, v4
	v_cndmask_b32_e64 v5, 0, v6, s[20:21]
	v_cndmask_b32_e32 v5, v6, v5, vcc
	v_cndmask_b32_e64 v8, 1.0, v3, s[20:21]
	v_add_f32_e32 v6, 1.0, v4
	v_rcp_f32_e32 v6, v6
	v_cndmask_b32_e32 v3, v3, v8, vcc
	v_mul_f32_e32 v8, v5, v2
	v_mul_f32_e32 v2, v3, v2
	v_mul_f32_e32 v3, v4, v6
	v_min_f32_e32 v4, 0x42ac0000, v44
	v_exp_f32_e32 v4, v4
	v_cndmask_b32_e64 v5, 0, v6, s[22:23]
	v_cndmask_b32_e32 v5, v6, v5, vcc
	v_cndmask_b32_e64 v9, 1.0, v3, s[22:23]
	v_add_f32_e32 v6, 1.0, v4
	v_rcp_f32_e32 v6, v6
	v_cndmask_b32_e32 v3, v3, v9, vcc
	v_mul_f32_e32 v9, v5, v2
	v_mul_f32_e32 v2, v3, v2
	v_mul_f32_e32 v3, v4, v6
	v_min_f32_e32 v4, 0x42ac0000, v43
	v_exp_f32_e32 v4, v4
	v_cndmask_b32_e64 v5, 0, v6, s[24:25]
	v_cndmask_b32_e64 v10, 1.0, v3, s[24:25]
	v_cndmask_b32_e32 v5, v6, v5, vcc
	v_add_f32_e32 v6, 1.0, v4
	v_cndmask_b32_e32 v3, v3, v10, vcc
	v_mul_f32_e32 v10, v5, v2
	v_rcp_f32_e32 v6, v6
	v_min_f32_e32 v5, 0x42ac0000, v42
	v_exp_f32_e32 v5, v5
	v_mul_f32_e32 v2, v3, v2
	v_mul_f32_e32 v3, v4, v6
	v_cndmask_b32_e64 v4, 0, v6, s[26:27]
	v_cndmask_b32_e64 v11, 1.0, v3, s[26:27]
	v_cndmask_b32_e32 v4, v6, v4, vcc
	v_add_f32_e32 v6, 1.0, v5
	v_cndmask_b32_e32 v3, v3, v11, vcc
	v_rcp_f32_e32 v11, v6
	v_min_f32_e32 v6, 0x42ac0000, v41
	v_exp_f32_e32 v6, v6
	v_mul_f32_e32 v12, v4, v2
	v_mul_f32_e32 v13, v3, v2
	v_mul_f32_e32 v2, v5, v11
	v_add_f32_e32 v3, 1.0, v6
	v_rcp_f32_e32 v3, v3
	v_min_f32_e32 v5, 0x42ac0000, v40
	v_exp_f32_e32 v5, v5
	v_cndmask_b32_e64 v4, 1.0, v2, s[28:29]
	v_cndmask_b32_e32 v2, v2, v4, vcc
	v_mul_f32_e32 v4, v6, v3
	v_cndmask_b32_e64 v6, 0, v3, s[30:31]
	v_cndmask_b32_e32 v3, v3, v6, vcc
	v_add_f32_e32 v6, 1.0, v5
	v_rcp_f32_e32 v6, v6
	v_cndmask_b32_e64 v14, 1.0, v4, s[30:31]
	v_mul_f32_e32 v2, v2, v13
	v_cndmask_b32_e32 v4, v4, v14, vcc
	v_mul_f32_e32 v3, v3, v2
	v_mul_f32_e32 v2, v4, v2
	v_mul_f32_e32 v4, v5, v6
	v_min_f32_e32 v5, 0x42ac0000, v39
	v_exp_f32_e32 v5, v5
	v_cndmask_b32_e64 v14, 0, v6, s[34:35]
	v_cndmask_b32_e32 v6, v6, v14, vcc
	v_cndmask_b32_e64 v15, 1.0, v4, s[34:35]
	v_add_f32_e32 v14, 1.0, v5
	v_rcp_f32_e32 v14, v14
	v_cndmask_b32_e32 v4, v4, v15, vcc
	v_mul_f32_e32 v15, v6, v2
	v_mul_f32_e32 v2, v4, v2
	v_mul_f32_e32 v4, v5, v14
	v_min_f32_e32 v5, 0x42ac0000, v38
	v_exp_f32_e32 v5, v5
	v_cndmask_b32_e64 v6, 0, v14, s[36:37]
	v_cndmask_b32_e32 v6, v14, v6, vcc
	v_cndmask_b32_e64 v17, 1.0, v4, s[36:37]
	v_add_f32_e32 v14, 1.0, v5
	v_rcp_f32_e32 v14, v14
	v_cndmask_b32_e32 v4, v4, v17, vcc
	v_mul_f32_e32 v17, v6, v2
	v_mul_f32_e32 v2, v4, v2
	v_mul_f32_e32 v4, v5, v14
	v_min_f32_e32 v5, 0x42ac0000, v37
	v_exp_f32_e32 v5, v5
	v_cndmask_b32_e64 v6, 0, v14, s[38:39]
	v_cndmask_b32_e32 v6, v14, v6, vcc
	v_cndmask_b32_e64 v18, 1.0, v4, s[38:39]
	v_add_f32_e32 v14, 1.0, v5
	v_rcp_f32_e32 v14, v14
	v_cndmask_b32_e32 v4, v4, v18, vcc
	v_mul_f32_e32 v18, v6, v2
	v_mul_f32_e32 v2, v4, v2
	v_mul_f32_e32 v4, v5, v14
	v_min_f32_e32 v5, 0x42ac0000, v36
	v_exp_f32_e32 v5, v5
	v_cndmask_b32_e64 v6, 0, v14, s[40:41]
	v_cndmask_b32_e32 v6, v14, v6, vcc
	v_cndmask_b32_e64 v19, 1.0, v4, s[40:41]
	v_add_f32_e32 v14, 1.0, v5
	v_rcp_f32_e32 v14, v14
	v_cndmask_b32_e32 v4, v4, v19, vcc
	v_mul_f32_e32 v19, v6, v2
	v_mul_f32_e32 v2, v4, v2
	v_mul_f32_e32 v4, v5, v14
	v_min_f32_e32 v5, 0x42ac0000, v35
	v_exp_f32_e32 v5, v5
	v_cndmask_b32_e64 v6, 0, v14, s[42:43]
	v_cndmask_b32_e32 v6, v14, v6, vcc
	v_cndmask_b32_e64 v20, 1.0, v4, s[42:43]
	v_add_f32_e32 v14, 1.0, v5
	v_rcp_f32_e32 v14, v14
	v_cndmask_b32_e32 v4, v4, v20, vcc
	v_mul_f32_e32 v20, v6, v2
	v_mul_f32_e32 v2, v4, v2
	v_mul_f32_e32 v4, v5, v14
	v_min_f32_e32 v5, 0x42ac0000, v34
	v_exp_f32_e32 v5, v5
	v_cndmask_b32_e64 v6, 0, v14, s[44:45]
	v_cndmask_b32_e32 v6, v14, v6, vcc
	v_cndmask_b32_e64 v21, 1.0, v4, s[44:45]
	v_add_f32_e32 v14, 1.0, v5
	v_rcp_f32_e32 v14, v14
	v_cndmask_b32_e32 v4, v4, v21, vcc
	v_mul_f32_e32 v21, v6, v2
	v_mul_f32_e32 v2, v4, v2
	v_mul_f32_e32 v4, v5, v14
	v_cndmask_b32_e64 v6, 1.0, v4, s[46:47]
	v_cndmask_b32_e64 v5, 0, v14, s[46:47]
	v_cndmask_b32_e32 v4, v4, v6, vcc
	v_cndmask_b32_e32 v5, v14, v5, vcc
	v_mul_f32_e32 v14, v4, v2
	v_mov_b32_e32 v22, v14
	s_nop 1
	s_nop 0
	v_permlane32_swap_b32_e32 v14, v22
	v_mul_f32_e32 v5, v5, v2
	v_cndmask_b32_e64 v2, 1.0, v22, s[10:11]
	v_mul_f32_e32 v6, v191, v2
	v_mul_f32_e32 v2, v5, v6
	v_mul_f32_e32 v4, v21, v6
	v_mul_f32_e32 v5, v20, v6
	v_mul_f32_e32 v19, v19, v6
	v_mul_f32_e32 v18, v18, v6
	v_mul_f32_e32 v17, v17, v6
	v_mul_f32_e32 v15, v15, v6
	v_mul_f32_e32 v20, v3, v6
	v_cvt_pk_bf16_f32 v2, v2, v4
	v_cvt_pk_bf16_f32 v3, v5, v19
	v_cvt_pk_bf16_f32 v4, v18, v17
	v_cvt_pk_bf16_f32 v5, v15, v20
	v_cndmask_b32_e64 v15, 0, v11, s[28:29]
	v_cndmask_b32_e32 v11, v11, v15, vcc
	s_waitcnt lgkmcnt(0)
	v_mfma_f32_32x32x16_bf16 v[98:113], v[158:161], v[2:5], v[98:113]
	v_mul_f32_e32 v11, v11, v13
	v_mul_f32_e32 v11, v11, v6
	v_mul_f32_e32 v12, v12, v6
	v_mul_f32_e32 v10, v10, v6
	v_mul_f32_e32 v9, v9, v6
	v_mfma_f32_32x32x16_bf16 v[82:97], v[154:157], v[2:5], v[82:97]
	v_mul_f32_e32 v2, v8, v6
	v_mul_f32_e32 v3, v7, v6
	v_mul_f32_e64 v4, v0, v6
	v_mul_f32_e64 v5, v1, v6
	v_cvt_pk_bf16_f32 v0, v11, v12
	v_cvt_pk_bf16_f32 v1, v10, v9
	v_cvt_pk_bf16_f32 v2, v2, v3
	v_cvt_pk_bf16_f32 v3, v4, v5
	v_mul_f32_e32 v4, v14, v22
	v_mul_f32_e32 v191, v191, v4
	v_mfma_f32_32x32x16_bf16 v[98:113], v[150:153], v[0:3], v[98:113]
	s_branch .Lsb_join_3

; DI unsigned pk2(float lo, float hi) { f32x2 v = {lo, hi}; bf2_t r = __builtin_convertvector(v, bf2_t); return __builtin_bit_cast(unsigned, r); }
; DI void xhalf(float x, float& lo, float& hi) { const u32x2p r = __builtin_amdgcn_permlane32_swap(__float_as_uint(x), __float_as_uint(x), false, false); lo = __uint_as_float(r.x); hi = __uint_as_float(r.y); }
; #define MFMA32(a, b, c) __builtin_amdgcn_mfma_f32_32x32x16_bf16((a), (b), (c), 0, 0, 0)
; DI void sb_block2(const Params& p, LAS unsigned char* lds, int bh, int qb2, int tid) {
;     ...
;                             for (int i = 15; i >= 0; --i) {
;                                 const float w = __builtin_amdgcn_exp2f(fminf(z[i], 86.f));
;                                 float be = __builtin_amdgcn_rcpf(1.f + w);
;                                 float om = w * be;
;                                 if (diag) { const bool valid = (16 * h + i < r); be = valid ? be : 0.f; om = valid ? om : 1.f; }
;                                 a[i] = be * tot;
;                                 tot *= om;
;                             }
;                             float tlo, thi; xhalf(tot, tlo, thi);
;                             const float bs = carry[g] * (h == 0 ? thi : 1.f);
;                             carry[g] *= tlo * thi;
; #pragma unroll
;                             for (int i = 0; i < 16; ++i) a[i] *= bs;
;                             bf16x8 pf[2];
; #pragma unroll
;                             for (int s2 = 0; s2 < 2; ++s2) {
;                                 u32x4 w; w.x = pk2(a[8 * s2 + 0], a[8 * s2 + 1]); w.y = pk2(a[8 * s2 + 2], a[8 * s2 + 3]); w.z = pk2(a[8 * s2 + 4], a[8 * s2 + 5]); w.w = pk2(a[8 * s2 + 6], a[8 * s2 + 7]);
;                                 pf[s2] = __builtin_bit_cast(bf16x8, w);
;                             }
; #pragma unroll
;                             for (int s2 = 0; s2 < 2; ++s2) { o0[g] = MFMA32(vf[s2], pf[s2], o0[g]); o1[g] = MFMA32(vf[2 + s2], pf[s2], o1[g]); }
;                             if (__all(carry[g] < SB_PTHR)) done[g] = true;
.LBB0_926:
	s_cmp_eq_u32 s77, s79
	s_cbranch_scc0 .Lsb_lean_4
	v_min_f32_e32 v0, 0x42ac0000, v33
	v_exp_f32_e32 v0, v0
	v_min_f32_e32 v1, 0x42ac0000, v32
	v_exp_f32_e32 v2, v1
	v_add_f32_e32 v1, 1.0, v0
	v_rcp_f32_e32 v1, v1
	s_cmp_eq_u32 s77, s79
	v_add_f32_e32 v3, 1.0, v2
	v_rcp_f32_e32 v3, v3
	v_mul_f32_e32 v0, v0, v1
	v_cndmask_b32_e64 v4, 0, v1, s[14:15]
	v_cndmask_b32_e64 v5, 1.0, v0, s[14:15]
	s_cselect_b64 vcc, -1, 0
	v_cndmask_b32_e32 v1, v1, v4, vcc
	v_cndmask_b32_e32 v4, v0, v5, vcc
	v_mul_f32_e32 v0, v2, v3
	v_min_f32_e32 v2, 0x42ac0000, v31
	v_exp_f32_e32 v2, v2
	v_cndmask_b32_e64 v5, 0, v3, s[16:17]
	v_cndmask_b32_e64 v6, 1.0, v0, s[16:17]
	v_cndmask_b32_e32 v3, v3, v5, vcc
	v_cndmask_b32_e32 v6, v0, v6, vcc
	v_add_f32_e32 v5, 1.0, v2
	v_mul_f32_e32 v0, v3, v4
	v_mul_f32_e32 v3, v4, v6
	v_rcp_f32_e32 v5, v5
	v_min_f32_e32 v4, 0x42ac0000, v30
	v_exp_f32_e32 v4, v4
	v_cndmask_b32_e64 v6, 0, v5, s[18:19]
	v_mul_f32_e32 v2, v2, v5
	v_cndmask_b32_e32 v5, v5, v6, vcc
	v_add_f32_e32 v6, 1.0, v4
	v_rcp_f32_e32 v6, v6
	v_cndmask_b32_e64 v7, 1.0, v2, s[18:19]
	v_cndmask_b32_e32 v2, v2, v7, vcc
	v_mul_f32_e32 v7, v5, v3
	v_mul_f32_e32 v2, v2, v3
	v_mul_f32_e32 v3, v4, v6
	v_min_f32_e32 v4, 0x42ac0000, v29
	v_exp_f32_e32 v4, v4
	v_cndmask_b32_e64 v5, 0, v6, s[20:21]
	v_cndmask_b32_e32 v5, v6, v5, vcc
	v_cndmask_b32_e64 v8, 1.0, v3, s[20:21]
	v_add_f32_e32 v6, 1.0, v4
	v_rcp_f32_e32 v6, v6
	v_cndmask_b32_e32 v3, v3, v8, vcc
	v_mul_f32_e32 v8, v5, v2
	v_mul_f32_e32 v2, v3, v2
	v_mul_f32_e32 v3, v4, v6
	v_min_f32_e32 v4, 0x42ac0000, v28
	v_exp_f32_e32 v4, v4
	v_cndmask_b32_e64 v5, 0, v6, s[22:23]
	v_cndmask_b32_e32 v5, v6, v5, vcc
	v_cndmask_b32_e64 v9, 1.0, v3, s[22:23]
	v_add_f32_e32 v6, 1.0, v4
	v_rcp_f32_e32 v6, v6
	v_cndmask_b32_e32 v3, v3, v9, vcc
	v_mul_f32_e32 v9, v5, v2
	v_mul_f32_e32 v2, v3, v2
	v_mul_f32_e32 v3, v4, v6
	v_min_f32_e32 v4, 0x42ac0000, v27
	v_exp_f32_e32 v4, v4
	v_cndmask_b32_e64 v5, 0, v6, s[24:25]
	v_cndmask_b32_e64 v10, 1.0, v3, s[24:25]
	v_cndmask_b32_e32 v5, v6, v5, vcc
	v_add_f32_e32 v6, 1.0, v4
	v_cndmask_b32_e32 v3, v3, v10, vcc
	v_mul_f32_e32 v10, v5, v2
	v_rcp_f32_e32 v6, v6
	v_min_f32_e32 v5, 0x42ac0000, v26
	v_exp_f32_e32 v5, v5
	v_mul_f32_e32 v2, v3, v2
	v_mul_f32_e32 v3, v4, v6
	v_cndmask_b32_e64 v4, 0, v6, s[26:27]
	v_cndmask_b32_e64 v11, 1.0, v3, s[26:27]
	v_cndmask_b32_e32 v4, v6, v4, vcc
	v_add_f32_e32 v6, 1.0, v5
	v_cndmask_b32_e32 v3, v3, v11, vcc
	v_rcp_f32_e32 v11, v6
	v_min_f32_e32 v6, 0x42ac0000, v25
	v_exp_f32_e32 v6, v6
	v_mul_f32_e32 v12, v4, v2
	v_mul_f32_e32 v13, v3, v2
	v_mul_f32_e32 v2, v5, v11
	v_add_f32_e32 v3, 1.0, v6
	v_rcp_f32_e32 v3, v3
	v_min_f32_e32 v5, 0x42ac0000, v24
	v_exp_f32_e32 v5, v5
	v_cndmask_b32_e64 v4, 1.0, v2, s[28:29]
	v_cndmask_b32_e32 v2, v2, v4, vcc
	v_mul_f32_e32 v4, v6, v3
	v_cndmask_b32_e64 v6, 0, v3, s[30:31]
	v_cndmask_b32_e32 v3, v3, v6, vcc
	v_add_f32_e32 v6, 1.0, v5
	v_rcp_f32_e32 v6, v6
	v_cndmask_b32_e64 v14, 1.0, v4, s[30:31]
	v_mul_f32_e32 v2, v2, v13
	v_cndmask_b32_e32 v4, v4, v14, vcc
	v_mul_f32_e32 v3, v3, v2
	v_mul_f32_e32 v2, v4, v2
	v_mul_f32_e32 v4, v5, v6
	v_min_f32_e32 v5, 0x42ac0000, v23
	v_exp_f32_e32 v5, v5
	v_cndmask_b32_e64 v14, 0, v6, s[34:35]
	v_cndmask_b32_e32 v6, v6, v14, vcc
	v_cndmask_b32_e64 v15, 1.0, v4, s[34:35]
	v_add_f32_e32 v14, 1.0, v5
	v_rcp_f32_e32 v14, v14
	v_cndmask_b32_e32 v4, v4, v15, vcc
	v_mul_f32_e32 v15, v6, v2
	v_mul_f32_e32 v2, v4, v2
	v_mul_f32_e32 v4, v5, v14
	v_min_f32_e32 v5, 0x42ac0000, v22
	v_exp_f32_e32 v5, v5
	v_cndmask_b32_e64 v6, 0, v14, s[36:37]
	v_cndmask_b32_e32 v6, v14, v6, vcc
	v_cndmask_b32_e64 v17, 1.0, v4, s[36:37]
	v_add_f32_e32 v14, 1.0, v5
	v_rcp_f32_e32 v14, v14
	v_cndmask_b32_e32 v4, v4, v17, vcc
	v_mul_f32_e32 v17, v6, v2
	v_mul_f32_e32 v2, v4, v2
	v_mul_f32_e32 v4, v5, v14
	v_min_f32_e32 v5, 0x42ac0000, v21
	v_exp_f32_e32 v5, v5
	v_cndmask_b32_e64 v6, 0, v14, s[38:39]
	v_cndmask_b32_e32 v6, v14, v6, vcc
	v_cndmask_b32_e64 v21, 1.0, v4, s[38:39]
	v_add_f32_e32 v14, 1.0, v5
	v_rcp_f32_e32 v14, v14
	v_cndmask_b32_e32 v4, v4, v21, vcc
	v_mul_f32_e32 v21, v6, v2
	v_mul_f32_e32 v2, v4, v2
	v_mul_f32_e32 v4, v5, v14
	v_min_f32_e32 v5, 0x42ac0000, v20
	v_exp_f32_e32 v5, v5
	v_cndmask_b32_e64 v6, 0, v14, s[40:41]
	v_cndmask_b32_e32 v6, v14, v6, vcc
	v_cndmask_b32_e64 v20, 1.0, v4, s[40:41]
	v_add_f32_e32 v14, 1.0, v5
	v_rcp_f32_e32 v14, v14
	v_cndmask_b32_e32 v4, v4, v20, vcc
	v_mul_f32_e32 v20, v6, v2
	v_mul_f32_e32 v2, v4, v2
	v_mul_f32_e32 v4, v5, v14
	v_min_f32_e32 v5, 0x42ac0000, v19
	v_exp_f32_e32 v5, v5
	v_cndmask_b32_e64 v6, 0, v14, s[42:43]
	v_cndmask_b32_e32 v6, v14, v6, vcc
	v_cndmask_b32_e64 v19, 1.0, v4, s[42:43]
	v_add_f32_e32 v14, 1.0, v5
	v_rcp_f32_e32 v14, v14
	v_cndmask_b32_e32 v4, v4, v19, vcc
	v_mul_f32_e32 v19, v6, v2
	v_mul_f32_e32 v2, v4, v2
	v_mul_f32_e32 v4, v5, v14
	v_min_f32_e32 v5, 0x42ac0000, v18
	v_exp_f32_e32 v5, v5
	v_cndmask_b32_e64 v6, 0, v14, s[44:45]
	v_cndmask_b32_e32 v6, v14, v6, vcc
	v_cndmask_b32_e64 v18, 1.0, v4, s[44:45]
	v_add_f32_e32 v14, 1.0, v5
	v_rcp_f32_e32 v14, v14
	v_cndmask_b32_e32 v4, v4, v18, vcc
	v_mul_f32_e32 v18, v6, v2
	v_mul_f32_e32 v2, v4, v2
	v_mul_f32_e32 v4, v5, v14
	v_cndmask_b32_e64 v6, 1.0, v4, s[46:47]
	v_cndmask_b32_e64 v5, 0, v14, s[46:47]
	v_cndmask_b32_e32 v4, v4, v6, vcc
	v_cndmask_b32_e32 v5, v14, v5, vcc
	v_mul_f32_e32 v14, v4, v2
	v_mov_b32_e32 v22, v14
	s_nop 1
	s_nop 0
	v_permlane32_swap_b32_e32 v14, v22
	v_mul_f32_e32 v5, v5, v2
	v_cndmask_b32_e64 v2, 1.0, v22, s[10:11]
	v_mul_f32_e32 v6, v190, v2
	v_mul_f32_e32 v2, v5, v6
	v_mul_f32_e32 v4, v18, v6
	v_mul_f32_e32 v5, v19, v6
	v_mul_f32_e32 v18, v20, v6
	v_mul_f32_e32 v19, v21, v6
	v_mul_f32_e32 v17, v17, v6
	v_mul_f32_e32 v15, v15, v6
	v_mul_f32_e32 v20, v3, v6
	v_cvt_pk_bf16_f32 v2, v2, v4
	v_cvt_pk_bf16_f32 v3, v5, v18
	v_cvt_pk_bf16_f32 v4, v19, v17
	v_cvt_pk_bf16_f32 v5, v15, v20
	v_cndmask_b32_e64 v15, 0, v11, s[28:29]
	v_cndmask_b32_e32 v11, v11, v15, vcc
	s_waitcnt lgkmcnt(0)
	v_mfma_f32_32x32x16_bf16 v[66:81], v[158:161], v[2:5], v[66:81]
	v_mul_f32_e32 v11, v11, v13
	v_mul_f32_e32 v11, v11, v6
	v_mul_f32_e32 v12, v12, v6
	v_mul_f32_e32 v10, v10, v6
	v_mul_f32_e32 v9, v9, v6
	v_mfma_f32_32x32x16_bf16 v[50:65], v[154:157], v[2:5], v[50:65]
	v_mul_f32_e32 v2, v8, v6
	v_mul_f32_e32 v3, v7, v6
	v_mul_f32_e64 v4, v0, v6
	v_mul_f32_e64 v5, v1, v6
	v_cvt_pk_bf16_f32 v0, v11, v12
	v_cvt_pk_bf16_f32 v1, v10, v9
	v_cvt_pk_bf16_f32 v2, v2, v3
	v_cvt_pk_bf16_f32 v3, v4, v5
	v_mul_f32_e32 v4, v14, v22
	v_mul_f32_e32 v190, v190, v4
	v_mfma_f32_32x32x16_bf16 v[66:81], v[150:153], v[0:3], v[66:81]
	s_branch .Lsb_join_4
; DI unsigned pk2(float lo, float hi) { f32x2 v = {lo, hi}; bf2_t r = __builtin_convertvector(v, bf2_t); return __builtin_bit_cast(unsigned, r); }
; DI void xhalf(float x, float& lo, float& hi) { const u32x2p r = __builtin_amdgcn_permlane32_swap(__float_as_uint(x), __float_as_uint(x), false, false); lo = __uint_as_float(r.x); hi = __uint_as_float(r.y); }
; #define MFMA32(a, b, c) __builtin_amdgcn_mfma_f32_32x32x16_bf16((a), (b), (c), 0, 0, 0)
; DI void sb_block2(const Params& p, LAS unsigned char* lds, int bh, int qb2, int tid) {
;     ...
;                             for (int i = 15; i >= 0; --i) {
;                                 const float w = __builtin_amdgcn_exp2f(fminf(z[i], 86.f));
;                                 float be = __builtin_amdgcn_rcpf(1.f + w);
;                                 float om = w * be;
;                                 if (diag) { const bool valid = (16 * h + i < r); be = valid ? be : 0.f; om = valid ? om : 1.f; }
;                                 a[i] = be * tot;
;                                 tot *= om;
;                             }
;                             float tlo, thi; xhalf(tot, tlo, thi);
;                             const float bs = carry[g] * (h == 0 ? thi : 1.f);
;                             carry[g] *= tlo * thi;
; #pragma unroll
;                             for (int i = 0; i < 16; ++i) a[i] *= bs;
;                             bf16x8 pf[2];
; #pragma unroll
;                             for (int s2 = 0; s2 < 2; ++s2) {
;                                 u32x4 w; w.x = pk2(a[8 * s2 + 0], a[8 * s2 + 1]); w.y = pk2(a[8 * s2 + 2], a[8 * s2 + 3]); w.z = pk2(a[8 * s2 + 4], a[8 * s2 + 5]); w.w = pk2(a[8 * s2 + 6], a[8 * s2 + 7]);
;                                 pf[s2] = __builtin_bit_cast(bf16x8, w);
;                             }
; #pragma unroll
;                             for (int s2 = 0; s2 < 2; ++s2) { o0[g] = MFMA32(vf[s2], pf[s2], o0[g]); o1[g] = MFMA32(vf[2 + s2], pf[s2], o1[g]); }
;                             if (__all(carry[g] < SB_PTHR)) done[g] = true;
.Lsb_lean_4:
	v_min_f32_e32 v0, 0x42ac0000, v33
	v_exp_f32_e32 v0, v0
	v_min_f32_e32 v1, 0x42ac0000, v32
	v_exp_f32_e32 v2, v1
	v_add_f32_e32 v1, 1.0, v0
	v_rcp_f32_e32 v1, v1
	v_add_f32_e32 v3, 1.0, v2
	v_rcp_f32_e32 v3, v3
	v_mul_f32_e32 v0, v0, v1
	v_mov_b32_e32 v4, v0
	v_mul_f32_e32 v0, v2, v3
	v_min_f32_e32 v2, 0x42ac0000, v31
	v_exp_f32_e32 v2, v2
	v_mov_b32_e32 v6, v0
	v_add_f32_e32 v5, 1.0, v2
	v_mul_f32_e32 v0, v3, v4
	v_mul_f32_e32 v3, v4, v6
	v_rcp_f32_e32 v5, v5
	v_min_f32_e32 v4, 0x42ac0000, v30
	v_exp_f32_e32 v4, v4
	v_mul_f32_e32 v2, v2, v5
	v_add_f32_e32 v6, 1.0, v4
	v_rcp_f32_e32 v6, v6
	v_mul_f32_e32 v7, v5, v3
	v_mul_f32_e32 v2, v2, v3
	v_mul_f32_e32 v3, v4, v6
	v_min_f32_e32 v4, 0x42ac0000, v29
	v_exp_f32_e32 v4, v4
	v_mov_b32_e32 v5, v6
	v_add_f32_e32 v6, 1.0, v4
	v_rcp_f32_e32 v6, v6
	v_mul_f32_e32 v8, v5, v2
	v_mul_f32_e32 v2, v3, v2
	v_mul_f32_e32 v3, v4, v6
	v_min_f32_e32 v4, 0x42ac0000, v28
	v_exp_f32_e32 v4, v4
	v_mov_b32_e32 v5, v6
	v_add_f32_e32 v6, 1.0, v4
	v_rcp_f32_e32 v6, v6
	v_mul_f32_e32 v9, v5, v2
	v_mul_f32_e32 v2, v3, v2
	v_mul_f32_e32 v3, v4, v6
	v_min_f32_e32 v4, 0x42ac0000, v27
	v_exp_f32_e32 v4, v4
	v_mov_b32_e32 v5, v6
	v_add_f32_e32 v6, 1.0, v4
	v_mul_f32_e32 v10, v5, v2
	v_rcp_f32_e32 v6, v6
	v_min_f32_e32 v5, 0x42ac0000, v26
	v_exp_f32_e32 v5, v5
	v_mul_f32_e32 v2, v3, v2
	v_mul_f32_e32 v3, v4, v6
	v_mov_b32_e32 v4, v6
	v_add_f32_e32 v6, 1.0, v5
	v_rcp_f32_e32 v11, v6
	v_min_f32_e32 v6, 0x42ac0000, v25
	v_exp_f32_e32 v6, v6
	v_mul_f32_e32 v12, v4, v2
	v_mul_f32_e32 v13, v3, v2
	v_mul_f32_e32 v2, v5, v11
	v_add_f32_e32 v3, 1.0, v6
	v_rcp_f32_e32 v3, v3
	v_min_f32_e32 v5, 0x42ac0000, v24
	v_exp_f32_e32 v5, v5
	v_mul_f32_e32 v4, v6, v3
	v_add_f32_e32 v6, 1.0, v5
	v_rcp_f32_e32 v6, v6
	v_mul_f32_e32 v2, v2, v13
	v_mul_f32_e32 v3, v3, v2
	v_mul_f32_e32 v2, v4, v2
	v_mul_f32_e32 v4, v5, v6
	v_min_f32_e32 v5, 0x42ac0000, v23
	v_exp_f32_e32 v5, v5
	s_nop 0
	v_add_f32_e32 v14, 1.0, v5
	v_rcp_f32_e32 v14, v14
	v_mul_f32_e32 v15, v6, v2
	v_mul_f32_e32 v2, v4, v2
	v_mul_f32_e32 v4, v5, v14
	v_min_f32_e32 v5, 0x42ac0000, v22
	v_exp_f32_e32 v5, v5
	v_mov_b32_e32 v6, v14
	v_add_f32_e32 v14, 1.0, v5
	v_rcp_f32_e32 v14, v14
	v_mul_f32_e32 v17, v6, v2
	v_mul_f32_e32 v2, v4, v2
	v_mul_f32_e32 v4, v5, v14
	v_min_f32_e32 v5, 0x42ac0000, v21
	v_exp_f32_e32 v5, v5
	v_mov_b32_e32 v6, v14
	v_add_f32_e32 v14, 1.0, v5
	v_rcp_f32_e32 v14, v14
	v_mul_f32_e32 v21, v6, v2
	v_mul_f32_e32 v2, v4, v2
	v_mul_f32_e32 v4, v5, v14
	v_min_f32_e32 v5, 0x42ac0000, v20
	v_exp_f32_e32 v5, v5
	v_mov_b32_e32 v6, v14
	v_add_f32_e32 v14, 1.0, v5
	v_rcp_f32_e32 v14, v14
	v_mul_f32_e32 v20, v6, v2
	v_mul_f32_e32 v2, v4, v2
	v_mul_f32_e32 v4, v5, v14
	v_min_f32_e32 v5, 0x42ac0000, v19
	v_exp_f32_e32 v5, v5
	v_mov_b32_e32 v6, v14
	v_add_f32_e32 v14, 1.0, v5
	v_rcp_f32_e32 v14, v14
	v_mul_f32_e32 v19, v6, v2
	v_mul_f32_e32 v2, v4, v2
	v_mul_f32_e32 v4, v5, v14
	v_min_f32_e32 v5, 0x42ac0000, v18
	v_exp_f32_e32 v5, v5
	v_mov_b32_e32 v6, v14
	v_add_f32_e32 v14, 1.0, v5
	v_rcp_f32_e32 v14, v14
	v_mul_f32_e32 v18, v6, v2
	v_mul_f32_e32 v2, v4, v2
	v_mul_f32_e32 v4, v5, v14
	v_mov_b32_e32 v5, v14
	v_mul_f32_e32 v14, v4, v2
	v_mov_b32_e32 v22, v14
	s_nop 1
	s_nop 0
	v_permlane32_swap_b32_e32 v14, v22
	v_mul_f32_e32 v5, v5, v2
	v_cndmask_b32_e64 v2, 1.0, v22, s[10:11]
	v_mul_f32_e32 v6, v190, v2
	v_mul_f32_e32 v2, v5, v6
	v_mul_f32_e32 v4, v18, v6
	v_mul_f32_e32 v5, v19, v6
	v_mul_f32_e32 v18, v20, v6
	v_mul_f32_e32 v19, v21, v6
	v_mul_f32_e32 v17, v17, v6
	v_mul_f32_e32 v15, v15, v6
	v_mul_f32_e32 v20, v3, v6
	v_cvt_pk_bf16_f32 v2, v2, v4
	v_cvt_pk_bf16_f32 v3, v5, v18
	v_cvt_pk_bf16_f32 v4, v19, v17
	v_cvt_pk_bf16_f32 v5, v15, v20
	v_cndmask_b32_e64 v15, 0, v11, s[28:29]
	s_waitcnt lgkmcnt(0)
	v_mfma_f32_32x32x16_bf16 v[66:81], v[158:161], v[2:5], v[66:81]
	v_mul_f32_e32 v11, v11, v13
	v_mul_f32_e32 v11, v11, v6
	v_mul_f32_e32 v12, v12, v6
	v_mul_f32_e32 v10, v10, v6
	v_mul_f32_e32 v9, v9, v6
	v_mfma_f32_32x32x16_bf16 v[50:65], v[154:157], v[2:5], v[50:65]
	v_mul_f32_e32 v2, v8, v6
	v_mul_f32_e32 v3, v7, v6
	v_mul_f32_e64 v4, v0, v6
	v_mul_f32_e64 v5, v1, v6
	v_cvt_pk_bf16_f32 v0, v11, v12
	v_cvt_pk_bf16_f32 v1, v10, v9
	v_cvt_pk_bf16_f32 v2, v2, v3
	v_cvt_pk_bf16_f32 v3, v4, v5
	v_mul_f32_e32 v4, v14, v22
	v_mul_f32_e32 v190, v190, v4
	v_mfma_f32_32x32x16_bf16 v[66:81], v[150:153], v[0:3], v[66:81]
.Lsb_join_4:
	v_cmp_gt_f32_e32 vcc, s68, v190
	s_cmp_eq_u64 vcc, exec
	s_cselect_b64 s[62:63], -1, 0
	v_mfma_f32_32x32x16_bf16 v[50:65], v[146:149], v[0:3], v[50:65]
	s_and_b64 vcc, exec, s[48:49]
	s_cbranch_vccz .LBB0_921
	s_branch .LBB0_922

; DI unsigned pk2(float lo, float hi) { f32x2 v = {lo, hi}; bf2_t r = __builtin_convertvector(v, bf2_t); return __builtin_bit_cast(unsigned, r); }
; DI void xhalf(float x, float& lo, float& hi) { const u32x2p r = __builtin_amdgcn_permlane32_swap(__float_as_uint(x), __float_as_uint(x), false, false); lo = __uint_as_float(r.x); hi = __uint_as_float(r.y); }
; #define MFMA32(a, b, c) __builtin_amdgcn_mfma_f32_32x32x16_bf16((a), (b), (c), 0, 0, 0)
; DI void sb_block2(const Params& p, LAS unsigned char* lds, int bh, int qb2, int tid) {
;     ...
;                             for (int i = 15; i >= 0; --i) {
;                                 const float w = __builtin_amdgcn_exp2f(fminf(z[i], 86.f));
;                                 float be = __builtin_amdgcn_rcpf(1.f + w);
;                                 float om = w * be;
;                                 if (diag) { const bool valid = (16 * h + i < r); be = valid ? be : 0.f; om = valid ? om : 1.f; }
;                                 a[i] = be * tot;
;                                 tot *= om;
;                             }
;                             float tlo, thi; xhalf(tot, tlo, thi);
;                             const float bs = carry[g] * (h == 0 ? thi : 1.f);
;                             carry[g] *= tlo * thi;
; #pragma unroll
;                             for (int i = 0; i < 16; ++i) a[i] *= bs;
;                             bf16x8 pf[2];
; #pragma unroll
;                             for (int s2 = 0; s2 < 2; ++s2) {
;                                 u32x4 w; w.x = pk2(a[8 * s2 + 0], a[8 * s2 + 1]); w.y = pk2(a[8 * s2 + 2], a[8 * s2 + 3]); w.z = pk2(a[8 * s2 + 4], a[8 * s2 + 5]); w.w = pk2(a[8 * s2 + 6], a[8 * s2 + 7]);
;                                 pf[s2] = __builtin_bit_cast(bf16x8, w);
;                             }
; #pragma unroll
;                             for (int s2 = 0; s2 < 2; ++s2) { o0[g] = MFMA32(vf[s2], pf[s2], o0[g]); o1[g] = MFMA32(vf[2 + s2], pf[s2], o1[g]); }
;                             if (__all(carry[g] < SB_PTHR)) done[g] = true;
.LBB0_932:
	s_cmp_eq_u32 s76, s79
	s_cbranch_scc0 .Lsb_lean_5
	v_min_f32_e32 v0, 0x42ac0000, v33
	v_exp_f32_e32 v0, v0
	v_min_f32_e32 v1, 0x42ac0000, v32
	v_exp_f32_e32 v2, v1
	v_add_f32_e32 v1, 1.0, v0
	v_rcp_f32_e32 v1, v1
	s_cmp_eq_u32 s76, s79
	v_add_f32_e32 v3, 1.0, v2
	v_rcp_f32_e32 v3, v3
	v_mul_f32_e32 v0, v0, v1
	v_cndmask_b32_e64 v4, 0, v1, s[14:15]
	v_cndmask_b32_e64 v5, 1.0, v0, s[14:15]
	s_cselect_b64 vcc, -1, 0
	v_cndmask_b32_e32 v1, v1, v4, vcc
	v_cndmask_b32_e32 v4, v0, v5, vcc
	v_mul_f32_e32 v0, v2, v3
	v_min_f32_e32 v2, 0x42ac0000, v31
	v_exp_f32_e32 v2, v2
	v_cndmask_b32_e64 v5, 0, v3, s[16:17]
	v_cndmask_b32_e64 v6, 1.0, v0, s[16:17]
	v_cndmask_b32_e32 v3, v3, v5, vcc
	v_cndmask_b32_e32 v6, v0, v6, vcc
	v_add_f32_e32 v5, 1.0, v2
	v_mul_f32_e32 v0, v3, v4
	v_mul_f32_e32 v3, v4, v6
	v_rcp_f32_e32 v5, v5
	v_min_f32_e32 v4, 0x42ac0000, v30
	v_exp_f32_e32 v4, v4
	v_cndmask_b32_e64 v6, 0, v5, s[18:19]
	v_mul_f32_e32 v2, v2, v5
	v_cndmask_b32_e32 v5, v5, v6, vcc
	v_add_f32_e32 v6, 1.0, v4
	v_rcp_f32_e32 v6, v6
	v_cndmask_b32_e64 v7, 1.0, v2, s[18:19]
	v_cndmask_b32_e32 v2, v2, v7, vcc
	v_mul_f32_e32 v7, v5, v3
	v_mul_f32_e32 v2, v2, v3
	v_mul_f32_e32 v3, v4, v6
	v_min_f32_e32 v4, 0x42ac0000, v29
	v_exp_f32_e32 v4, v4
	v_cndmask_b32_e64 v5, 0, v6, s[20:21]
	v_cndmask_b32_e32 v5, v6, v5, vcc
	v_cndmask_b32_e64 v8, 1.0, v3, s[20:21]
	v_add_f32_e32 v6, 1.0, v4
	v_rcp_f32_e32 v6, v6
	v_cndmask_b32_e32 v3, v3, v8, vcc
	v_mul_f32_e32 v8, v5, v2
	v_mul_f32_e32 v2, v3, v2
	v_mul_f32_e32 v3, v4, v6
	v_min_f32_e32 v4, 0x42ac0000, v28
	v_exp_f32_e32 v4, v4
	v_cndmask_b32_e64 v5, 0, v6, s[22:23]
	v_cndmask_b32_e32 v5, v6, v5, vcc
	v_cndmask_b32_e64 v9, 1.0, v3, s[22:23]
	v_add_f32_e32 v6, 1.0, v4
	v_rcp_f32_e32 v6, v6
	v_cndmask_b32_e32 v3, v3, v9, vcc
	v_mul_f32_e32 v9, v5, v2
	v_mul_f32_e32 v2, v3, v2
	v_mul_f32_e32 v3, v4, v6
	v_min_f32_e32 v4, 0x42ac0000, v27
	v_exp_f32_e32 v4, v4
	v_cndmask_b32_e64 v5, 0, v6, s[24:25]
	v_cndmask_b32_e64 v10, 1.0, v3, s[24:25]
	v_cndmask_b32_e32 v5, v6, v5, vcc
	v_add_f32_e32 v6, 1.0, v4
	v_cndmask_b32_e32 v3, v3, v10, vcc
	v_mul_f32_e32 v10, v5, v2
	v_rcp_f32_e32 v6, v6
	v_min_f32_e32 v5, 0x42ac0000, v26
	v_exp_f32_e32 v5, v5
	v_mul_f32_e32 v2, v3, v2
	v_mul_f32_e32 v3, v4, v6
	v_cndmask_b32_e64 v4, 0, v6, s[26:27]
	v_cndmask_b32_e64 v11, 1.0, v3, s[26:27]
	v_cndmask_b32_e32 v4, v6, v4, vcc
	v_add_f32_e32 v6, 1.0, v5
	v_cndmask_b32_e32 v3, v3, v11, vcc
	v_rcp_f32_e32 v11, v6
	v_min_f32_e32 v6, 0x42ac0000, v25
	v_exp_f32_e32 v6, v6
	v_mul_f32_e32 v12, v4, v2
	v_mul_f32_e32 v13, v3, v2
	v_mul_f32_e32 v2, v5, v11
	v_add_f32_e32 v3, 1.0, v6
	v_rcp_f32_e32 v3, v3
	v_min_f32_e32 v5, 0x42ac0000, v24
	v_exp_f32_e32 v5, v5
	v_cndmask_b32_e64 v4, 1.0, v2, s[28:29]
	v_cndmask_b32_e32 v2, v2, v4, vcc
	v_mul_f32_e32 v4, v6, v3
	v_cndmask_b32_e64 v6, 0, v3, s[30:31]
	v_cndmask_b32_e32 v3, v3, v6, vcc
	v_add_f32_e32 v6, 1.0, v5
	v_rcp_f32_e32 v6, v6
	v_cndmask_b32_e64 v14, 1.0, v4, s[30:31]
	v_mul_f32_e32 v2, v2, v13
	v_cndmask_b32_e32 v4, v4, v14, vcc
	v_mul_f32_e32 v3, v3, v2
	v_mul_f32_e32 v2, v4, v2
	v_mul_f32_e32 v4, v5, v6
	v_min_f32_e32 v5, 0x42ac0000, v23
	v_exp_f32_e32 v5, v5
	v_cndmask_b32_e64 v14, 0, v6, s[34:35]
	v_cndmask_b32_e32 v6, v6, v14, vcc
	v_cndmask_b32_e64 v15, 1.0, v4, s[34:35]
	v_add_f32_e32 v14, 1.0, v5
	v_rcp_f32_e32 v14, v14
	v_cndmask_b32_e32 v4, v4, v15, vcc
	v_mul_f32_e32 v15, v6, v2
	v_mul_f32_e32 v2, v4, v2
	v_mul_f32_e32 v4, v5, v14
	v_min_f32_e32 v5, 0x42ac0000, v22
	v_exp_f32_e32 v5, v5
	v_cndmask_b32_e64 v6, 0, v14, s[36:37]
	v_cndmask_b32_e32 v6, v14, v6, vcc
	v_cndmask_b32_e64 v17, 1.0, v4, s[36:37]
	v_add_f32_e32 v14, 1.0, v5
	v_rcp_f32_e32 v14, v14
	v_cndmask_b32_e32 v4, v4, v17, vcc
	v_mul_f32_e32 v17, v6, v2
	v_mul_f32_e32 v2, v4, v2
	v_mul_f32_e32 v4, v5, v14
	v_min_f32_e32 v5, 0x42ac0000, v21
	v_exp_f32_e32 v5, v5
	v_cndmask_b32_e64 v6, 0, v14, s[38:39]
	v_cndmask_b32_e32 v6, v14, v6, vcc
	v_cndmask_b32_e64 v21, 1.0, v4, s[38:39]
	v_add_f32_e32 v14, 1.0, v5
	v_rcp_f32_e32 v14, v14
	v_cndmask_b32_e32 v4, v4, v21, vcc
	v_mul_f32_e32 v21, v6, v2
	v_mul_f32_e32 v2, v4, v2
	v_mul_f32_e32 v4, v5, v14
	v_min_f32_e32 v5, 0x42ac0000, v20
	v_exp_f32_e32 v5, v5
	v_cndmask_b32_e64 v6, 0, v14, s[40:41]
	v_cndmask_b32_e32 v6, v14, v6, vcc
	v_cndmask_b32_e64 v20, 1.0, v4, s[40:41]
	v_add_f32_e32 v14, 1.0, v5
	v_rcp_f32_e32 v14, v14
	v_cndmask_b32_e32 v4, v4, v20, vcc
	v_mul_f32_e32 v20, v6, v2
	v_mul_f32_e32 v2, v4, v2
	v_mul_f32_e32 v4, v5, v14
	v_min_f32_e32 v5, 0x42ac0000, v19
	v_exp_f32_e32 v5, v5
	v_cndmask_b32_e64 v6, 0, v14, s[42:43]
	v_cndmask_b32_e32 v6, v14, v6, vcc
	v_cndmask_b32_e64 v19, 1.0, v4, s[42:43]
	v_add_f32_e32 v14, 1.0, v5
	v_rcp_f32_e32 v14, v14
	v_cndmask_b32_e32 v4, v4, v19, vcc
	v_mul_f32_e32 v19, v6, v2
	v_mul_f32_e32 v2, v4, v2
	v_mul_f32_e32 v4, v5, v14
	v_min_f32_e32 v5, 0x42ac0000, v18
	v_exp_f32_e32 v5, v5
	v_cndmask_b32_e64 v6, 0, v14, s[44:45]
	v_cndmask_b32_e32 v6, v14, v6, vcc
	v_cndmask_b32_e64 v18, 1.0, v4, s[44:45]
	v_add_f32_e32 v14, 1.0, v5
	v_rcp_f32_e32 v14, v14
	v_cndmask_b32_e32 v4, v4, v18, vcc
	v_mul_f32_e32 v18, v6, v2
	v_mul_f32_e32 v2, v4, v2
	v_mul_f32_e32 v4, v5, v14
	v_cndmask_b32_e64 v6, 1.0, v4, s[46:47]
	v_cndmask_b32_e64 v5, 0, v14, s[46:47]
	v_cndmask_b32_e32 v4, v4, v6, vcc
	v_cndmask_b32_e32 v5, v14, v5, vcc
	v_mul_f32_e32 v14, v4, v2
	v_mov_b32_e32 v22, v14
	s_nop 1
	s_nop 0
	v_permlane32_swap_b32_e32 v14, v22
	v_mul_f32_e32 v5, v5, v2
	v_cndmask_b32_e64 v2, 1.0, v22, s[10:11]
	v_mul_f32_e32 v6, v190, v2
	v_mul_f32_e32 v2, v5, v6
	v_mul_f32_e32 v4, v18, v6
	v_mul_f32_e32 v5, v19, v6
	v_mul_f32_e32 v18, v20, v6
	v_mul_f32_e32 v19, v21, v6
	v_mul_f32_e32 v17, v17, v6
	v_mul_f32_e32 v15, v15, v6
	v_mul_f32_e32 v20, v3, v6
	v_cvt_pk_bf16_f32 v2, v2, v4
	v_cvt_pk_bf16_f32 v3, v5, v18
	v_cvt_pk_bf16_f32 v4, v19, v17
	v_cvt_pk_bf16_f32 v5, v15, v20
	v_cndmask_b32_e64 v15, 0, v11, s[28:29]
	v_cndmask_b32_e32 v11, v11, v15, vcc
	s_waitcnt lgkmcnt(0)
	v_mfma_f32_32x32x16_bf16 v[66:81], v[158:161], v[2:5], v[66:81]
	v_mul_f32_e32 v11, v11, v13
	v_mul_f32_e32 v11, v11, v6
	v_mul_f32_e32 v12, v12, v6
	v_mul_f32_e32 v10, v10, v6
	v_mul_f32_e32 v9, v9, v6
	v_mfma_f32_32x32x16_bf16 v[50:65], v[154:157], v[2:5], v[50:65]
	v_mul_f32_e32 v2, v8, v6
	v_mul_f32_e32 v3, v7, v6
	v_mul_f32_e64 v4, v0, v6
	v_mul_f32_e64 v5, v1, v6
	v_cvt_pk_bf16_f32 v0, v11, v12
	v_cvt_pk_bf16_f32 v1, v10, v9
	v_cvt_pk_bf16_f32 v2, v2, v3
	v_cvt_pk_bf16_f32 v3, v4, v5
	v_mul_f32_e32 v4, v14, v22
	v_mul_f32_e32 v190, v190, v4
	v_mfma_f32_32x32x16_bf16 v[66:81], v[150:153], v[0:3], v[66:81]
	s_branch .Lsb_join_5

; DI unsigned pk2(float lo, float hi) { f32x2 v = {lo, hi}; bf2_t r = __builtin_convertvector(v, bf2_t); return __builtin_bit_cast(unsigned, r); }
; DI void xhalf(float x, float& lo, float& hi) { const u32x2p r = __builtin_amdgcn_permlane32_swap(__float_as_uint(x), __float_as_uint(x), false, false); lo = __uint_as_float(r.x); hi = __uint_as_float(r.y); }
; #define MFMA32(a, b, c) __builtin_amdgcn_mfma_f32_32x32x16_bf16((a), (b), (c), 0, 0, 0)
; DI void sb_block2(const Params& p, LAS unsigned char* lds, int bh, int qb2, int tid) {
;     ...
;                             for (int i = 15; i >= 0; --i) {
;                                 const float w = __builtin_amdgcn_exp2f(fminf(z[i], 86.f));
;                                 float be = __builtin_amdgcn_rcpf(1.f + w);
;                                 float om = w * be;
;                                 if (diag) { const bool valid = (16 * h + i < r); be = valid ? be : 0.f; om = valid ? om : 1.f; }
;                                 a[i] = be * tot;
;                                 tot *= om;
;                             }
;                             float tlo, thi; xhalf(tot, tlo, thi);
;                             const float bs = carry[g] * (h == 0 ? thi : 1.f);
;                             carry[g] *= tlo * thi;
; #pragma unroll
;                             for (int i = 0; i < 16; ++i) a[i] *= bs;
;                             bf16x8 pf[2];
; #pragma unroll
;                             for (int s2 = 0; s2 < 2; ++s2) {
;                                 u32x4 w; w.x = pk2(a[8 * s2 + 0], a[8 * s2 + 1]); w.y = pk2(a[8 * s2 + 2], a[8 * s2 + 3]); w.z = pk2(a[8 * s2 + 4], a[8 * s2 + 5]); w.w = pk2(a[8 * s2 + 6], a[8 * s2 + 7]);
;                                 pf[s2] = __builtin_bit_cast(bf16x8, w);
;                             }
; #pragma unroll
;                             for (int s2 = 0; s2 < 2; ++s2) { o0[g] = MFMA32(vf[s2], pf[s2], o0[g]); o1[g] = MFMA32(vf[2 + s2], pf[s2], o1[g]); }
;                             if (__all(carry[g] < SB_PTHR)) done[g] = true;
.Lsb_join_5:
	v_cmp_gt_f32_e32 vcc, s68, v190
	s_cmp_eq_u64 vcc, exec
	s_cselect_b64 s[62:63], -1, 0
	v_mfma_f32_32x32x16_bf16 v[50:65], v[146:149], v[0:3], v[50:65]
	s_and_b64 vcc, exec, s[48:49]
	s_cbranch_vccnz .LBB0_850
.LBB0_933:
	s_nop 6
	s_cmp_eq_u32 s74, s79
	s_cbranch_scc0 .Lsb_lean_6
	v_min_f32_e32 v0, 0x42ac0000, v49
	v_exp_f32_e32 v0, v0
	v_min_f32_e32 v1, 0x42ac0000, v48
	v_exp_f32_e32 v2, v1
	v_add_f32_e32 v1, 1.0, v0
	v_rcp_f32_e32 v1, v1
	s_cmp_eq_u32 s74, s79
	v_add_f32_e32 v3, 1.0, v2
	v_rcp_f32_e32 v3, v3
	v_mul_f32_e32 v0, v0, v1
	v_cndmask_b32_e64 v4, 0, v1, s[14:15]
	v_cndmask_b32_e64 v5, 1.0, v0, s[14:15]
	s_cselect_b64 vcc, -1, 0
	v_cndmask_b32_e32 v1, v1, v4, vcc
	v_cndmask_b32_e32 v4, v0, v5, vcc
	v_mul_f32_e32 v0, v2, v3
	v_min_f32_e32 v2, 0x42ac0000, v47
	v_exp_f32_e32 v2, v2
	v_cndmask_b32_e64 v5, 0, v3, s[16:17]
	v_cndmask_b32_e64 v6, 1.0, v0, s[16:17]
	v_cndmask_b32_e32 v3, v3, v5, vcc
	v_cndmask_b32_e32 v6, v0, v6, vcc
	v_add_f32_e32 v5, 1.0, v2
	v_mul_f32_e32 v0, v3, v4
	v_mul_f32_e32 v3, v4, v6
	v_rcp_f32_e32 v5, v5
	v_min_f32_e32 v4, 0x42ac0000, v46
	v_exp_f32_e32 v4, v4
	v_cndmask_b32_e64 v6, 0, v5, s[18:19]
	v_mul_f32_e32 v2, v2, v5
	v_cndmask_b32_e32 v5, v5, v6, vcc
	v_add_f32_e32 v6, 1.0, v4
	v_rcp_f32_e32 v6, v6
	v_cndmask_b32_e64 v7, 1.0, v2, s[18:19]
	v_cndmask_b32_e32 v2, v2, v7, vcc
	v_mul_f32_e32 v7, v5, v3
	v_mul_f32_e32 v2, v2, v3
	v_mul_f32_e32 v3, v4, v6
	v_min_f32_e32 v4, 0x42ac0000, v45
	v_exp_f32_e32 v4, v4
	v_cndmask_b32_e64 v5, 0, v6, s[20:21]
	v_cndmask_b32_e32 v5, v6, v5, vcc
	v_cndmask_b32_e64 v8, 1.0, v3, s[20:21]
	v_add_f32_e32 v6, 1.0, v4
	v_rcp_f32_e32 v6, v6
	v_cndmask_b32_e32 v3, v3, v8, vcc
	v_mul_f32_e32 v8, v5, v2
	v_mul_f32_e32 v2, v3, v2
	v_mul_f32_e32 v3, v4, v6
	v_min_f32_e32 v4, 0x42ac0000, v44
	v_exp_f32_e32 v4, v4
	v_cndmask_b32_e64 v5, 0, v6, s[22:23]
	v_cndmask_b32_e32 v5, v6, v5, vcc
	v_cndmask_b32_e64 v9, 1.0, v3, s[22:23]
	v_add_f32_e32 v6, 1.0, v4
	v_rcp_f32_e32 v6, v6
	v_cndmask_b32_e32 v3, v3, v9, vcc
	v_mul_f32_e32 v9, v5, v2
	v_mul_f32_e32 v2, v3, v2
	v_mul_f32_e32 v3, v4, v6
	v_min_f32_e32 v4, 0x42ac0000, v43
	v_exp_f32_e32 v4, v4
	v_cndmask_b32_e64 v5, 0, v6, s[24:25]
	v_cndmask_b32_e64 v10, 1.0, v3, s[24:25]
	v_cndmask_b32_e32 v5, v6, v5, vcc
	v_add_f32_e32 v6, 1.0, v4
	v_cndmask_b32_e32 v3, v3, v10, vcc
	v_mul_f32_e32 v10, v5, v2
	v_rcp_f32_e32 v6, v6
	v_min_f32_e32 v5, 0x42ac0000, v42
	v_exp_f32_e32 v5, v5
	v_mul_f32_e32 v2, v3, v2
	v_mul_f32_e32 v3, v4, v6
	v_cndmask_b32_e64 v4, 0, v6, s[26:27]
	v_cndmask_b32_e64 v11, 1.0, v3, s[26:27]
	v_cndmask_b32_e32 v4, v6, v4, vcc
	v_add_f32_e32 v6, 1.0, v5
	v_cndmask_b32_e32 v3, v3, v11, vcc
	v_rcp_f32_e32 v11, v6
	v_min_f32_e32 v6, 0x42ac0000, v41
	v_exp_f32_e32 v6, v6
	v_mul_f32_e32 v12, v4, v2
	v_mul_f32_e32 v13, v3, v2
	v_mul_f32_e32 v2, v5, v11
	v_add_f32_e32 v3, 1.0, v6
	v_rcp_f32_e32 v3, v3
	v_min_f32_e32 v5, 0x42ac0000, v40
	v_exp_f32_e32 v5, v5
	v_cndmask_b32_e64 v4, 1.0, v2, s[28:29]
	v_cndmask_b32_e32 v2, v2, v4, vcc
	v_mul_f32_e32 v4, v6, v3
	v_cndmask_b32_e64 v6, 0, v3, s[30:31]
	v_cndmask_b32_e32 v3, v3, v6, vcc
	v_add_f32_e32 v6, 1.0, v5
	v_rcp_f32_e32 v6, v6
	v_cndmask_b32_e64 v14, 1.0, v4, s[30:31]
	v_mul_f32_e32 v2, v2, v13
	v_cndmask_b32_e32 v4, v4, v14, vcc
	v_mul_f32_e32 v3, v3, v2
	v_mul_f32_e32 v2, v4, v2
	v_mul_f32_e32 v4, v5, v6
	v_min_f32_e32 v5, 0x42ac0000, v39
	v_exp_f32_e32 v5, v5
	v_cndmask_b32_e64 v14, 0, v6, s[34:35]
	v_cndmask_b32_e32 v6, v6, v14, vcc
	v_cndmask_b32_e64 v15, 1.0, v4, s[34:35]
	v_add_f32_e32 v14, 1.0, v5
	v_rcp_f32_e32 v14, v14
	v_cndmask_b32_e32 v4, v4, v15, vcc
	v_mul_f32_e32 v15, v6, v2
	v_mul_f32_e32 v2, v4, v2
	v_mul_f32_e32 v4, v5, v14
	v_min_f32_e32 v5, 0x42ac0000, v38
	v_exp_f32_e32 v5, v5
	v_cndmask_b32_e64 v6, 0, v14, s[36:37]
	v_cndmask_b32_e32 v6, v14, v6, vcc
	v_cndmask_b32_e64 v17, 1.0, v4, s[36:37]
	v_add_f32_e32 v14, 1.0, v5
	v_rcp_f32_e32 v14, v14
	v_cndmask_b32_e32 v4, v4, v17, vcc
	v_mul_f32_e32 v17, v6, v2
	v_mul_f32_e32 v2, v4, v2
	v_mul_f32_e32 v4, v5, v14
	v_min_f32_e32 v5, 0x42ac0000, v37
	v_exp_f32_e32 v5, v5
	v_cndmask_b32_e64 v6, 0, v14, s[38:39]
	v_cndmask_b32_e32 v6, v14, v6, vcc
	v_cndmask_b32_e64 v18, 1.0, v4, s[38:39]
	v_add_f32_e32 v14, 1.0, v5
	v_rcp_f32_e32 v14, v14
	v_cndmask_b32_e32 v4, v4, v18, vcc
	v_mul_f32_e32 v18, v6, v2
	v_mul_f32_e32 v2, v4, v2
	v_mul_f32_e32 v4, v5, v14
	v_min_f32_e32 v5, 0x42ac0000, v36
	v_exp_f32_e32 v5, v5
	v_cndmask_b32_e64 v6, 0, v14, s[40:41]
	v_cndmask_b32_e32 v6, v14, v6, vcc
	v_cndmask_b32_e64 v19, 1.0, v4, s[40:41]
	v_add_f32_e32 v14, 1.0, v5
	v_rcp_f32_e32 v14, v14
	v_cndmask_b32_e32 v4, v4, v19, vcc
	v_mul_f32_e32 v19, v6, v2
	v_mul_f32_e32 v2, v4, v2
	v_mul_f32_e32 v4, v5, v14
	v_min_f32_e32 v5, 0x42ac0000, v35
	v_exp_f32_e32 v5, v5
	v_cndmask_b32_e64 v6, 0, v14, s[42:43]
	v_cndmask_b32_e32 v6, v14, v6, vcc
	v_cndmask_b32_e64 v20, 1.0, v4, s[42:43]
	v_add_f32_e32 v14, 1.0, v5
	v_rcp_f32_e32 v14, v14
	v_cndmask_b32_e32 v4, v4, v20, vcc
	v_mul_f32_e32 v20, v6, v2
	v_mul_f32_e32 v2, v4, v2
	v_mul_f32_e32 v4, v5, v14
	v_min_f32_e32 v5, 0x42ac0000, v34
	v_exp_f32_e32 v5, v5
	v_cndmask_b32_e64 v6, 0, v14, s[44:45]
	v_cndmask_b32_e32 v6, v14, v6, vcc
	v_cndmask_b32_e64 v21, 1.0, v4, s[44:45]
	v_add_f32_e32 v14, 1.0, v5
	v_rcp_f32_e32 v14, v14
	v_cndmask_b32_e32 v4, v4, v21, vcc
	v_mul_f32_e32 v21, v6, v2
	v_mul_f32_e32 v2, v4, v2
	v_mul_f32_e32 v4, v5, v14
	v_cndmask_b32_e64 v6, 1.0, v4, s[46:47]
	v_cndmask_b32_e64 v5, 0, v14, s[46:47]
	v_cndmask_b32_e32 v4, v4, v6, vcc
	v_cndmask_b32_e32 v5, v14, v5, vcc
	v_mul_f32_e32 v14, v4, v2
	v_mov_b32_e32 v22, v14
	s_nop 1
	s_nop 0
	v_permlane32_swap_b32_e32 v14, v22
	v_mul_f32_e32 v5, v5, v2
	v_cndmask_b32_e64 v2, 1.0, v22, s[10:11]
	v_mul_f32_e32 v6, v191, v2
	v_mul_f32_e32 v2, v5, v6
	v_mul_f32_e32 v4, v21, v6
	v_mul_f32_e32 v5, v20, v6
	v_mul_f32_e32 v19, v19, v6
	v_mul_f32_e32 v18, v18, v6
	v_mul_f32_e32 v17, v17, v6
	v_mul_f32_e32 v15, v15, v6
	v_mul_f32_e32 v20, v3, v6
	v_cvt_pk_bf16_f32 v2, v2, v4
	v_cvt_pk_bf16_f32 v3, v5, v19
	v_cvt_pk_bf16_f32 v4, v18, v17
	v_cvt_pk_bf16_f32 v5, v15, v20
	v_cndmask_b32_e64 v15, 0, v11, s[28:29]
	v_cndmask_b32_e32 v11, v11, v15, vcc
	s_waitcnt lgkmcnt(0)
	v_mfma_f32_32x32x16_bf16 v[98:113], v[158:161], v[2:5], v[98:113]
	v_mul_f32_e32 v11, v11, v13
	v_mul_f32_e32 v11, v11, v6
	v_mul_f32_e32 v12, v12, v6
	v_mul_f32_e32 v10, v10, v6
	v_mul_f32_e32 v9, v9, v6
	v_mfma_f32_32x32x16_bf16 v[82:97], v[154:157], v[2:5], v[82:97]
	v_mul_f32_e32 v2, v8, v6
	v_mul_f32_e32 v3, v7, v6
	v_mul_f32_e64 v4, v0, v6
	v_mul_f32_e64 v5, v1, v6
	v_cvt_pk_bf16_f32 v0, v11, v12
	v_cvt_pk_bf16_f32 v1, v10, v9
	v_cvt_pk_bf16_f32 v2, v2, v3
	v_cvt_pk_bf16_f32 v3, v4, v5
	v_mul_f32_e32 v4, v14, v22
	v_mul_f32_e32 v191, v191, v4
	v_mfma_f32_32x32x16_bf16 v[98:113], v[150:153], v[0:3], v[98:113]
	s_branch .Lsb_join_6

; #define MFMA32(a, b, c) __builtin_amdgcn_mfma_f32_32x32x16_bf16((a), (b), (c), 0, 0, 0)
; DI void sb_block2(const Params& p, LAS unsigned char* lds, int bh, int qb2, int tid) {
;     ...
;                             for (int s2 = 0; s2 < 2; ++s2) { o0[g] = MFMA32(vf[s2], pf[s2], o0[g]); o1[g] = MFMA32(vf[2 + s2], pf[s2], o1[g]); }
;                             if (__all(carry[g] < SB_PTHR)) done[g] = true;
.Lsb_join_6:
	v_cmp_gt_f32_e32 vcc, s68, v191
	s_cmp_eq_u64 vcc, exec
	s_cselect_b64 s[0:1], -1, 0
	v_mfma_f32_32x32x16_bf16 v[82:97], v[146:149], v[0:3], v[82:97]
	v_cndmask_b32_e64 v0, 0, 1, s[0:1]
	s_nop 0
	v_readfirstlane_b32 s81, v0
	s_branch .LBB0_850

; DI unsigned pk2(float lo, float hi) { f32x2 v = {lo, hi}; bf2_t r = __builtin_convertvector(v, bf2_t); return __builtin_bit_cast(unsigned, r); }
; DI void xhalf(float x, float& lo, float& hi) { const u32x2p r = __builtin_amdgcn_permlane32_swap(__float_as_uint(x), __float_as_uint(x), false, false); lo = __uint_as_float(r.x); hi = __uint_as_float(r.y); }
; #define MFMA32(a, b, c) __builtin_amdgcn_mfma_f32_32x32x16_bf16((a), (b), (c), 0, 0, 0)
; DI void sb_block2(const Params& p, LAS unsigned char* lds, int bh, int qb2, int tid) {
;     ...
;                             for (int i = 15; i >= 0; --i) {
;                                 const float w = __builtin_amdgcn_exp2f(fminf(z[i], 86.f));
;                                 float be = __builtin_amdgcn_rcpf(1.f + w);
;                                 float om = w * be;
;                                 if (diag) { const bool valid = (16 * h + i < r); be = valid ? be : 0.f; om = valid ? om : 1.f; }
;                                 a[i] = be * tot;
;                                 tot *= om;
;                             }
;                             float tlo, thi; xhalf(tot, tlo, thi);
;                             const float bs = carry[g] * (h == 0 ? thi : 1.f);
;                             carry[g] *= tlo * thi;
; #pragma unroll
;                             for (int i = 0; i < 16; ++i) a[i] *= bs;
;                             bf16x8 pf[2];
; #pragma unroll
;                             for (int s2 = 0; s2 < 2; ++s2) {
;                                 u32x4 w; w.x = pk2(a[8 * s2 + 0], a[8 * s2 + 1]); w.y = pk2(a[8 * s2 + 2], a[8 * s2 + 3]); w.z = pk2(a[8 * s2 + 4], a[8 * s2 + 5]); w.w = pk2(a[8 * s2 + 6], a[8 * s2 + 7]);
;                                 pf[s2] = __builtin_bit_cast(bf16x8, w);
;                             }
; #pragma unroll
;                             for (int s2 = 0; s2 < 2; ++s2) { o0[g] = MFMA32(vf[s2], pf[s2], o0[g]); o1[g] = MFMA32(vf[2 + s2], pf[s2], o1[g]); }
;                             if (__all(carry[g] < SB_PTHR)) done[g] = true;
.LBB0_935:
	s_cmp_eq_u32 s59, s56
	s_cbranch_scc0 .Lsb_lean_7
	v_min_f32_e32 v0, 0x42ac0000, v33
	v_exp_f32_e32 v0, v0
	v_min_f32_e32 v1, 0x42ac0000, v32
	v_exp_f32_e32 v2, v1
	v_add_f32_e32 v1, 1.0, v0
	v_rcp_f32_e32 v1, v1
	s_cmp_eq_u32 s59, s56
	v_add_f32_e32 v3, 1.0, v2
	v_rcp_f32_e32 v3, v3
	v_mul_f32_e32 v0, v0, v1
	v_cndmask_b32_e64 v4, 0, v1, s[14:15]
	v_cndmask_b32_e64 v5, 1.0, v0, s[14:15]
	s_cselect_b64 vcc, -1, 0
	v_cndmask_b32_e32 v1, v1, v4, vcc
	v_cndmask_b32_e32 v4, v0, v5, vcc
	v_mul_f32_e32 v0, v2, v3
	v_min_f32_e32 v2, 0x42ac0000, v31
	v_exp_f32_e32 v2, v2
	v_cndmask_b32_e64 v5, 0, v3, s[16:17]
	v_cndmask_b32_e64 v6, 1.0, v0, s[16:17]
	v_cndmask_b32_e32 v3, v3, v5, vcc
	v_cndmask_b32_e32 v6, v0, v6, vcc
	v_add_f32_e32 v5, 1.0, v2
	v_mul_f32_e32 v0, v3, v4
	v_mul_f32_e32 v3, v4, v6
	v_rcp_f32_e32 v5, v5
	v_min_f32_e32 v4, 0x42ac0000, v30
	v_exp_f32_e32 v4, v4
	v_cndmask_b32_e64 v6, 0, v5, s[18:19]
	v_mul_f32_e32 v2, v2, v5
	v_cndmask_b32_e32 v5, v5, v6, vcc
	v_add_f32_e32 v6, 1.0, v4
	v_rcp_f32_e32 v6, v6
	v_cndmask_b32_e64 v7, 1.0, v2, s[18:19]
	v_cndmask_b32_e32 v2, v2, v7, vcc
	v_mul_f32_e32 v7, v5, v3
	v_mul_f32_e32 v2, v2, v3
	v_mul_f32_e32 v3, v4, v6
	v_min_f32_e32 v4, 0x42ac0000, v29
	v_exp_f32_e32 v4, v4
	v_cndmask_b32_e64 v5, 0, v6, s[20:21]
	v_cndmask_b32_e32 v5, v6, v5, vcc
	v_cndmask_b32_e64 v8, 1.0, v3, s[20:21]
	v_add_f32_e32 v6, 1.0, v4
	v_rcp_f32_e32 v6, v6
	v_cndmask_b32_e32 v3, v3, v8, vcc
	v_mul_f32_e32 v8, v5, v2
	v_mul_f32_e32 v2, v3, v2
	v_mul_f32_e32 v3, v4, v6
	v_min_f32_e32 v4, 0x42ac0000, v28
	v_exp_f32_e32 v4, v4
	v_cndmask_b32_e64 v5, 0, v6, s[22:23]
	v_cndmask_b32_e32 v5, v6, v5, vcc
	v_cndmask_b32_e64 v9, 1.0, v3, s[22:23]
	v_add_f32_e32 v6, 1.0, v4
	v_rcp_f32_e32 v6, v6
	v_cndmask_b32_e32 v3, v3, v9, vcc
	v_mul_f32_e32 v9, v5, v2
	v_mul_f32_e32 v2, v3, v2
	v_mul_f32_e32 v3, v4, v6
	v_min_f32_e32 v4, 0x42ac0000, v27
	v_exp_f32_e32 v4, v4
	v_cndmask_b32_e64 v5, 0, v6, s[24:25]
	v_cndmask_b32_e64 v10, 1.0, v3, s[24:25]
	v_cndmask_b32_e32 v5, v6, v5, vcc
	v_add_f32_e32 v6, 1.0, v4
	v_cndmask_b32_e32 v3, v3, v10, vcc
	v_mul_f32_e32 v10, v5, v2
	v_rcp_f32_e32 v6, v6
	v_min_f32_e32 v5, 0x42ac0000, v26
	v_exp_f32_e32 v5, v5
	v_mul_f32_e32 v2, v3, v2
	v_mul_f32_e32 v3, v4, v6
	v_cndmask_b32_e64 v4, 0, v6, s[26:27]
	v_cndmask_b32_e64 v11, 1.0, v3, s[26:27]
	v_cndmask_b32_e32 v4, v6, v4, vcc
	v_add_f32_e32 v6, 1.0, v5
	v_cndmask_b32_e32 v3, v3, v11, vcc
	v_rcp_f32_e32 v11, v6
	v_min_f32_e32 v6, 0x42ac0000, v25
	v_exp_f32_e32 v6, v6
	v_mul_f32_e32 v12, v4, v2
	v_mul_f32_e32 v13, v3, v2
	v_mul_f32_e32 v2, v5, v11
	v_add_f32_e32 v3, 1.0, v6
	v_rcp_f32_e32 v3, v3
	v_min_f32_e32 v5, 0x42ac0000, v24
	v_exp_f32_e32 v5, v5
	v_cndmask_b32_e64 v4, 1.0, v2, s[28:29]
	v_cndmask_b32_e32 v2, v2, v4, vcc
	v_mul_f32_e32 v4, v6, v3
	v_cndmask_b32_e64 v6, 0, v3, s[30:31]
	v_cndmask_b32_e32 v3, v3, v6, vcc
	v_add_f32_e32 v6, 1.0, v5
	v_rcp_f32_e32 v6, v6
	v_cndmask_b32_e64 v14, 1.0, v4, s[30:31]
	v_mul_f32_e32 v2, v2, v13
	v_cndmask_b32_e32 v4, v4, v14, vcc
	v_mul_f32_e32 v3, v3, v2
	v_mul_f32_e32 v2, v4, v2
	v_mul_f32_e32 v4, v5, v6
	v_min_f32_e32 v5, 0x42ac0000, v23
	v_exp_f32_e32 v5, v5
	v_cndmask_b32_e64 v14, 0, v6, s[34:35]
	v_cndmask_b32_e32 v6, v6, v14, vcc
	v_cndmask_b32_e64 v15, 1.0, v4, s[34:35]
	v_add_f32_e32 v14, 1.0, v5
	v_rcp_f32_e32 v14, v14
	v_cndmask_b32_e32 v4, v4, v15, vcc
	v_mul_f32_e32 v15, v6, v2
	v_mul_f32_e32 v2, v4, v2
	v_mul_f32_e32 v4, v5, v14
	v_min_f32_e32 v5, 0x42ac0000, v22
	v_exp_f32_e32 v5, v5
	v_cndmask_b32_e64 v6, 0, v14, s[36:37]
	v_cndmask_b32_e32 v6, v14, v6, vcc
	v_cndmask_b32_e64 v17, 1.0, v4, s[36:37]
	v_add_f32_e32 v14, 1.0, v5
	v_rcp_f32_e32 v14, v14
	v_cndmask_b32_e32 v4, v4, v17, vcc
	v_mul_f32_e32 v17, v6, v2
	v_mul_f32_e32 v2, v4, v2
	v_mul_f32_e32 v4, v5, v14
	v_min_f32_e32 v5, 0x42ac0000, v21
	v_exp_f32_e32 v5, v5
	v_cndmask_b32_e64 v6, 0, v14, s[38:39]
	v_cndmask_b32_e32 v6, v14, v6, vcc
	v_cndmask_b32_e64 v21, 1.0, v4, s[38:39]
	v_add_f32_e32 v14, 1.0, v5
	v_rcp_f32_e32 v14, v14
	v_cndmask_b32_e32 v4, v4, v21, vcc
	v_mul_f32_e32 v21, v6, v2
	v_mul_f32_e32 v2, v4, v2
	v_mul_f32_e32 v4, v5, v14
	v_min_f32_e32 v5, 0x42ac0000, v20
	v_exp_f32_e32 v5, v5
	v_cndmask_b32_e64 v6, 0, v14, s[40:41]
	v_cndmask_b32_e32 v6, v14, v6, vcc
	v_cndmask_b32_e64 v20, 1.0, v4, s[40:41]
	v_add_f32_e32 v14, 1.0, v5
	v_rcp_f32_e32 v14, v14
	v_cndmask_b32_e32 v4, v4, v20, vcc
	v_mul_f32_e32 v20, v6, v2
	v_mul_f32_e32 v2, v4, v2
	v_mul_f32_e32 v4, v5, v14
	v_min_f32_e32 v5, 0x42ac0000, v19
	v_exp_f32_e32 v5, v5
	v_cndmask_b32_e64 v6, 0, v14, s[42:43]
	v_cndmask_b32_e32 v6, v14, v6, vcc
	v_cndmask_b32_e64 v19, 1.0, v4, s[42:43]
	v_add_f32_e32 v14, 1.0, v5
	v_rcp_f32_e32 v14, v14
	v_cndmask_b32_e32 v4, v4, v19, vcc
	v_mul_f32_e32 v19, v6, v2
	v_mul_f32_e32 v2, v4, v2
	v_mul_f32_e32 v4, v5, v14
	v_min_f32_e32 v5, 0x42ac0000, v18
	v_exp_f32_e32 v5, v5
	v_cndmask_b32_e64 v6, 0, v14, s[44:45]
	v_cndmask_b32_e32 v6, v14, v6, vcc
	v_cndmask_b32_e64 v18, 1.0, v4, s[44:45]
	v_add_f32_e32 v14, 1.0, v5
	v_rcp_f32_e32 v14, v14
	v_cndmask_b32_e32 v4, v4, v18, vcc
	v_mul_f32_e32 v18, v6, v2
	v_mul_f32_e32 v2, v4, v2
	v_mul_f32_e32 v4, v5, v14
	v_cndmask_b32_e64 v6, 1.0, v4, s[46:47]
	v_cndmask_b32_e64 v5, 0, v14, s[46:47]
	v_cndmask_b32_e32 v4, v4, v6, vcc
	v_cndmask_b32_e32 v5, v14, v5, vcc
	v_mul_f32_e32 v14, v4, v2
	v_mov_b32_e32 v22, v14
	s_nop 1
	s_nop 0
	v_permlane32_swap_b32_e32 v14, v22
	v_mul_f32_e32 v5, v5, v2
	v_cndmask_b32_e64 v2, 1.0, v22, s[10:11]
	v_mul_f32_e32 v6, v190, v2
	v_mul_f32_e32 v2, v5, v6
	v_mul_f32_e32 v4, v18, v6
	v_mul_f32_e32 v5, v19, v6
	v_mul_f32_e32 v18, v20, v6
	v_mul_f32_e32 v19, v21, v6
	v_mul_f32_e32 v17, v17, v6
	v_mul_f32_e32 v15, v15, v6
	v_mul_f32_e32 v20, v3, v6
	v_cvt_pk_bf16_f32 v2, v2, v4
	v_cvt_pk_bf16_f32 v3, v5, v18
	v_cvt_pk_bf16_f32 v4, v19, v17
	v_cvt_pk_bf16_f32 v5, v15, v20
	v_cndmask_b32_e64 v15, 0, v11, s[28:29]
	v_cndmask_b32_e32 v11, v11, v15, vcc
	s_waitcnt lgkmcnt(0)
	v_mfma_f32_32x32x16_bf16 v[66:81], v[158:161], v[2:5], v[66:81]
	v_mul_f32_e32 v11, v11, v13
	v_mul_f32_e32 v11, v11, v6
	v_mul_f32_e32 v12, v12, v6
	v_mul_f32_e32 v10, v10, v6
	v_mul_f32_e32 v9, v9, v6
	v_mfma_f32_32x32x16_bf16 v[50:65], v[154:157], v[2:5], v[50:65]
	v_mul_f32_e32 v2, v8, v6
	v_mul_f32_e32 v3, v7, v6
	v_mul_f32_e64 v4, v0, v6
	v_mul_f32_e64 v5, v1, v6
	v_cvt_pk_bf16_f32 v0, v11, v12
	v_cvt_pk_bf16_f32 v1, v10, v9
	v_cvt_pk_bf16_f32 v2, v2, v3
	v_cvt_pk_bf16_f32 v3, v4, v5
	v_mul_f32_e32 v4, v14, v22
	v_mul_f32_e32 v190, v190, v4
	v_mfma_f32_32x32x16_bf16 v[66:81], v[150:153], v[0:3], v[66:81]
	s_branch .Lsb_join_7
